# GEMM K-loops: additionally merged the two MFMA priority windows of each phase (adjacent s_setprio 0 / s_setprio 1 pair removed, 32 sites)
# baseline (speedup 1.0000x reference)
; #define PG8_STAGE(bufoff, gbase, voff) do { _Pragma("unroll") for (int _i = 0; _i < 2; ++_i) \
;         __builtin_amdgcn_global_load_lds((const unsigned*)((const char*)(gbase) + (voff)[_i]), (PG8_LAS unsigned*)(lds + (bufoff) + ldsw + _i * 8192), 16, 0, 0); } while (0)
; #define PG8_LDA(dst, b, h) do { _Pragma("unroll") for (int m = 0; m < 4; ++m) _Pragma("unroll") for (int k = 0; k < 2; ++k) dst[m][k] = *(const PG8_LAS bf16x8*)(lds + PG8_SA(b, h) + aoff + m * 2048 + k * 1024); } while (0)
; #define PG8_LDB(dst, b, h) do { _Pragma("unroll") for (int n = 0; n < 2; ++n) _Pragma("unroll") for (int k = 0; k < 2; ++k) dst[n][k] = *(const PG8_LAS bf16x8*)(lds + PG8_SB(b, h) + boff + n * 2048 + k * 1024); } while (0)
; #define PG8_MMA(ai, bj, At, Bt) do { __builtin_amdgcn_s_setprio(1); _Pragma("unroll") for (int m = 0; m < 4; ++m) _Pragma("unroll") for (int n = 0; n < 2; ++n) _Pragma("unroll") for (int k = 0; k < 2; ++k) \
;         acc[ai][bj][m][n] = __builtin_amdgcn_mfma_f32_16x16x32_bf16(Bt[n][k], At[m][k], acc[ai][bj][m][n], 0, 0, 0); __builtin_amdgcn_s_setprio(0); } while (0)
; #define PG8_WAIT_V(n) asm volatile("s_waitcnt vmcnt(" #n ")" ::: "memory")
; #define PG8_BAR __builtin_amdgcn_s_barrier()
; template <class Epi, class Sched, bool ALIGN_EPI = false, bool SP2 = false>
; __device__ __forceinline__ void gemm_phase(PG8_LAS unsigned char* lds, const Gemm g, const Sched& S, const Epi& E) {
;     ...
;         for (int t = 0; t < ntc; t += 2) {
;             const bool last = (t == ntc - 2);
;             const char* a1 = cA + (size_t)(t + 1) * kstep;
;             const char* a2 = last ? nA : cA + (size_t)(t + 2) * kstep; const char* b2 = last ? nB : cB + (size_t)(t + 2) * kstep;
;             const char* a3 = a2 + kstep; const char* b3 = b2 + kstep;
;             if (last && has_next) S.a_ready(nxt);
;             if constexpr (SP2) {
;             PG8_LDB(B0, 0, 0); PG8_LDB(B1, 0, 1); PG8_SCHED; PG8_LDA(At, 0, 0); PG8_STAGE(PG8_SA(1, 1), a1 + hstepA, voffA);
;             PG8_WAIT_V(8); PG8_WAIT_L(0); PG8_BAR; PG8_MMA(0, 0, At, B0); PG8_MMA(0, 1, At, B1); PG8_BAR; PG8_SCHED;
;             PG8_LDA(At, 0, 1); PG8_STAGE(PG8_SB(0, 0), b2, voffB); PG8_STAGE(PG8_SB(0, 1), b2 + hstepB, voffB); PG8_STAGE(PG8_SA(0, 0), a2, voffA);
;             PG8_WAIT_V(8); PG8_WAIT_L(0); PG8_BAR; PG8_MMA(1, 0, At, B0); PG8_MMA(1, 1, At, B1); PG8_BAR; PG8_SCHED;
.LBB0_200:
	s_add_i32 s47, s24, 2
	s_add_u32 s25, s4, 0xfffc0080
	s_addc_u32 s26, s5, -1
	s_add_i32 s48, 0, 0x10000
	s_cmp_eq_u32 s39, s24
	s_cselect_b32 s27, s17, s26
	s_cselect_b32 s26, s19, s25
	s_cselect_b32 s25, s43, s46
	s_cselect_b32 s24, s44, s45
	s_add_i32 s50, 0, 0x14000
	v_add_u32_e32 v102, s48, v177
	v_add_u32_e32 v126, s50, v177
	ds_read_b128 v[86:89], v102
	ds_read_b128 v[94:97], v102 offset:1024
	ds_read_b128 v[98:101], v102 offset:2048
	ds_read_b128 v[102:105], v102 offset:3072
	ds_read_b128 v[106:109], v126
	ds_read_b128 v[110:113], v126 offset:1024
	ds_read_b128 v[118:121], v126 offset:2048
	ds_read_b128 v[126:129], v126 offset:3072
	s_add_i32 m0, s30, 0xc000
	ds_read_b128 v[202:205], v179
	ds_read_b128 v[206:209], v179 offset:1024
	ds_read_b128 v[210:213], v179 offset:2048
	ds_read_b128 v[214:217], v179 offset:3072
	ds_read_b128 v[218:221], v179 offset:4096
	ds_read_b128 v[222:225], v179 offset:5120
	ds_read_b128 v[240:243], v179 offset:6144
	ds_read_b128 v[244:247], v179 offset:7168
	global_load_lds_dwordx4 v168, s[4:5]
	s_add_i32 m0, s30, 0xe000
	s_nop 0
	global_load_lds_dwordx4 v170, s[4:5]
	s_waitcnt vmcnt(8)
	s_waitcnt lgkmcnt(0)
	s_barrier
	s_setprio 1
	v_mfma_f32_16x16x32_bf16 v[158:161], v[86:89], v[202:205], v[158:161]
	v_mfma_f32_16x16x32_bf16 v[150:153], v[98:101], v[202:205], v[150:153]
	v_mfma_f32_16x16x32_bf16 v[142:145], v[86:89], v[210:213], v[142:145]
	v_mfma_f32_16x16x32_bf16 v[134:137], v[98:101], v[210:213], v[134:137]
	v_mfma_f32_16x16x32_bf16 v[122:125], v[86:89], v[218:221], v[122:125]
	v_mfma_f32_16x16x32_bf16 v[90:93], v[98:101], v[218:221], v[90:93]
	v_mfma_f32_16x16x32_bf16 v[78:81], v[86:89], v[240:243], v[78:81]
	v_mfma_f32_16x16x32_bf16 v[70:73], v[98:101], v[240:243], v[70:73]
	v_mfma_f32_16x16x32_bf16 v[158:161], v[94:97], v[206:209], v[158:161]
	v_mfma_f32_16x16x32_bf16 v[150:153], v[102:105], v[206:209], v[150:153]
	v_mfma_f32_16x16x32_bf16 v[142:145], v[94:97], v[214:217], v[142:145]
	v_mfma_f32_16x16x32_bf16 v[134:137], v[102:105], v[214:217], v[134:137]
	v_mfma_f32_16x16x32_bf16 v[122:125], v[94:97], v[222:225], v[122:125]
	v_mfma_f32_16x16x32_bf16 v[90:93], v[102:105], v[222:225], v[90:93]
	v_mfma_f32_16x16x32_bf16 v[78:81], v[94:97], v[244:247], v[78:81]
	v_mfma_f32_16x16x32_bf16 v[70:73], v[102:105], v[244:247], v[70:73]
	v_mfma_f32_16x16x32_bf16 v[154:157], v[106:109], v[202:205], v[154:157]
	v_mfma_f32_16x16x32_bf16 v[146:149], v[118:121], v[202:205], v[146:149]
	v_mfma_f32_16x16x32_bf16 v[138:141], v[106:109], v[210:213], v[138:141]
	v_mfma_f32_16x16x32_bf16 v[130:133], v[118:121], v[210:213], v[130:133]
	v_mfma_f32_16x16x32_bf16 v[114:117], v[106:109], v[218:221], v[114:117]
	v_mfma_f32_16x16x32_bf16 v[82:85], v[118:121], v[218:221], v[82:85]
	v_mfma_f32_16x16x32_bf16 v[74:77], v[106:109], v[240:243], v[74:77]
	v_mfma_f32_16x16x32_bf16 v[66:69], v[118:121], v[240:243], v[66:69]
	v_mfma_f32_16x16x32_bf16 v[154:157], v[110:113], v[206:209], v[154:157]
	v_mfma_f32_16x16x32_bf16 v[146:149], v[126:129], v[206:209], v[146:149]
	v_mfma_f32_16x16x32_bf16 v[138:141], v[110:113], v[214:217], v[138:141]
	v_mfma_f32_16x16x32_bf16 v[130:133], v[126:129], v[214:217], v[130:133]
	v_mfma_f32_16x16x32_bf16 v[114:117], v[110:113], v[222:225], v[114:117]
	v_mfma_f32_16x16x32_bf16 v[82:85], v[126:129], v[222:225], v[82:85]
	v_mfma_f32_16x16x32_bf16 v[74:77], v[110:113], v[244:247], v[74:77]
	v_mfma_f32_16x16x32_bf16 v[66:69], v[126:129], v[244:247], v[66:69]
	s_setprio 0
	s_barrier
	s_add_i32 s48, s48, s28
	s_mov_b32 m0, s48
	ds_read_b128 v[202:205], v179 offset:16384
	ds_read_b128 v[206:209], v179 offset:17408
	ds_read_b128 v[210:213], v179 offset:18432
	ds_read_b128 v[214:217], v179 offset:19456
	ds_read_b128 v[218:221], v179 offset:20480
	ds_read_b128 v[222:225], v179 offset:21504
	ds_read_b128 v[240:243], v179 offset:22528
	ds_read_b128 v[244:247], v179 offset:23552
	global_load_lds_dwordx4 v64, s[24:25]
	s_add_i32 m0, s48, 0x2000
	s_add_u32 s48, s24, 0x40000
	s_addc_u32 s49, s25, 0
	s_add_i32 s50, s50, s28
	global_load_lds_dwordx4 v162, s[24:25]
	s_mov_b32 m0, s50
	s_nop 0
	global_load_lds_dwordx4 v64, s[48:49]
	s_add_i32 m0, s50, 0x2000
	s_nop 0
	global_load_lds_dwordx4 v162, s[48:49]
	s_mov_b32 m0, s30
	s_nop 0
	global_load_lds_dwordx4 v166, s[26:27]
	s_mov_b32 m0, s31
	s_nop 0
	global_load_lds_dwordx4 v164, s[26:27]
	s_waitcnt vmcnt(8)
	s_waitcnt lgkmcnt(0)
	s_barrier
	s_setprio 1
	v_mfma_f32_16x16x32_bf16 v[60:63], v[86:89], v[202:205], v[60:63]
	v_mfma_f32_16x16x32_bf16 v[52:55], v[98:101], v[202:205], v[52:55]
	v_mfma_f32_16x16x32_bf16 v[44:47], v[86:89], v[210:213], v[44:47]
	v_mfma_f32_16x16x32_bf16 v[36:39], v[98:101], v[210:213], v[36:39]
	v_mfma_f32_16x16x32_bf16 v[28:31], v[86:89], v[218:221], v[28:31]
	v_mfma_f32_16x16x32_bf16 v[20:23], v[98:101], v[218:221], v[20:23]
	v_mfma_f32_16x16x32_bf16 v[12:15], v[86:89], v[240:243], v[12:15]
	v_mfma_f32_16x16x32_bf16 v[4:7], v[98:101], v[240:243], v[4:7]
	v_mfma_f32_16x16x32_bf16 v[60:63], v[94:97], v[206:209], v[60:63]
	v_mfma_f32_16x16x32_bf16 v[52:55], v[102:105], v[206:209], v[52:55]
	v_mfma_f32_16x16x32_bf16 v[44:47], v[94:97], v[214:217], v[44:47]
	v_mfma_f32_16x16x32_bf16 v[36:39], v[102:105], v[214:217], v[36:39]
	v_mfma_f32_16x16x32_bf16 v[28:31], v[94:97], v[222:225], v[28:31]
	v_mfma_f32_16x16x32_bf16 v[20:23], v[102:105], v[222:225], v[20:23]
	v_mfma_f32_16x16x32_bf16 v[12:15], v[94:97], v[244:247], v[12:15]
	v_mfma_f32_16x16x32_bf16 v[4:7], v[102:105], v[244:247], v[4:7]
	v_mfma_f32_16x16x32_bf16 v[56:59], v[106:109], v[202:205], v[56:59]
	v_mfma_f32_16x16x32_bf16 v[48:51], v[118:121], v[202:205], v[48:51]
	v_mfma_f32_16x16x32_bf16 v[40:43], v[106:109], v[210:213], v[40:43]
	v_mfma_f32_16x16x32_bf16 v[32:35], v[118:121], v[210:213], v[32:35]
	v_mfma_f32_16x16x32_bf16 v[24:27], v[106:109], v[218:221], v[24:27]
	v_mfma_f32_16x16x32_bf16 v[16:19], v[118:121], v[218:221], v[16:19]
	v_mfma_f32_16x16x32_bf16 v[8:11], v[106:109], v[240:243], v[8:11]
	v_mfma_f32_16x16x32_bf16 v[0:3], v[118:121], v[240:243], v[0:3]
	v_mfma_f32_16x16x32_bf16 v[56:59], v[110:113], v[206:209], v[56:59]
	v_mfma_f32_16x16x32_bf16 v[48:51], v[126:129], v[206:209], v[48:51]
	v_mfma_f32_16x16x32_bf16 v[40:43], v[110:113], v[214:217], v[40:43]
	v_mfma_f32_16x16x32_bf16 v[32:35], v[126:129], v[214:217], v[32:35]
	v_mfma_f32_16x16x32_bf16 v[24:27], v[110:113], v[222:225], v[24:27]
	v_mfma_f32_16x16x32_bf16 v[16:19], v[126:129], v[222:225], v[16:19]
	v_mfma_f32_16x16x32_bf16 v[8:11], v[110:113], v[244:247], v[8:11]
	v_mfma_f32_16x16x32_bf16 v[0:3], v[126:129], v[244:247], v[0:3]
	s_setprio 0
	s_barrier
; #define PG8_STAGE(bufoff, gbase, voff) do { _Pragma("unroll") for (int _i = 0; _i < 2; ++_i) \
;         __builtin_amdgcn_global_load_lds((const unsigned*)((const char*)(gbase) + (voff)[_i]), (PG8_LAS unsigned*)(lds + (bufoff) + ldsw + _i * 8192), 16, 0, 0); } while (0)
; #define PG8_LDA(dst, b, h) do { _Pragma("unroll") for (int m = 0; m < 4; ++m) _Pragma("unroll") for (int k = 0; k < 2; ++k) dst[m][k] = *(const PG8_LAS bf16x8*)(lds + PG8_SA(b, h) + aoff + m * 2048 + k * 1024); } while (0)
; #define PG8_LDB(dst, b, h) do { _Pragma("unroll") for (int n = 0; n < 2; ++n) _Pragma("unroll") for (int k = 0; k < 2; ++k) dst[n][k] = *(const PG8_LAS bf16x8*)(lds + PG8_SB(b, h) + boff + n * 2048 + k * 1024); } while (0)
; #define PG8_MMA(ai, bj, At, Bt) do { __builtin_amdgcn_s_setprio(1); _Pragma("unroll") for (int m = 0; m < 4; ++m) _Pragma("unroll") for (int n = 0; n < 2; ++n) _Pragma("unroll") for (int k = 0; k < 2; ++k) \
;         acc[ai][bj][m][n] = __builtin_amdgcn_mfma_f32_16x16x32_bf16(Bt[n][k], At[m][k], acc[ai][bj][m][n], 0, 0, 0); __builtin_amdgcn_s_setprio(0); } while (0)
; #define PG8_WAIT_V(n) asm volatile("s_waitcnt vmcnt(" #n ")" ::: "memory")
; #define PG8_WAIT_L(n) asm volatile("s_waitcnt lgkmcnt(" #n ")" ::: "memory")
; #define PG8_BAR __builtin_amdgcn_s_barrier()
; #define PG8_SCHED __builtin_amdgcn_sched_barrier(0)
; template <class Epi, class Sched, bool ALIGN_EPI = false, bool SP2 = false>
; __device__ __forceinline__ void gemm_phase(PG8_LAS unsigned char* lds, const Gemm g, const Sched& S, const Epi& E) {
;     ...
;         for (int t = 0; t < ntc; t += 2) {
;     ...
;             PG8_LDB(B0, 1, 0); PG8_LDB(B1, 1, 1); PG8_SCHED; PG8_LDA(At, 1, 0); PG8_STAGE(PG8_SA(0, 1), a2 + hstepA, voffA);
;             PG8_WAIT_V(8); PG8_WAIT_L(0); PG8_BAR; PG8_MMA(0, 0, At, B0); PG8_MMA(0, 1, At, B1); PG8_BAR; PG8_SCHED;
;             PG8_LDA(At, 1, 1); PG8_STAGE(PG8_SB(1, 0), b3, voffB); PG8_STAGE(PG8_SB(1, 1), b3 + hstepB, voffB); PG8_STAGE(PG8_SA(1, 0), a3, voffA);
;             PG8_WAIT_V(8); PG8_WAIT_L(0); PG8_BAR; PG8_MMA(1, 0, At, B0); PG8_MMA(1, 1, At, B1); PG8_BAR; PG8_SCHED;
	s_add_i32 s48, 0, 0x18000
	s_add_i32 s49, 0, 0x1c000
	v_add_u32_e32 v102, s48, v177
	v_add_u32_e32 v126, s49, v177
	ds_read_b128 v[86:89], v102
	ds_read_b128 v[94:97], v102 offset:1024
	ds_read_b128 v[98:101], v102 offset:2048
	ds_read_b128 v[102:105], v102 offset:3072
	ds_read_b128 v[106:109], v126
	ds_read_b128 v[110:113], v126 offset:1024
	ds_read_b128 v[118:121], v126 offset:2048
	ds_read_b128 v[126:129], v126 offset:3072
	s_add_u32 s26, s26, 0x40000
	s_addc_u32 s27, s27, 0
	s_add_u32 s100, s26, 0xfffc0080
	s_addc_u32 s101, s27, -1
	s_mov_b32 m0, s34
	ds_read_b128 v[202:205], v179 offset:32768
	ds_read_b128 v[206:209], v179 offset:33792
	ds_read_b128 v[210:213], v179 offset:34816
	ds_read_b128 v[214:217], v179 offset:35840
	ds_read_b128 v[218:221], v179 offset:36864
	ds_read_b128 v[222:225], v179 offset:37888
	ds_read_b128 v[240:243], v179 offset:38912
	ds_read_b128 v[244:247], v179 offset:39936
	global_load_lds_dwordx4 v166, s[26:27]
	s_mov_b32 m0, s35
	s_nop 0
	global_load_lds_dwordx4 v164, s[26:27]
	s_waitcnt vmcnt(8)
	s_waitcnt lgkmcnt(0)
	s_barrier
	s_setprio 1
	v_mfma_f32_16x16x32_bf16 v[158:161], v[86:89], v[202:205], v[158:161]
	v_mfma_f32_16x16x32_bf16 v[150:153], v[98:101], v[202:205], v[150:153]
	v_mfma_f32_16x16x32_bf16 v[142:145], v[86:89], v[210:213], v[142:145]
	v_mfma_f32_16x16x32_bf16 v[134:137], v[98:101], v[210:213], v[134:137]
	v_mfma_f32_16x16x32_bf16 v[122:125], v[86:89], v[218:221], v[122:125]
	v_mfma_f32_16x16x32_bf16 v[90:93], v[98:101], v[218:221], v[90:93]
	v_mfma_f32_16x16x32_bf16 v[78:81], v[86:89], v[240:243], v[78:81]
	v_mfma_f32_16x16x32_bf16 v[70:73], v[98:101], v[240:243], v[70:73]
	v_mfma_f32_16x16x32_bf16 v[158:161], v[94:97], v[206:209], v[158:161]
	v_mfma_f32_16x16x32_bf16 v[150:153], v[102:105], v[206:209], v[150:153]
	v_mfma_f32_16x16x32_bf16 v[142:145], v[94:97], v[214:217], v[142:145]
	v_mfma_f32_16x16x32_bf16 v[134:137], v[102:105], v[214:217], v[134:137]
	v_mfma_f32_16x16x32_bf16 v[122:125], v[94:97], v[222:225], v[122:125]
	v_mfma_f32_16x16x32_bf16 v[90:93], v[102:105], v[222:225], v[90:93]
	v_mfma_f32_16x16x32_bf16 v[78:81], v[94:97], v[244:247], v[78:81]
	v_mfma_f32_16x16x32_bf16 v[70:73], v[102:105], v[244:247], v[70:73]
	v_mfma_f32_16x16x32_bf16 v[154:157], v[106:109], v[202:205], v[154:157]
	v_mfma_f32_16x16x32_bf16 v[146:149], v[118:121], v[202:205], v[146:149]
	v_mfma_f32_16x16x32_bf16 v[138:141], v[106:109], v[210:213], v[138:141]
	v_mfma_f32_16x16x32_bf16 v[130:133], v[118:121], v[210:213], v[130:133]
	v_mfma_f32_16x16x32_bf16 v[114:117], v[106:109], v[218:221], v[114:117]
	v_mfma_f32_16x16x32_bf16 v[82:85], v[118:121], v[218:221], v[82:85]
	v_mfma_f32_16x16x32_bf16 v[74:77], v[106:109], v[240:243], v[74:77]
	v_mfma_f32_16x16x32_bf16 v[66:69], v[118:121], v[240:243], v[66:69]
	v_mfma_f32_16x16x32_bf16 v[154:157], v[110:113], v[206:209], v[154:157]
	v_mfma_f32_16x16x32_bf16 v[146:149], v[126:129], v[206:209], v[146:149]
	v_mfma_f32_16x16x32_bf16 v[138:141], v[110:113], v[214:217], v[138:141]
	v_mfma_f32_16x16x32_bf16 v[130:133], v[126:129], v[214:217], v[130:133]
	v_mfma_f32_16x16x32_bf16 v[114:117], v[110:113], v[222:225], v[114:117]
	v_mfma_f32_16x16x32_bf16 v[82:85], v[126:129], v[222:225], v[82:85]
	v_mfma_f32_16x16x32_bf16 v[74:77], v[110:113], v[244:247], v[74:77]
	v_mfma_f32_16x16x32_bf16 v[66:69], v[126:129], v[244:247], v[66:69]
	s_setprio 0
	s_barrier
	s_add_i32 s26, s48, s28
	s_add_u32 s24, s24, 0x80
	s_addc_u32 s25, s25, 0
	s_mov_b32 m0, s26
	ds_read_b128 v[202:205], v179 offset:49152
	ds_read_b128 v[206:209], v179 offset:50176
	ds_read_b128 v[210:213], v179 offset:51200
	ds_read_b128 v[214:217], v179 offset:52224
	ds_read_b128 v[218:221], v179 offset:53248
	ds_read_b128 v[222:225], v179 offset:54272
	ds_read_b128 v[240:243], v179 offset:55296
	ds_read_b128 v[244:247], v179 offset:56320
	global_load_lds_dwordx4 v64, s[24:25]
	s_add_i32 m0, s26, 0x2000
	s_add_i32 s26, s49, s28
	global_load_lds_dwordx4 v162, s[24:25]
	s_add_u32 s24, s24, 0x40000
	s_addc_u32 s25, s25, 0
	s_mov_b32 m0, s26
	s_nop 0
	global_load_lds_dwordx4 v64, s[24:25]
	s_add_i32 m0, s26, 0x2000
	s_nop 0
	global_load_lds_dwordx4 v162, s[24:25]
	s_mov_b32 m0, s37
	s_nop 0
	global_load_lds_dwordx4 v166, s[100:101]
	s_mov_b32 m0, s38
	s_nop 0
	global_load_lds_dwordx4 v164, s[100:101]
	s_waitcnt vmcnt(8)
	s_waitcnt lgkmcnt(0)
	s_barrier
	s_setprio 1
	v_mfma_f32_16x16x32_bf16 v[60:63], v[86:89], v[202:205], v[60:63]
	v_mfma_f32_16x16x32_bf16 v[52:55], v[98:101], v[202:205], v[52:55]
	v_mfma_f32_16x16x32_bf16 v[44:47], v[86:89], v[210:213], v[44:47]
	v_mfma_f32_16x16x32_bf16 v[36:39], v[98:101], v[210:213], v[36:39]
	v_mfma_f32_16x16x32_bf16 v[28:31], v[86:89], v[218:221], v[28:31]
	v_mfma_f32_16x16x32_bf16 v[20:23], v[98:101], v[218:221], v[20:23]
	v_mfma_f32_16x16x32_bf16 v[12:15], v[86:89], v[240:243], v[12:15]
	v_mfma_f32_16x16x32_bf16 v[4:7], v[98:101], v[240:243], v[4:7]
	v_mfma_f32_16x16x32_bf16 v[60:63], v[94:97], v[206:209], v[60:63]
	v_mfma_f32_16x16x32_bf16 v[52:55], v[102:105], v[206:209], v[52:55]
	v_mfma_f32_16x16x32_bf16 v[44:47], v[94:97], v[214:217], v[44:47]
	v_mfma_f32_16x16x32_bf16 v[36:39], v[102:105], v[214:217], v[36:39]
	v_mfma_f32_16x16x32_bf16 v[28:31], v[94:97], v[222:225], v[28:31]
	v_mfma_f32_16x16x32_bf16 v[20:23], v[102:105], v[222:225], v[20:23]
	v_mfma_f32_16x16x32_bf16 v[12:15], v[94:97], v[244:247], v[12:15]
	v_mfma_f32_16x16x32_bf16 v[4:7], v[102:105], v[244:247], v[4:7]
	v_mfma_f32_16x16x32_bf16 v[56:59], v[106:109], v[202:205], v[56:59]
	v_mfma_f32_16x16x32_bf16 v[48:51], v[118:121], v[202:205], v[48:51]
	v_mfma_f32_16x16x32_bf16 v[40:43], v[106:109], v[210:213], v[40:43]
	v_mfma_f32_16x16x32_bf16 v[32:35], v[118:121], v[210:213], v[32:35]
	v_mfma_f32_16x16x32_bf16 v[24:27], v[106:109], v[218:221], v[24:27]
	v_mfma_f32_16x16x32_bf16 v[16:19], v[118:121], v[218:221], v[16:19]
	v_mfma_f32_16x16x32_bf16 v[8:11], v[106:109], v[240:243], v[8:11]
	v_mfma_f32_16x16x32_bf16 v[0:3], v[118:121], v[240:243], v[0:3]
	v_mfma_f32_16x16x32_bf16 v[56:59], v[110:113], v[206:209], v[56:59]
	v_mfma_f32_16x16x32_bf16 v[48:51], v[126:129], v[206:209], v[48:51]
	v_mfma_f32_16x16x32_bf16 v[40:43], v[110:113], v[214:217], v[40:43]
	v_mfma_f32_16x16x32_bf16 v[32:35], v[126:129], v[214:217], v[32:35]
	v_mfma_f32_16x16x32_bf16 v[24:27], v[110:113], v[222:225], v[24:27]
	v_mfma_f32_16x16x32_bf16 v[16:19], v[126:129], v[222:225], v[16:19]
	v_mfma_f32_16x16x32_bf16 v[8:11], v[110:113], v[244:247], v[8:11]
	v_mfma_f32_16x16x32_bf16 v[0:3], v[126:129], v[244:247], v[0:3]
	s_setprio 0
	s_barrier
	s_add_u32 s4, s4, 0x100
	s_addc_u32 s5, s5, 0
	s_add_u32 s45, s45, 0x100
	s_addc_u32 s46, s46, 0
	s_cmp_ge_i32 s47, s36
	s_mov_b32 s24, s47
	s_cbranch_scc0 .LBB0_200

; #define PG8_STAGE(bufoff, gbase, voff) do { _Pragma("unroll") for (int _i = 0; _i < 2; ++_i) \
;         __builtin_amdgcn_global_load_lds((const unsigned*)((const char*)(gbase) + (voff)[_i]), (PG8_LAS unsigned*)(lds + (bufoff) + ldsw + _i * 8192), 16, 0, 0); } while (0)
; #define PG8_LDA(dst, b, h) do { _Pragma("unroll") for (int m = 0; m < 4; ++m) _Pragma("unroll") for (int k = 0; k < 2; ++k) dst[m][k] = *(const PG8_LAS bf16x8*)(lds + PG8_SA(b, h) + aoff + m * 2048 + k * 1024); } while (0)
; #define PG8_LDB(dst, b, h) do { _Pragma("unroll") for (int n = 0; n < 2; ++n) _Pragma("unroll") for (int k = 0; k < 2; ++k) dst[n][k] = *(const PG8_LAS bf16x8*)(lds + PG8_SB(b, h) + boff + n * 2048 + k * 1024); } while (0)
; #define PG8_MMA(ai, bj, At, Bt) do { __builtin_amdgcn_s_setprio(1); _Pragma("unroll") for (int m = 0; m < 4; ++m) _Pragma("unroll") for (int n = 0; n < 2; ++n) _Pragma("unroll") for (int k = 0; k < 2; ++k) \
;         acc[ai][bj][m][n] = __builtin_amdgcn_mfma_f32_16x16x32_bf16(Bt[n][k], At[m][k], acc[ai][bj][m][n], 0, 0, 0); __builtin_amdgcn_s_setprio(0); } while (0)
; #define PG8_WAIT_V(n) asm volatile("s_waitcnt vmcnt(" #n ")" ::: "memory")
; #define PG8_WAIT_L(n) asm volatile("s_waitcnt lgkmcnt(" #n ")" ::: "memory")
; #define PG8_BAR __builtin_amdgcn_s_barrier()
; #define PG8_SCHED __builtin_amdgcn_sched_barrier(0)
; template <class Epi, class Sched, bool ALIGN_EPI = false, bool SP2 = false>
; __device__ __forceinline__ void gemm_phase(PG8_LAS unsigned char* lds, const Gemm g, const Sched& S, const Epi& E) {
;     ...
;         for (int t = 0; t < ntc; t += 2) {
;             const bool last = (t == ntc - 2);
;             const char* a1 = cA + (size_t)(t + 1) * kstep;
;             const char* a2 = last ? nA : cA + (size_t)(t + 2) * kstep; const char* b2 = last ? nB : cB + (size_t)(t + 2) * kstep;
;             const char* a3 = a2 + kstep; const char* b3 = b2 + kstep;
;             if (last && has_next) S.a_ready(nxt);
;             if constexpr (SP2) {
;             PG8_LDB(B0, 0, 0); PG8_LDB(B1, 0, 1); PG8_SCHED; PG8_LDA(At, 0, 0); PG8_STAGE(PG8_SA(1, 1), a1 + hstepA, voffA);
;             PG8_WAIT_V(8); PG8_WAIT_L(0); PG8_BAR; PG8_MMA(0, 0, At, B0); PG8_MMA(0, 1, At, B1); PG8_BAR; PG8_SCHED;
;             PG8_LDA(At, 0, 1); PG8_STAGE(PG8_SB(0, 0), b2, voffB); PG8_STAGE(PG8_SB(0, 1), b2 + hstepB, voffB); PG8_STAGE(PG8_SA(0, 0), a2, voffA);
.LBB0_278:
	s_add_i32 s51, s10, 2
	s_add_u32 s8, s4, 0x100
	s_addc_u32 s9, s5, 0
	s_add_i32 s52, 0, 0x10000
	s_cmp_eq_u32 s45, s10
	s_cselect_b32 s29, s25, s9
	s_cselect_b32 s28, s24, s8
	s_cselect_b32 s11, s27, s50
	s_cselect_b32 s10, s26, s49
	s_add_i32 s53, 0, 0x14000
	v_add_u32_e32 v152, s52, v242
	v_add_u32_e32 v168, s53, v242
	ds_read_b128 v[140:143], v152
	ds_read_b128 v[144:147], v152 offset:1024
	ds_read_b128 v[148:151], v152 offset:2048
	ds_read_b128 v[152:155], v152 offset:3072
	ds_read_b128 v[156:159], v168
	ds_read_b128 v[160:163], v168 offset:1024
	ds_read_b128 v[164:167], v168 offset:2048
	ds_read_b128 v[168:171], v168 offset:3072
	v_lshl_add_u64 v[188:189], s[4:5], 0, v[136:137]
	s_add_i32 m0, s35, 0xc000
	ds_read_b128 v[172:175], v243
	ds_read_b128 v[176:179], v243 offset:1024
	ds_read_b128 v[180:183], v243 offset:2048
	ds_read_b128 v[184:187], v243 offset:3072
	ds_read_b128 v[202:205], v243 offset:4096
	ds_read_b128 v[206:209], v243 offset:5120
	ds_read_b128 v[210:213], v243 offset:6144
	ds_read_b128 v[214:217], v243 offset:7168
	global_load_lds_dwordx4 v[188:189], off
	v_lshl_add_u64 v[188:189], s[4:5], 0, v[138:139]
	s_add_i32 m0, s35, 0xe000
	s_nop 0
	global_load_lds_dwordx4 v[188:189], off
	s_waitcnt vmcnt(8)
	s_waitcnt lgkmcnt(0)
	s_barrier
	s_setprio 1
	v_mfma_f32_16x16x32_bf16 v[126:129], v[140:143], v[172:175], v[126:129]
	v_mfma_f32_16x16x32_bf16 v[122:125], v[148:151], v[172:175], v[122:125]
	v_mfma_f32_16x16x32_bf16 v[118:121], v[140:143], v[180:183], v[118:121]
	v_mfma_f32_16x16x32_bf16 v[114:117], v[148:151], v[180:183], v[114:117]
	v_mfma_f32_16x16x32_bf16 v[106:109], v[140:143], v[202:205], v[106:109]
	v_mfma_f32_16x16x32_bf16 v[98:101], v[148:151], v[202:205], v[98:101]
	v_mfma_f32_16x16x32_bf16 v[90:93], v[140:143], v[210:213], v[90:93]
	v_mfma_f32_16x16x32_bf16 v[82:85], v[148:151], v[210:213], v[82:85]
	v_mfma_f32_16x16x32_bf16 v[126:129], v[144:147], v[176:179], v[126:129]
	v_mfma_f32_16x16x32_bf16 v[122:125], v[152:155], v[176:179], v[122:125]
	v_mfma_f32_16x16x32_bf16 v[118:121], v[144:147], v[184:187], v[118:121]
	v_mfma_f32_16x16x32_bf16 v[114:117], v[152:155], v[184:187], v[114:117]
	v_mfma_f32_16x16x32_bf16 v[106:109], v[144:147], v[206:209], v[106:109]
	v_mfma_f32_16x16x32_bf16 v[98:101], v[152:155], v[206:209], v[98:101]
	v_mfma_f32_16x16x32_bf16 v[90:93], v[144:147], v[214:217], v[90:93]
	v_mfma_f32_16x16x32_bf16 v[82:85], v[152:155], v[214:217], v[82:85]
	v_mfma_f32_16x16x32_bf16 v[110:113], v[156:159], v[172:175], v[110:113]
	v_mfma_f32_16x16x32_bf16 v[102:105], v[164:167], v[172:175], v[102:105]
	v_mfma_f32_16x16x32_bf16 v[94:97], v[156:159], v[180:183], v[94:97]
	v_mfma_f32_16x16x32_bf16 v[86:89], v[164:167], v[180:183], v[86:89]
	v_mfma_f32_16x16x32_bf16 v[78:81], v[156:159], v[202:205], v[78:81]
	v_mfma_f32_16x16x32_bf16 v[74:77], v[164:167], v[202:205], v[74:77]
	v_mfma_f32_16x16x32_bf16 v[70:73], v[156:159], v[210:213], v[70:73]
	v_mfma_f32_16x16x32_bf16 v[66:69], v[164:167], v[210:213], v[66:69]
	v_mfma_f32_16x16x32_bf16 v[110:113], v[160:163], v[176:179], v[110:113]
	v_mfma_f32_16x16x32_bf16 v[102:105], v[168:171], v[176:179], v[102:105]
	v_mfma_f32_16x16x32_bf16 v[94:97], v[160:163], v[184:187], v[94:97]
	v_mfma_f32_16x16x32_bf16 v[86:89], v[168:171], v[184:187], v[86:89]
	v_mfma_f32_16x16x32_bf16 v[78:81], v[160:163], v[206:209], v[78:81]
	v_mfma_f32_16x16x32_bf16 v[74:77], v[168:171], v[206:209], v[74:77]
	v_mfma_f32_16x16x32_bf16 v[70:73], v[160:163], v[214:217], v[70:73]
	v_mfma_f32_16x16x32_bf16 v[66:69], v[168:171], v[214:217], v[66:69]
	s_setprio 0
	s_barrier
	s_add_i32 s4, s52, s30
	v_lshl_add_u64 v[188:189], s[10:11], 0, v[64:65]
	s_mov_b32 m0, s4
	ds_read_b128 v[172:175], v243 offset:16384
	ds_read_b128 v[176:179], v243 offset:17408
	ds_read_b128 v[180:183], v243 offset:18432
	ds_read_b128 v[184:187], v243 offset:19456
	ds_read_b128 v[202:205], v243 offset:20480
	ds_read_b128 v[206:209], v243 offset:21504
	ds_read_b128 v[210:213], v243 offset:22528
	ds_read_b128 v[214:217], v243 offset:23552
	global_load_lds_dwordx4 v[188:189], off
	s_add_i32 m0, s4, 0x2000
	s_add_u32 s4, s10, 0xb0000
	v_lshl_add_u64 v[218:219], s[10:11], 0, v[130:131]
	s_addc_u32 s5, s11, 0
	s_add_i32 s52, s53, s30
	global_load_lds_dwordx4 v[218:219], off
	v_lshl_add_u64 v[220:221], s[4:5], 0, v[64:65]
	s_mov_b32 m0, s52
	v_lshl_add_u64 v[222:223], s[28:29], 0, v[132:133]
	global_load_lds_dwordx4 v[220:221], off
	v_lshl_add_u64 v[220:221], s[4:5], 0, v[130:131]
	s_add_i32 m0, s52, 0x2000
	s_nop 0
	global_load_lds_dwordx4 v[220:221], off
	v_lshl_add_u64 v[220:221], s[28:29], 0, v[134:135]
	s_mov_b32 m0, s35
	s_nop 0
	global_load_lds_dwordx4 v[220:221], off
	s_mov_b32 m0, s36
	s_nop 0
	global_load_lds_dwordx4 v[222:223], off
	s_waitcnt vmcnt(8)
	s_waitcnt lgkmcnt(0)
	s_barrier
; #define PG8_STAGE(bufoff, gbase, voff) do { _Pragma("unroll") for (int _i = 0; _i < 2; ++_i) \
;         __builtin_amdgcn_global_load_lds((const unsigned*)((const char*)(gbase) + (voff)[_i]), (PG8_LAS unsigned*)(lds + (bufoff) + ldsw + _i * 8192), 16, 0, 0); } while (0)
; #define PG8_LDA(dst, b, h) do { _Pragma("unroll") for (int m = 0; m < 4; ++m) _Pragma("unroll") for (int k = 0; k < 2; ++k) dst[m][k] = *(const PG8_LAS bf16x8*)(lds + PG8_SA(b, h) + aoff + m * 2048 + k * 1024); } while (0)
; #define PG8_LDB(dst, b, h) do { _Pragma("unroll") for (int n = 0; n < 2; ++n) _Pragma("unroll") for (int k = 0; k < 2; ++k) dst[n][k] = *(const PG8_LAS bf16x8*)(lds + PG8_SB(b, h) + boff + n * 2048 + k * 1024); } while (0)
; #define PG8_MMA(ai, bj, At, Bt) do { __builtin_amdgcn_s_setprio(1); _Pragma("unroll") for (int m = 0; m < 4; ++m) _Pragma("unroll") for (int n = 0; n < 2; ++n) _Pragma("unroll") for (int k = 0; k < 2; ++k) \
;         acc[ai][bj][m][n] = __builtin_amdgcn_mfma_f32_16x16x32_bf16(Bt[n][k], At[m][k], acc[ai][bj][m][n], 0, 0, 0); __builtin_amdgcn_s_setprio(0); } while (0)
; #define PG8_WAIT_V(n) asm volatile("s_waitcnt vmcnt(" #n ")" ::: "memory")
; #define PG8_WAIT_L(n) asm volatile("s_waitcnt lgkmcnt(" #n ")" ::: "memory")
; #define PG8_BAR __builtin_amdgcn_s_barrier()
; #define PG8_SCHED __builtin_amdgcn_sched_barrier(0)
; template <class Epi, class Sched, bool ALIGN_EPI = false, bool SP2 = false>
; __device__ __forceinline__ void gemm_phase(PG8_LAS unsigned char* lds, const Gemm g, const Sched& S, const Epi& E) {
;     ...
;             PG8_WAIT_V(8); PG8_WAIT_L(0); PG8_BAR; PG8_MMA(1, 0, At, B0); PG8_MMA(1, 1, At, B1); PG8_BAR; PG8_SCHED;
;             PG8_LDB(B0, 1, 0); PG8_LDB(B1, 1, 1); PG8_SCHED; PG8_LDA(At, 1, 0); PG8_STAGE(PG8_SA(0, 1), a2 + hstepA, voffA);
;             PG8_WAIT_V(8); PG8_WAIT_L(0); PG8_BAR; PG8_MMA(0, 0, At, B0); PG8_MMA(0, 1, At, B1); PG8_BAR; PG8_SCHED;
	s_setprio 1
	v_mfma_f32_16x16x32_bf16 v[60:63], v[140:143], v[172:175], v[60:63]
	v_mfma_f32_16x16x32_bf16 v[56:59], v[148:151], v[172:175], v[56:59]
	v_mfma_f32_16x16x32_bf16 v[52:55], v[140:143], v[180:183], v[52:55]
	v_mfma_f32_16x16x32_bf16 v[48:51], v[148:151], v[180:183], v[48:51]
	v_mfma_f32_16x16x32_bf16 v[40:43], v[140:143], v[202:205], v[40:43]
	v_mfma_f32_16x16x32_bf16 v[32:35], v[148:151], v[202:205], v[32:35]
	v_mfma_f32_16x16x32_bf16 v[24:27], v[140:143], v[210:213], v[24:27]
	v_mfma_f32_16x16x32_bf16 v[16:19], v[148:151], v[210:213], v[16:19]
	v_mfma_f32_16x16x32_bf16 v[60:63], v[144:147], v[176:179], v[60:63]
	v_mfma_f32_16x16x32_bf16 v[56:59], v[152:155], v[176:179], v[56:59]
	v_mfma_f32_16x16x32_bf16 v[52:55], v[144:147], v[184:187], v[52:55]
	v_mfma_f32_16x16x32_bf16 v[48:51], v[152:155], v[184:187], v[48:51]
	v_mfma_f32_16x16x32_bf16 v[40:43], v[144:147], v[206:209], v[40:43]
	v_mfma_f32_16x16x32_bf16 v[32:35], v[152:155], v[206:209], v[32:35]
	v_mfma_f32_16x16x32_bf16 v[24:27], v[144:147], v[214:217], v[24:27]
	v_mfma_f32_16x16x32_bf16 v[16:19], v[152:155], v[214:217], v[16:19]
	v_mfma_f32_16x16x32_bf16 v[44:47], v[156:159], v[172:175], v[44:47]
	v_mfma_f32_16x16x32_bf16 v[36:39], v[164:167], v[172:175], v[36:39]
	v_mfma_f32_16x16x32_bf16 v[28:31], v[156:159], v[180:183], v[28:31]
	v_mfma_f32_16x16x32_bf16 v[20:23], v[164:167], v[180:183], v[20:23]
	v_mfma_f32_16x16x32_bf16 v[12:15], v[156:159], v[202:205], v[12:15]
	v_mfma_f32_16x16x32_bf16 v[8:11], v[164:167], v[202:205], v[8:11]
	v_mfma_f32_16x16x32_bf16 v[4:7], v[156:159], v[210:213], v[4:7]
	v_mfma_f32_16x16x32_bf16 v[0:3], v[164:167], v[210:213], v[0:3]
	v_mfma_f32_16x16x32_bf16 v[44:47], v[160:163], v[176:179], v[44:47]
	v_mfma_f32_16x16x32_bf16 v[36:39], v[168:171], v[176:179], v[36:39]
	v_mfma_f32_16x16x32_bf16 v[28:31], v[160:163], v[184:187], v[28:31]
	v_mfma_f32_16x16x32_bf16 v[20:23], v[168:171], v[184:187], v[20:23]
	v_mfma_f32_16x16x32_bf16 v[12:15], v[160:163], v[206:209], v[12:15]
	v_mfma_f32_16x16x32_bf16 v[8:11], v[168:171], v[206:209], v[8:11]
	v_mfma_f32_16x16x32_bf16 v[4:7], v[160:163], v[214:217], v[4:7]
	v_mfma_f32_16x16x32_bf16 v[0:3], v[168:171], v[214:217], v[0:3]
	s_setprio 0
	s_barrier
	s_add_i32 s52, 0, 0x18000
	s_add_i32 s53, 0, 0x1c000
	v_add_u32_e32 v152, s52, v242
	v_add_u32_e32 v168, s53, v242
	ds_read_b128 v[140:143], v152
	ds_read_b128 v[144:147], v152 offset:1024
	ds_read_b128 v[148:151], v152 offset:2048
	ds_read_b128 v[152:155], v152 offset:3072
	ds_read_b128 v[156:159], v168
	ds_read_b128 v[160:163], v168 offset:1024
	ds_read_b128 v[164:167], v168 offset:2048
	ds_read_b128 v[168:171], v168 offset:3072
	s_add_u32 s4, s28, 0xb0000
	s_addc_u32 s5, s29, 0
	s_mov_b32 m0, s37
	v_lshl_add_u64 v[224:225], s[4:5], 0, v[134:135]
	ds_read_b128 v[172:175], v243 offset:32768
	ds_read_b128 v[176:179], v243 offset:33792
	ds_read_b128 v[180:183], v243 offset:34816
	ds_read_b128 v[184:187], v243 offset:35840
	ds_read_b128 v[202:205], v243 offset:36864
	ds_read_b128 v[206:209], v243 offset:37888
	ds_read_b128 v[210:213], v243 offset:38912
	ds_read_b128 v[214:217], v243 offset:39936
	global_load_lds_dwordx4 v[224:225], off
	v_lshl_add_u64 v[224:225], s[4:5], 0, v[132:133]
	s_mov_b32 m0, s38
	s_nop 0
	global_load_lds_dwordx4 v[224:225], off
	s_waitcnt vmcnt(8)
	s_waitcnt lgkmcnt(0)
	s_barrier
	s_setprio 1
	v_mfma_f32_16x16x32_bf16 v[126:129], v[140:143], v[172:175], v[126:129]
	v_mfma_f32_16x16x32_bf16 v[122:125], v[148:151], v[172:175], v[122:125]
	v_mfma_f32_16x16x32_bf16 v[118:121], v[140:143], v[180:183], v[118:121]
	v_mfma_f32_16x16x32_bf16 v[114:117], v[148:151], v[180:183], v[114:117]
	v_mfma_f32_16x16x32_bf16 v[106:109], v[140:143], v[202:205], v[106:109]
	v_mfma_f32_16x16x32_bf16 v[98:101], v[148:151], v[202:205], v[98:101]
	v_mfma_f32_16x16x32_bf16 v[90:93], v[140:143], v[210:213], v[90:93]
	v_mfma_f32_16x16x32_bf16 v[82:85], v[148:151], v[210:213], v[82:85]
	v_mfma_f32_16x16x32_bf16 v[126:129], v[144:147], v[176:179], v[126:129]
	v_mfma_f32_16x16x32_bf16 v[122:125], v[152:155], v[176:179], v[122:125]
	v_mfma_f32_16x16x32_bf16 v[118:121], v[144:147], v[184:187], v[118:121]
	v_mfma_f32_16x16x32_bf16 v[114:117], v[152:155], v[184:187], v[114:117]
	v_mfma_f32_16x16x32_bf16 v[106:109], v[144:147], v[206:209], v[106:109]
	v_mfma_f32_16x16x32_bf16 v[98:101], v[152:155], v[206:209], v[98:101]
	v_mfma_f32_16x16x32_bf16 v[90:93], v[144:147], v[214:217], v[90:93]
	v_mfma_f32_16x16x32_bf16 v[82:85], v[152:155], v[214:217], v[82:85]
	v_mfma_f32_16x16x32_bf16 v[110:113], v[156:159], v[172:175], v[110:113]
	v_mfma_f32_16x16x32_bf16 v[102:105], v[164:167], v[172:175], v[102:105]
	v_mfma_f32_16x16x32_bf16 v[94:97], v[156:159], v[180:183], v[94:97]
	v_mfma_f32_16x16x32_bf16 v[86:89], v[164:167], v[180:183], v[86:89]
	v_mfma_f32_16x16x32_bf16 v[78:81], v[156:159], v[202:205], v[78:81]
	v_mfma_f32_16x16x32_bf16 v[74:77], v[164:167], v[202:205], v[74:77]
	v_mfma_f32_16x16x32_bf16 v[70:73], v[156:159], v[210:213], v[70:73]
	v_mfma_f32_16x16x32_bf16 v[66:69], v[164:167], v[210:213], v[66:69]
	v_mfma_f32_16x16x32_bf16 v[110:113], v[160:163], v[176:179], v[110:113]
	v_mfma_f32_16x16x32_bf16 v[102:105], v[168:171], v[176:179], v[102:105]
	v_mfma_f32_16x16x32_bf16 v[94:97], v[160:163], v[184:187], v[94:97]
	v_mfma_f32_16x16x32_bf16 v[86:89], v[168:171], v[184:187], v[86:89]
	v_mfma_f32_16x16x32_bf16 v[78:81], v[160:163], v[206:209], v[78:81]
	v_mfma_f32_16x16x32_bf16 v[74:77], v[168:171], v[206:209], v[74:77]
	v_mfma_f32_16x16x32_bf16 v[70:73], v[160:163], v[214:217], v[70:73]
	v_mfma_f32_16x16x32_bf16 v[66:69], v[168:171], v[214:217], v[66:69]
	s_setprio 0
	s_barrier
; #define PG8_STAGE(bufoff, gbase, voff) do { _Pragma("unroll") for (int _i = 0; _i < 2; ++_i) \
;         __builtin_amdgcn_global_load_lds((const unsigned*)((const char*)(gbase) + (voff)[_i]), (PG8_LAS unsigned*)(lds + (bufoff) + ldsw + _i * 8192), 16, 0, 0); } while (0)
; #define PG8_LDA(dst, b, h) do { _Pragma("unroll") for (int m = 0; m < 4; ++m) _Pragma("unroll") for (int k = 0; k < 2; ++k) dst[m][k] = *(const PG8_LAS bf16x8*)(lds + PG8_SA(b, h) + aoff + m * 2048 + k * 1024); } while (0)
; #define PG8_MMA(ai, bj, At, Bt) do { __builtin_amdgcn_s_setprio(1); _Pragma("unroll") for (int m = 0; m < 4; ++m) _Pragma("unroll") for (int n = 0; n < 2; ++n) _Pragma("unroll") for (int k = 0; k < 2; ++k) \
;         acc[ai][bj][m][n] = __builtin_amdgcn_mfma_f32_16x16x32_bf16(Bt[n][k], At[m][k], acc[ai][bj][m][n], 0, 0, 0); __builtin_amdgcn_s_setprio(0); } while (0)
; #define PG8_WAIT_V(n) asm volatile("s_waitcnt vmcnt(" #n ")" ::: "memory")
; #define PG8_WAIT_L(n) asm volatile("s_waitcnt lgkmcnt(" #n ")" ::: "memory")
; #define PG8_BAR __builtin_amdgcn_s_barrier()
; #define PG8_SCHED __builtin_amdgcn_sched_barrier(0)
; template <class Epi, class Sched, bool ALIGN_EPI = false, bool SP2 = false>
; __device__ __forceinline__ void gemm_phase(PG8_LAS unsigned char* lds, const Gemm g, const Sched& S, const Epi& E) {
;     ...
;         for (int t = 0; t < ntc; t += 2) {
;     ...
;             PG8_LDA(At, 1, 1); PG8_STAGE(PG8_SB(1, 0), b3, voffB); PG8_STAGE(PG8_SB(1, 1), b3 + hstepB, voffB); PG8_STAGE(PG8_SA(1, 0), a3, voffA);
;             PG8_WAIT_V(8); PG8_WAIT_L(0); PG8_BAR; PG8_MMA(1, 0, At, B0); PG8_MMA(1, 1, At, B1); PG8_BAR; PG8_SCHED;
	s_add_i32 s4, s52, s30
	v_lshl_add_u64 v[188:189], v[188:189], 0, s[88:89]
	s_mov_b32 m0, s4
	ds_read_b128 v[172:175], v243 offset:49152
	ds_read_b128 v[176:179], v243 offset:50176
	ds_read_b128 v[180:183], v243 offset:51200
	ds_read_b128 v[184:187], v243 offset:52224
	ds_read_b128 v[202:205], v243 offset:53248
	ds_read_b128 v[206:209], v243 offset:54272
	ds_read_b128 v[210:213], v243 offset:55296
	ds_read_b128 v[214:217], v243 offset:56320
	global_load_lds_dwordx4 v[188:189], off
	s_add_i32 m0, s4, 0x2000
	s_add_u32 s4, s10, 0xb0080
	v_lshl_add_u64 v[188:189], v[218:219], 0, s[88:89]
	s_addc_u32 s5, s11, 0
	s_add_i32 s10, s53, s30
	global_load_lds_dwordx4 v[188:189], off
	v_lshl_add_u64 v[188:189], s[4:5], 0, v[64:65]
	s_mov_b32 m0, s10
	s_nop 0
	global_load_lds_dwordx4 v[188:189], off
	v_lshl_add_u64 v[188:189], s[4:5], 0, v[130:131]
	s_add_i32 m0, s10, 0x2000
	s_nop 0
	global_load_lds_dwordx4 v[188:189], off
	v_lshl_add_u64 v[188:189], v[220:221], 0, s[88:89]
	s_mov_b32 m0, s43
	s_nop 0
	global_load_lds_dwordx4 v[188:189], off
	v_lshl_add_u64 v[188:189], v[222:223], 0, s[88:89]
	s_mov_b32 m0, s44
	s_nop 0
	global_load_lds_dwordx4 v[188:189], off
	s_waitcnt vmcnt(8)
	s_waitcnt lgkmcnt(0)
	s_barrier
	s_setprio 1
	v_mfma_f32_16x16x32_bf16 v[60:63], v[140:143], v[172:175], v[60:63]
	v_mfma_f32_16x16x32_bf16 v[56:59], v[148:151], v[172:175], v[56:59]
	v_mfma_f32_16x16x32_bf16 v[52:55], v[140:143], v[180:183], v[52:55]
	v_mfma_f32_16x16x32_bf16 v[48:51], v[148:151], v[180:183], v[48:51]
	v_mfma_f32_16x16x32_bf16 v[40:43], v[140:143], v[202:205], v[40:43]
	v_mfma_f32_16x16x32_bf16 v[32:35], v[148:151], v[202:205], v[32:35]
	v_mfma_f32_16x16x32_bf16 v[24:27], v[140:143], v[210:213], v[24:27]
	v_mfma_f32_16x16x32_bf16 v[16:19], v[148:151], v[210:213], v[16:19]
	v_mfma_f32_16x16x32_bf16 v[60:63], v[144:147], v[176:179], v[60:63]
	v_mfma_f32_16x16x32_bf16 v[56:59], v[152:155], v[176:179], v[56:59]
	v_mfma_f32_16x16x32_bf16 v[52:55], v[144:147], v[184:187], v[52:55]
	v_mfma_f32_16x16x32_bf16 v[48:51], v[152:155], v[184:187], v[48:51]
	v_mfma_f32_16x16x32_bf16 v[40:43], v[144:147], v[206:209], v[40:43]
	v_mfma_f32_16x16x32_bf16 v[32:35], v[152:155], v[206:209], v[32:35]
	v_mfma_f32_16x16x32_bf16 v[24:27], v[144:147], v[214:217], v[24:27]
	v_mfma_f32_16x16x32_bf16 v[16:19], v[152:155], v[214:217], v[16:19]
	v_mfma_f32_16x16x32_bf16 v[44:47], v[156:159], v[172:175], v[44:47]
	v_mfma_f32_16x16x32_bf16 v[36:39], v[164:167], v[172:175], v[36:39]
	v_mfma_f32_16x16x32_bf16 v[28:31], v[156:159], v[180:183], v[28:31]
	v_mfma_f32_16x16x32_bf16 v[20:23], v[164:167], v[180:183], v[20:23]
	v_mfma_f32_16x16x32_bf16 v[12:15], v[156:159], v[202:205], v[12:15]
	v_mfma_f32_16x16x32_bf16 v[8:11], v[164:167], v[202:205], v[8:11]
	v_mfma_f32_16x16x32_bf16 v[4:7], v[156:159], v[210:213], v[4:7]
	v_mfma_f32_16x16x32_bf16 v[0:3], v[164:167], v[210:213], v[0:3]
	v_mfma_f32_16x16x32_bf16 v[44:47], v[160:163], v[176:179], v[44:47]
	v_mfma_f32_16x16x32_bf16 v[36:39], v[168:171], v[176:179], v[36:39]
	v_mfma_f32_16x16x32_bf16 v[28:31], v[160:163], v[184:187], v[28:31]
	v_mfma_f32_16x16x32_bf16 v[20:23], v[168:171], v[184:187], v[20:23]
	v_mfma_f32_16x16x32_bf16 v[12:15], v[160:163], v[206:209], v[12:15]
	v_mfma_f32_16x16x32_bf16 v[8:11], v[168:171], v[206:209], v[8:11]
	v_mfma_f32_16x16x32_bf16 v[4:7], v[160:163], v[214:217], v[4:7]
	v_mfma_f32_16x16x32_bf16 v[0:3], v[168:171], v[214:217], v[0:3]
	s_setprio 0
	s_barrier
	s_add_u32 s49, s49, 0x100
	s_addc_u32 s50, s50, 0
	s_cmp_ge_i32 s51, s41
	s_mov_b64 s[4:5], s[8:9]
	s_mov_b32 s10, s51
	s_cbranch_scc0 .LBB0_278
;     __device__ __forceinline__ void operator()(const f32x4 (&acc)[2][2][4][2], const Unit& u, int wr, int wc, int fr, int fq, const float (&)[8]) const {
;     ...
;         for (int ai = 0; ai < 2; ++ai)
; #pragma unroll
;             for (int m = 0; m < 4; ++m) {
;                 const int row = u.pm * BM + ai * HALF + wr * 64 + m * 16 + fr; float sq = 0.f;
; #pragma unroll
;                 for (int bj = 0; bj < 2; ++bj) {
;                     const size_t off = off0 + (size_t)ai * (HALF * 1024) + (size_t)m * (16 * 1024) + bj * HALF;
;                     f32x4 b0, b1;
;                     if (xf) { b0 = *(const f32x4*)(xf + off); b1 = *(const f32x4*)(xf + off + 4); }
;                     else { const u32x4 w = raw[ai * 4 + m][bj];
;                         b0[0] = __uint_as_float(w.x << 16); b0[1] = __uint_as_float(w.x & 0xffff0000u); b0[2] = __uint_as_float(w.y << 16); b0[3] = __uint_as_float(w.y & 0xffff0000u);
;                         b1[0] = __uint_as_float(w.z << 16); b1[1] = __uint_as_float(w.z & 0xffff0000u); b1[2] = __uint_as_float(w.w << 16); b1[3] = __uint_as_float(w.w & 0xffff0000u); }
;                     const f32x4 o0 = b0 + acc[ai][bj][m][0] * alpha, o1 = b1 + acc[ai][bj][m][1] * alpha;
	v_pk_mul_f32 v[128:129], v[128:129], 0.5 op_sel_hi:[1,0]
	v_pk_mul_f32 v[218:219], v[126:127], 0.5 op_sel_hi:[1,0]
	v_pk_mul_f32 v[222:223], v[124:125], 0.5 op_sel_hi:[1,0]
	v_pk_mul_f32 v[226:227], v[122:123], 0.5 op_sel_hi:[1,0]
	v_pk_mul_f32 v[224:225], v[112:113], 0.5 op_sel_hi:[1,0]
	v_pk_mul_f32 v[220:221], v[110:111], 0.5 op_sel_hi:[1,0]
	v_pk_mul_f32 v[216:217], v[104:105], 0.5 op_sel_hi:[1,0]
	v_pk_mul_f32 v[214:215], v[102:103], 0.5 op_sel_hi:[1,0]
	v_pk_mul_f32 v[212:213], v[120:121], 0.5 op_sel_hi:[1,0]
	v_pk_mul_f32 v[210:211], v[118:119], 0.5 op_sel_hi:[1,0]
	v_pk_mul_f32 v[208:209], v[116:117], 0.5 op_sel_hi:[1,0]
	v_pk_mul_f32 v[206:207], v[114:115], 0.5 op_sel_hi:[1,0]
	v_pk_mul_f32 v[204:205], v[96:97], 0.5 op_sel_hi:[1,0]
	v_pk_mul_f32 v[202:203], v[94:95], 0.5 op_sel_hi:[1,0]
	v_pk_mul_f32 v[188:189], v[88:89], 0.5 op_sel_hi:[1,0]
	v_pk_mul_f32 v[186:187], v[86:87], 0.5 op_sel_hi:[1,0]
	v_pk_mul_f32 v[184:185], v[108:109], 0.5 op_sel_hi:[1,0]
	v_pk_mul_f32 v[182:183], v[106:107], 0.5 op_sel_hi:[1,0]
	v_pk_mul_f32 v[180:181], v[100:101], 0.5 op_sel_hi:[1,0]
	v_pk_mul_f32 v[178:179], v[98:99], 0.5 op_sel_hi:[1,0]
	v_pk_mul_f32 v[176:177], v[80:81], 0.5 op_sel_hi:[1,0]
	v_pk_mul_f32 v[174:175], v[78:79], 0.5 op_sel_hi:[1,0]
	v_pk_mul_f32 v[172:173], v[76:77], 0.5 op_sel_hi:[1,0]
	v_pk_mul_f32 v[170:171], v[74:75], 0.5 op_sel_hi:[1,0]
	v_pk_mul_f32 v[168:169], v[92:93], 0.5 op_sel_hi:[1,0]
	v_pk_mul_f32 v[166:167], v[90:91], 0.5 op_sel_hi:[1,0]
	v_pk_mul_f32 v[164:165], v[84:85], 0.5 op_sel_hi:[1,0]
	v_pk_mul_f32 v[162:163], v[82:83], 0.5 op_sel_hi:[1,0]
	v_pk_mul_f32 v[160:161], v[72:73], 0.5 op_sel_hi:[1,0]
	v_pk_mul_f32 v[158:159], v[70:71], 0.5 op_sel_hi:[1,0]
	v_pk_mul_f32 v[156:157], v[68:69], 0.5 op_sel_hi:[1,0]
	v_pk_mul_f32 v[154:155], v[66:67], 0.5 op_sel_hi:[1,0]
	v_pk_mul_f32 v[152:153], v[62:63], 0.5 op_sel_hi:[1,0]
	v_pk_mul_f32 v[150:151], v[60:61], 0.5 op_sel_hi:[1,0]
	v_pk_mul_f32 v[148:149], v[58:59], 0.5 op_sel_hi:[1,0]
	v_pk_mul_f32 v[146:147], v[56:57], 0.5 op_sel_hi:[1,0]
	v_pk_mul_f32 v[144:145], v[46:47], 0.5 op_sel_hi:[1,0]
	v_pk_mul_f32 v[142:143], v[44:45], 0.5 op_sel_hi:[1,0]
	v_pk_mul_f32 v[140:141], v[38:39], 0.5 op_sel_hi:[1,0]
	v_pk_mul_f32 v[126:127], v[36:37], 0.5 op_sel_hi:[1,0]
	v_pk_mul_f32 v[122:123], v[54:55], 0.5 op_sel_hi:[1,0]
	v_pk_mul_f32 v[120:121], v[52:53], 0.5 op_sel_hi:[1,0]
	v_pk_mul_f32 v[118:119], v[50:51], 0.5 op_sel_hi:[1,0]
	v_pk_mul_f32 v[116:117], v[48:49], 0.5 op_sel_hi:[1,0]
	v_pk_mul_f32 v[114:115], v[30:31], 0.5 op_sel_hi:[1,0]
	v_pk_mul_f32 v[112:113], v[28:29], 0.5 op_sel_hi:[1,0]
	v_pk_mul_f32 v[110:111], v[22:23], 0.5 op_sel_hi:[1,0]
	v_pk_mul_f32 v[108:109], v[20:21], 0.5 op_sel_hi:[1,0]
	v_pk_mul_f32 v[104:105], v[42:43], 0.5 op_sel_hi:[1,0]
	v_pk_mul_f32 v[102:103], v[40:41], 0.5 op_sel_hi:[1,0]
	v_pk_mul_f32 v[100:101], v[34:35], 0.5 op_sel_hi:[1,0]
	v_pk_mul_f32 v[98:99], v[32:33], 0.5 op_sel_hi:[1,0]
	v_pk_mul_f32 v[96:97], v[14:15], 0.5 op_sel_hi:[1,0]
	v_pk_mul_f32 v[94:95], v[12:13], 0.5 op_sel_hi:[1,0]
	v_pk_mul_f32 v[92:93], v[10:11], 0.5 op_sel_hi:[1,0]
	v_pk_mul_f32 v[90:91], v[8:9], 0.5 op_sel_hi:[1,0]
	v_pk_mul_f32 v[88:89], v[26:27], 0.5 op_sel_hi:[1,0]
	v_pk_mul_f32 v[86:87], v[24:25], 0.5 op_sel_hi:[1,0]
	v_pk_mul_f32 v[84:85], v[18:19], 0.5 op_sel_hi:[1,0]
	v_pk_mul_f32 v[82:83], v[16:17], 0.5 op_sel_hi:[1,0]
	v_pk_mul_f32 v[80:81], v[6:7], 0.5 op_sel_hi:[1,0]
	v_pk_mul_f32 v[78:79], v[4:5], 0.5 op_sel_hi:[1,0]
	v_pk_mul_f32 v[76:77], v[2:3], 0.5 op_sel_hi:[1,0]
	v_pk_mul_f32 v[74:75], v[0:1], 0.5 op_sel_hi:[1,0]

; #define PG8_STAGE(bufoff, gbase, voff) do { _Pragma("unroll") for (int _i = 0; _i < 2; ++_i) \
;         __builtin_amdgcn_global_load_lds((const unsigned*)((const char*)(gbase) + (voff)[_i]), (PG8_LAS unsigned*)(lds + (bufoff) + ldsw + _i * 8192), 16, 0, 0); } while (0)
; #define PG8_LDA(dst, b, h) do { _Pragma("unroll") for (int m = 0; m < 4; ++m) _Pragma("unroll") for (int k = 0; k < 2; ++k) dst[m][k] = *(const PG8_LAS bf16x8*)(lds + PG8_SA(b, h) + aoff + m * 2048 + k * 1024); } while (0)
; #define PG8_LDB(dst, b, h) do { _Pragma("unroll") for (int n = 0; n < 2; ++n) _Pragma("unroll") for (int k = 0; k < 2; ++k) dst[n][k] = *(const PG8_LAS bf16x8*)(lds + PG8_SB(b, h) + boff + n * 2048 + k * 1024); } while (0)
; #define PG8_MMA(ai, bj, At, Bt) do { __builtin_amdgcn_s_setprio(1); _Pragma("unroll") for (int m = 0; m < 4; ++m) _Pragma("unroll") for (int n = 0; n < 2; ++n) _Pragma("unroll") for (int k = 0; k < 2; ++k) \
;         acc[ai][bj][m][n] = __builtin_amdgcn_mfma_f32_16x16x32_bf16(Bt[n][k], At[m][k], acc[ai][bj][m][n], 0, 0, 0); __builtin_amdgcn_s_setprio(0); } while (0)
; #define PG8_WAIT_V(n) asm volatile("s_waitcnt vmcnt(" #n ")" ::: "memory")
; #define PG8_WAIT_L(n) asm volatile("s_waitcnt lgkmcnt(" #n ")" ::: "memory")
; #define PG8_BAR __builtin_amdgcn_s_barrier()
; #define PG8_SCHED __builtin_amdgcn_sched_barrier(0)
; template <class Epi, class Sched, bool ALIGN_EPI = false, bool SP2 = false>
; __device__ __forceinline__ void gemm_phase(PG8_LAS unsigned char* lds, const Gemm g, const Sched& S, const Epi& E) {
;     ...
;         for (int t = 0; t < ntc; t += 2) {
;             const bool last = (t == ntc - 2);
;             const char* a1 = cA + (size_t)(t + 1) * kstep;
;             const char* a2 = last ? nA : cA + (size_t)(t + 2) * kstep; const char* b2 = last ? nB : cB + (size_t)(t + 2) * kstep;
;             const char* a3 = a2 + kstep; const char* b3 = b2 + kstep;
;             if (last && has_next) S.a_ready(nxt);
;             if constexpr (SP2) {
;             PG8_LDB(B0, 0, 0); PG8_LDB(B1, 0, 1); PG8_SCHED; PG8_LDA(At, 0, 0); PG8_STAGE(PG8_SA(1, 1), a1 + hstepA, voffA);
;             PG8_WAIT_V(8); PG8_WAIT_L(0); PG8_BAR; PG8_MMA(0, 0, At, B0); PG8_MMA(0, 1, At, B1); PG8_BAR; PG8_SCHED;
;             PG8_LDA(At, 0, 1); PG8_STAGE(PG8_SB(0, 0), b2, voffB); PG8_STAGE(PG8_SB(0, 1), b2 + hstepB, voffB); PG8_STAGE(PG8_SA(0, 0), a2, voffA);
.LBB0_404:
	s_add_i32 s47, s24, 2
	s_add_u32 s25, s4, 0xfffc0080
	s_addc_u32 s26, s5, -1
	s_add_i32 s48, 0, 0x10000
	s_cmp_eq_u32 s39, s24
	s_cselect_b32 s27, s17, s26
	s_cselect_b32 s26, s19, s25
	s_cselect_b32 s25, s43, s46
	s_cselect_b32 s24, s44, s45
	s_add_i32 s50, 0, 0x14000
	v_add_u32_e32 v60, s48, v177
	v_add_u32_e32 v86, s50, v177
	ds_read_b128 v[48:51], v60
	ds_read_b128 v[52:55], v60 offset:1024
	ds_read_b128 v[56:59], v60 offset:2048
	ds_read_b128 v[60:63], v60 offset:3072
	ds_read_b128 v[66:69], v86
	ds_read_b128 v[78:81], v86 offset:1024
	ds_read_b128 v[82:85], v86 offset:2048
	ds_read_b128 v[86:89], v86 offset:3072
	v_lshl_add_u64 v[186:187], s[4:5], 0, v[168:169]
	s_add_i32 m0, s30, 0xc000
	ds_read_b128 v[202:205], v179
	ds_read_b128 v[206:209], v179 offset:1024
	ds_read_b128 v[210:213], v179 offset:2048
	ds_read_b128 v[214:217], v179 offset:3072
	ds_read_b128 v[218:221], v179 offset:4096
	ds_read_b128 v[222:225], v179 offset:5120
	ds_read_b128 v[240:243], v179 offset:6144
	ds_read_b128 v[244:247], v179 offset:7168
	global_load_lds_dwordx4 v[186:187], off
	v_lshl_add_u64 v[186:187], s[4:5], 0, v[170:171]
	s_add_i32 m0, s30, 0xe000
	s_nop 0
	global_load_lds_dwordx4 v[186:187], off
	s_waitcnt vmcnt(8)
	s_waitcnt lgkmcnt(0)
	s_barrier
	s_setprio 1
	v_mfma_f32_16x16x32_bf16 v[158:161], v[48:51], v[202:205], v[158:161]
	v_mfma_f32_16x16x32_bf16 v[154:157], v[56:59], v[202:205], v[154:157]
	v_mfma_f32_16x16x32_bf16 v[142:145], v[48:51], v[210:213], v[142:145]
	v_mfma_f32_16x16x32_bf16 v[138:141], v[56:59], v[210:213], v[138:141]
	v_mfma_f32_16x16x32_bf16 v[126:129], v[48:51], v[218:221], v[126:129]
	v_mfma_f32_16x16x32_bf16 v[122:125], v[56:59], v[218:221], v[122:125]
	v_mfma_f32_16x16x32_bf16 v[110:113], v[48:51], v[240:243], v[110:113]
	v_mfma_f32_16x16x32_bf16 v[106:109], v[56:59], v[240:243], v[106:109]
	v_mfma_f32_16x16x32_bf16 v[158:161], v[52:55], v[206:209], v[158:161]
	v_mfma_f32_16x16x32_bf16 v[154:157], v[60:63], v[206:209], v[154:157]
	v_mfma_f32_16x16x32_bf16 v[142:145], v[52:55], v[214:217], v[142:145]
	v_mfma_f32_16x16x32_bf16 v[138:141], v[60:63], v[214:217], v[138:141]
	v_mfma_f32_16x16x32_bf16 v[126:129], v[52:55], v[222:225], v[126:129]
	v_mfma_f32_16x16x32_bf16 v[122:125], v[60:63], v[222:225], v[122:125]
	v_mfma_f32_16x16x32_bf16 v[110:113], v[52:55], v[244:247], v[110:113]
	v_mfma_f32_16x16x32_bf16 v[106:109], v[60:63], v[244:247], v[106:109]
	v_mfma_f32_16x16x32_bf16 v[150:153], v[66:69], v[202:205], v[150:153]
	v_mfma_f32_16x16x32_bf16 v[146:149], v[82:85], v[202:205], v[146:149]
	v_mfma_f32_16x16x32_bf16 v[134:137], v[66:69], v[210:213], v[134:137]
	v_mfma_f32_16x16x32_bf16 v[130:133], v[82:85], v[210:213], v[130:133]
	v_mfma_f32_16x16x32_bf16 v[118:121], v[66:69], v[218:221], v[118:121]
	v_mfma_f32_16x16x32_bf16 v[114:117], v[82:85], v[218:221], v[114:117]
	v_mfma_f32_16x16x32_bf16 v[102:105], v[66:69], v[240:243], v[102:105]
	v_mfma_f32_16x16x32_bf16 v[98:101], v[82:85], v[240:243], v[98:101]
	v_mfma_f32_16x16x32_bf16 v[150:153], v[78:81], v[206:209], v[150:153]
	v_mfma_f32_16x16x32_bf16 v[146:149], v[86:89], v[206:209], v[146:149]
	v_mfma_f32_16x16x32_bf16 v[134:137], v[78:81], v[214:217], v[134:137]
	v_mfma_f32_16x16x32_bf16 v[130:133], v[86:89], v[214:217], v[130:133]
	v_mfma_f32_16x16x32_bf16 v[118:121], v[78:81], v[222:225], v[118:121]
	v_mfma_f32_16x16x32_bf16 v[114:117], v[86:89], v[222:225], v[114:117]
	v_mfma_f32_16x16x32_bf16 v[102:105], v[78:81], v[244:247], v[102:105]
	v_mfma_f32_16x16x32_bf16 v[98:101], v[86:89], v[244:247], v[98:101]
	s_setprio 0
	s_barrier
	s_add_i32 s48, s48, s28
	v_lshl_add_u64 v[186:187], s[24:25], 0, v[64:65]
	s_mov_b32 m0, s48
	ds_read_b128 v[202:205], v179 offset:16384
	ds_read_b128 v[206:209], v179 offset:17408
	ds_read_b128 v[210:213], v179 offset:18432
	ds_read_b128 v[214:217], v179 offset:19456
	ds_read_b128 v[218:221], v179 offset:20480
	ds_read_b128 v[222:225], v179 offset:21504
	ds_read_b128 v[240:243], v179 offset:22528
	ds_read_b128 v[244:247], v179 offset:23552
	global_load_lds_dwordx4 v[186:187], off
	s_add_i32 m0, s48, 0x2000
	s_add_u32 s48, s24, 0x40000
	v_lshl_add_u64 v[226:227], s[24:25], 0, v[162:163]
	s_addc_u32 s49, s25, 0
	s_add_i32 s50, s50, s28
	global_load_lds_dwordx4 v[226:227], off
	v_lshl_add_u64 v[248:249], s[48:49], 0, v[64:65]
	s_mov_b32 m0, s50
	v_lshl_add_u64 v[252:253], s[26:27], 0, v[166:167]
	global_load_lds_dwordx4 v[248:249], off
	v_lshl_add_u64 v[248:249], s[48:49], 0, v[162:163]
	s_add_i32 m0, s50, 0x2000
	v_lshl_add_u64 v[234:235], s[26:27], 0, v[164:165]
	global_load_lds_dwordx4 v[248:249], off
	s_mov_b32 m0, s30
	s_nop 0
	global_load_lds_dwordx4 v[252:253], off
	s_mov_b32 m0, s31
	s_nop 0
	global_load_lds_dwordx4 v[234:235], off
	s_waitcnt vmcnt(8)
	s_waitcnt lgkmcnt(0)
	s_barrier
; #define PG8_STAGE(bufoff, gbase, voff) do { _Pragma("unroll") for (int _i = 0; _i < 2; ++_i) \
;         __builtin_amdgcn_global_load_lds((const unsigned*)((const char*)(gbase) + (voff)[_i]), (PG8_LAS unsigned*)(lds + (bufoff) + ldsw + _i * 8192), 16, 0, 0); } while (0)
; #define PG8_LDA(dst, b, h) do { _Pragma("unroll") for (int m = 0; m < 4; ++m) _Pragma("unroll") for (int k = 0; k < 2; ++k) dst[m][k] = *(const PG8_LAS bf16x8*)(lds + PG8_SA(b, h) + aoff + m * 2048 + k * 1024); } while (0)
; #define PG8_LDB(dst, b, h) do { _Pragma("unroll") for (int n = 0; n < 2; ++n) _Pragma("unroll") for (int k = 0; k < 2; ++k) dst[n][k] = *(const PG8_LAS bf16x8*)(lds + PG8_SB(b, h) + boff + n * 2048 + k * 1024); } while (0)
; #define PG8_MMA(ai, bj, At, Bt) do { __builtin_amdgcn_s_setprio(1); _Pragma("unroll") for (int m = 0; m < 4; ++m) _Pragma("unroll") for (int n = 0; n < 2; ++n) _Pragma("unroll") for (int k = 0; k < 2; ++k) \
;         acc[ai][bj][m][n] = __builtin_amdgcn_mfma_f32_16x16x32_bf16(Bt[n][k], At[m][k], acc[ai][bj][m][n], 0, 0, 0); __builtin_amdgcn_s_setprio(0); } while (0)
; #define PG8_WAIT_V(n) asm volatile("s_waitcnt vmcnt(" #n ")" ::: "memory")
; #define PG8_WAIT_L(n) asm volatile("s_waitcnt lgkmcnt(" #n ")" ::: "memory")
; #define PG8_BAR __builtin_amdgcn_s_barrier()
; #define PG8_SCHED __builtin_amdgcn_sched_barrier(0)
; template <class Epi, class Sched, bool ALIGN_EPI = false, bool SP2 = false>
; __device__ __forceinline__ void gemm_phase(PG8_LAS unsigned char* lds, const Gemm g, const Sched& S, const Epi& E) {
;     ...
;             PG8_WAIT_V(8); PG8_WAIT_L(0); PG8_BAR; PG8_MMA(1, 0, At, B0); PG8_MMA(1, 1, At, B1); PG8_BAR; PG8_SCHED;
;             PG8_LDB(B0, 1, 0); PG8_LDB(B1, 1, 1); PG8_SCHED; PG8_LDA(At, 1, 0); PG8_STAGE(PG8_SA(0, 1), a2 + hstepA, voffA);
;             PG8_WAIT_V(8); PG8_WAIT_L(0); PG8_BAR; PG8_MMA(0, 0, At, B0); PG8_MMA(0, 1, At, B1); PG8_BAR; PG8_SCHED;
	s_setprio 1
	v_mfma_f32_16x16x32_bf16 v[94:97], v[48:51], v[202:205], v[94:97]
	v_mfma_f32_16x16x32_bf16 v[90:93], v[56:59], v[202:205], v[90:93]
	v_mfma_f32_16x16x32_bf16 v[44:47], v[48:51], v[210:213], v[44:47]
	v_mfma_f32_16x16x32_bf16 v[40:43], v[56:59], v[210:213], v[40:43]
	v_mfma_f32_16x16x32_bf16 v[28:31], v[48:51], v[218:221], v[28:31]
	v_mfma_f32_16x16x32_bf16 v[24:27], v[56:59], v[218:221], v[24:27]
	v_mfma_f32_16x16x32_bf16 v[12:15], v[48:51], v[240:243], v[12:15]
	v_mfma_f32_16x16x32_bf16 v[8:11], v[56:59], v[240:243], v[8:11]
	v_mfma_f32_16x16x32_bf16 v[94:97], v[52:55], v[206:209], v[94:97]
	v_mfma_f32_16x16x32_bf16 v[90:93], v[60:63], v[206:209], v[90:93]
	v_mfma_f32_16x16x32_bf16 v[44:47], v[52:55], v[214:217], v[44:47]
	v_mfma_f32_16x16x32_bf16 v[40:43], v[60:63], v[214:217], v[40:43]
	v_mfma_f32_16x16x32_bf16 v[28:31], v[52:55], v[222:225], v[28:31]
	v_mfma_f32_16x16x32_bf16 v[24:27], v[60:63], v[222:225], v[24:27]
	v_mfma_f32_16x16x32_bf16 v[12:15], v[52:55], v[244:247], v[12:15]
	v_mfma_f32_16x16x32_bf16 v[8:11], v[60:63], v[244:247], v[8:11]
	v_mfma_f32_16x16x32_bf16 v[36:39], v[66:69], v[210:213], v[36:39]
	v_mfma_f32_16x16x32_bf16 v[32:35], v[82:85], v[210:213], v[32:35]
	v_mfma_f32_16x16x32_bf16 v[20:23], v[66:69], v[218:221], v[20:23]
	v_mfma_f32_16x16x32_bf16 v[16:19], v[82:85], v[218:221], v[16:19]
	v_mfma_f32_16x16x32_bf16 v[4:7], v[66:69], v[240:243], v[4:7]
	v_mfma_f32_16x16x32_bf16 v[0:3], v[82:85], v[240:243], v[0:3]
	v_mfma_f32_16x16x32_bf16 v[48:51], v[66:69], v[202:205], v[74:77]
	v_mfma_f32_16x16x32_bf16 v[52:55], v[82:85], v[202:205], v[70:73]
	v_mfma_f32_16x16x32_bf16 v[36:39], v[78:81], v[214:217], v[36:39]
	v_mfma_f32_16x16x32_bf16 v[32:35], v[86:89], v[214:217], v[32:35]
	v_mfma_f32_16x16x32_bf16 v[20:23], v[78:81], v[222:225], v[20:23]
	v_mfma_f32_16x16x32_bf16 v[16:19], v[86:89], v[222:225], v[16:19]
	v_mfma_f32_16x16x32_bf16 v[4:7], v[78:81], v[244:247], v[4:7]
	v_mfma_f32_16x16x32_bf16 v[0:3], v[86:89], v[244:247], v[0:3]
	v_mfma_f32_16x16x32_bf16 v[48:51], v[78:81], v[206:209], v[48:51]
	v_mfma_f32_16x16x32_bf16 v[52:55], v[86:89], v[206:209], v[52:55]
	s_setprio 0
	s_barrier
	s_add_i32 s48, 0, 0x18000
	s_add_i32 s49, 0, 0x1c000
	v_add_u32_e32 v70, s48, v177
	v_add_u32_e32 v74, s49, v177
	ds_read_b128 v[56:59], v70
	ds_read_b128 v[60:63], v70 offset:1024
	ds_read_b128 v[66:69], v70 offset:2048
	ds_read_b128 v[70:73], v70 offset:3072
	ds_read_b128 v[78:81], v74
	ds_read_b128 v[82:85], v74 offset:1024
	ds_read_b128 v[86:89], v74 offset:2048
	ds_read_b128 v[202:205], v74 offset:3072
	s_add_u32 s26, s26, 0x40000
	s_addc_u32 s27, s27, 0
	s_mov_b32 m0, s34
	v_lshl_add_u64 v[248:249], s[26:27], 0, v[166:167]
	ds_read_b128 v[74:77], v179 offset:32768
	ds_read_b128 v[206:209], v179 offset:33792
	ds_read_b128 v[210:213], v179 offset:34816
	ds_read_b128 v[214:217], v179 offset:35840
	ds_read_b128 v[218:221], v179 offset:36864
	ds_read_b128 v[222:225], v179 offset:37888
	ds_read_b128 v[240:243], v179 offset:38912
	ds_read_b128 v[244:247], v179 offset:39936
	global_load_lds_dwordx4 v[248:249], off
	v_lshl_add_u64 v[248:249], s[26:27], 0, v[164:165]
	s_mov_b32 m0, s35
	s_nop 0
	global_load_lds_dwordx4 v[248:249], off
	s_waitcnt vmcnt(8)
	s_waitcnt lgkmcnt(0)
	s_barrier
	s_setprio 1
	v_mfma_f32_16x16x32_bf16 v[158:161], v[56:59], v[74:77], v[158:161]
	v_mfma_f32_16x16x32_bf16 v[154:157], v[66:69], v[74:77], v[154:157]
	v_mfma_f32_16x16x32_bf16 v[142:145], v[56:59], v[210:213], v[142:145]
	v_mfma_f32_16x16x32_bf16 v[138:141], v[66:69], v[210:213], v[138:141]
	v_mfma_f32_16x16x32_bf16 v[126:129], v[56:59], v[218:221], v[126:129]
	v_mfma_f32_16x16x32_bf16 v[122:125], v[66:69], v[218:221], v[122:125]
	v_mfma_f32_16x16x32_bf16 v[110:113], v[56:59], v[240:243], v[110:113]
	v_mfma_f32_16x16x32_bf16 v[106:109], v[66:69], v[240:243], v[106:109]
	v_mfma_f32_16x16x32_bf16 v[158:161], v[60:63], v[206:209], v[158:161]
	v_mfma_f32_16x16x32_bf16 v[154:157], v[70:73], v[206:209], v[154:157]
	v_mfma_f32_16x16x32_bf16 v[142:145], v[60:63], v[214:217], v[142:145]
	v_mfma_f32_16x16x32_bf16 v[138:141], v[70:73], v[214:217], v[138:141]
	v_mfma_f32_16x16x32_bf16 v[126:129], v[60:63], v[222:225], v[126:129]
	v_mfma_f32_16x16x32_bf16 v[122:125], v[70:73], v[222:225], v[122:125]
	v_mfma_f32_16x16x32_bf16 v[110:113], v[60:63], v[244:247], v[110:113]
	v_mfma_f32_16x16x32_bf16 v[106:109], v[70:73], v[244:247], v[106:109]
	v_mfma_f32_16x16x32_bf16 v[150:153], v[78:81], v[74:77], v[150:153]
	v_mfma_f32_16x16x32_bf16 v[74:77], v[86:89], v[74:77], v[146:149]
	v_mfma_f32_16x16x32_bf16 v[146:149], v[202:205], v[206:209], v[74:77]
	v_mfma_f32_16x16x32_bf16 v[74:77], v[78:81], v[210:213], v[134:137]
	v_mfma_f32_16x16x32_bf16 v[134:137], v[82:85], v[214:217], v[74:77]
	v_mfma_f32_16x16x32_bf16 v[74:77], v[86:89], v[210:213], v[130:133]
	v_mfma_f32_16x16x32_bf16 v[130:133], v[202:205], v[214:217], v[74:77]
	v_mfma_f32_16x16x32_bf16 v[74:77], v[78:81], v[218:221], v[118:121]
	v_mfma_f32_16x16x32_bf16 v[118:121], v[82:85], v[222:225], v[74:77]
	v_mfma_f32_16x16x32_bf16 v[74:77], v[86:89], v[218:221], v[114:117]
	v_mfma_f32_16x16x32_bf16 v[114:117], v[202:205], v[222:225], v[74:77]
	v_mfma_f32_16x16x32_bf16 v[74:77], v[78:81], v[240:243], v[102:105]
	v_mfma_f32_16x16x32_bf16 v[102:105], v[82:85], v[244:247], v[74:77]
	v_mfma_f32_16x16x32_bf16 v[74:77], v[86:89], v[240:243], v[98:101]
	v_mfma_f32_16x16x32_bf16 v[150:153], v[82:85], v[206:209], v[150:153]
	v_mfma_f32_16x16x32_bf16 v[98:101], v[202:205], v[244:247], v[74:77]
	s_setprio 0
	s_barrier
; #define PG8_STAGE(bufoff, gbase, voff) do { _Pragma("unroll") for (int _i = 0; _i < 2; ++_i) \
;         __builtin_amdgcn_global_load_lds((const unsigned*)((const char*)(gbase) + (voff)[_i]), (PG8_LAS unsigned*)(lds + (bufoff) + ldsw + _i * 8192), 16, 0, 0); } while (0)
; #define PG8_LDA(dst, b, h) do { _Pragma("unroll") for (int m = 0; m < 4; ++m) _Pragma("unroll") for (int k = 0; k < 2; ++k) dst[m][k] = *(const PG8_LAS bf16x8*)(lds + PG8_SA(b, h) + aoff + m * 2048 + k * 1024); } while (0)
; #define PG8_MMA(ai, bj, At, Bt) do { __builtin_amdgcn_s_setprio(1); _Pragma("unroll") for (int m = 0; m < 4; ++m) _Pragma("unroll") for (int n = 0; n < 2; ++n) _Pragma("unroll") for (int k = 0; k < 2; ++k) \
;         acc[ai][bj][m][n] = __builtin_amdgcn_mfma_f32_16x16x32_bf16(Bt[n][k], At[m][k], acc[ai][bj][m][n], 0, 0, 0); __builtin_amdgcn_s_setprio(0); } while (0)
; #define PG8_WAIT_V(n) asm volatile("s_waitcnt vmcnt(" #n ")" ::: "memory")
; #define PG8_WAIT_L(n) asm volatile("s_waitcnt lgkmcnt(" #n ")" ::: "memory")
; #define PG8_BAR __builtin_amdgcn_s_barrier()
; #define PG8_SCHED __builtin_amdgcn_sched_barrier(0)
; template <class Epi, class Sched, bool ALIGN_EPI = false, bool SP2 = false>
; __device__ __forceinline__ void gemm_phase(PG8_LAS unsigned char* lds, const Gemm g, const Sched& S, const Epi& E) {
;     ...
;             PG8_LDA(At, 1, 1); PG8_STAGE(PG8_SB(1, 0), b3, voffB); PG8_STAGE(PG8_SB(1, 1), b3 + hstepB, voffB); PG8_STAGE(PG8_SA(1, 0), a3, voffA);
;             PG8_WAIT_V(8); PG8_WAIT_L(0); PG8_BAR; PG8_MMA(1, 0, At, B0); PG8_MMA(1, 1, At, B1); PG8_BAR; PG8_SCHED;
	s_add_i32 s26, s48, s28
	s_nop 2
	v_lshl_add_u64 v[74:75], v[186:187], 0, s[88:89]
	s_mov_b32 m0, s26
	ds_read_b128 v[206:209], v179 offset:49152
	ds_read_b128 v[210:213], v179 offset:50176
	ds_read_b128 v[214:217], v179 offset:51200
	ds_read_b128 v[218:221], v179 offset:52224
	ds_read_b128 v[222:225], v179 offset:53248
	ds_read_b128 v[240:243], v179 offset:54272
	ds_read_b128 v[244:247], v179 offset:55296
	ds_read_b128 v[248:251], v179 offset:56320
	global_load_lds_dwordx4 v[74:75], off
	s_add_i32 m0, s26, 0x2000
	s_add_u32 s24, s24, 0x40080
	v_lshl_add_u64 v[74:75], v[226:227], 0, s[88:89]
	s_addc_u32 s25, s25, 0
	s_add_i32 s26, s49, s28
	global_load_lds_dwordx4 v[74:75], off
	v_lshl_add_u64 v[74:75], s[24:25], 0, v[64:65]
	s_mov_b32 m0, s26
	s_nop 0
	global_load_lds_dwordx4 v[74:75], off
	v_lshl_add_u64 v[74:75], s[24:25], 0, v[162:163]
	s_add_i32 m0, s26, 0x2000
	s_nop 0
	global_load_lds_dwordx4 v[74:75], off
	v_lshl_add_u64 v[74:75], v[252:253], 0, s[88:89]
	s_mov_b32 m0, s37
	s_nop 0
	global_load_lds_dwordx4 v[74:75], off
	v_lshl_add_u64 v[74:75], v[234:235], 0, s[88:89]
	s_mov_b32 m0, s38
	s_nop 0
	global_load_lds_dwordx4 v[74:75], off
	s_waitcnt vmcnt(8)
	s_waitcnt lgkmcnt(0)
	s_barrier
	s_setprio 1
	v_mfma_f32_16x16x32_bf16 v[74:77], v[56:59], v[206:209], v[94:97]
	v_mfma_f32_16x16x32_bf16 v[94:97], v[60:63], v[210:213], v[74:77]
	v_mfma_f32_16x16x32_bf16 v[74:77], v[66:69], v[206:209], v[90:93]
	v_mfma_f32_16x16x32_bf16 v[44:47], v[56:59], v[214:217], v[44:47]
	v_mfma_f32_16x16x32_bf16 v[40:43], v[66:69], v[214:217], v[40:43]
	v_mfma_f32_16x16x32_bf16 v[28:31], v[56:59], v[222:225], v[28:31]
	v_mfma_f32_16x16x32_bf16 v[24:27], v[66:69], v[222:225], v[24:27]
	v_mfma_f32_16x16x32_bf16 v[12:15], v[56:59], v[244:247], v[12:15]
	v_mfma_f32_16x16x32_bf16 v[8:11], v[66:69], v[244:247], v[8:11]
	v_mfma_f32_16x16x32_bf16 v[90:93], v[70:73], v[210:213], v[74:77]
	v_mfma_f32_16x16x32_bf16 v[44:47], v[60:63], v[218:221], v[44:47]
	v_mfma_f32_16x16x32_bf16 v[40:43], v[70:73], v[218:221], v[40:43]
	v_mfma_f32_16x16x32_bf16 v[28:31], v[60:63], v[240:243], v[28:31]
	v_mfma_f32_16x16x32_bf16 v[24:27], v[70:73], v[240:243], v[24:27]
	v_mfma_f32_16x16x32_bf16 v[12:15], v[60:63], v[248:251], v[12:15]
	v_mfma_f32_16x16x32_bf16 v[8:11], v[70:73], v[248:251], v[8:11]
	v_mfma_f32_16x16x32_bf16 v[48:51], v[78:81], v[206:209], v[48:51]
	v_mfma_f32_16x16x32_bf16 v[74:77], v[82:85], v[210:213], v[48:51]
	v_mfma_f32_16x16x32_bf16 v[48:51], v[86:89], v[206:209], v[52:55]
	v_mfma_f32_16x16x32_bf16 v[36:39], v[78:81], v[214:217], v[36:39]
	v_mfma_f32_16x16x32_bf16 v[32:35], v[86:89], v[214:217], v[32:35]
	v_mfma_f32_16x16x32_bf16 v[20:23], v[78:81], v[222:225], v[20:23]
	v_mfma_f32_16x16x32_bf16 v[16:19], v[86:89], v[222:225], v[16:19]
	v_mfma_f32_16x16x32_bf16 v[4:7], v[78:81], v[244:247], v[4:7]
	v_mfma_f32_16x16x32_bf16 v[0:3], v[86:89], v[244:247], v[0:3]
	v_mfma_f32_16x16x32_bf16 v[70:73], v[202:205], v[210:213], v[48:51]
	v_mfma_f32_16x16x32_bf16 v[36:39], v[82:85], v[218:221], v[36:39]
	v_mfma_f32_16x16x32_bf16 v[32:35], v[202:205], v[218:221], v[32:35]
	v_mfma_f32_16x16x32_bf16 v[20:23], v[82:85], v[240:243], v[20:23]
	v_mfma_f32_16x16x32_bf16 v[16:19], v[202:205], v[240:243], v[16:19]
	v_mfma_f32_16x16x32_bf16 v[4:7], v[82:85], v[248:251], v[4:7]
	v_mfma_f32_16x16x32_bf16 v[0:3], v[202:205], v[248:251], v[0:3]
	s_setprio 0
	s_barrier
	s_add_u32 s4, s4, 0x100
	s_addc_u32 s5, s5, 0
	s_add_u32 s45, s45, 0x100
	s_addc_u32 s46, s46, 0
	s_cmp_ge_i32 s47, s36
	s_mov_b32 s24, s47
	s_cbranch_scc0 .LBB0_404

; #define PG8_STAGE(bufoff, gbase, voff) do { _Pragma("unroll") for (int _i = 0; _i < 2; ++_i) \
;         __builtin_amdgcn_global_load_lds((const unsigned*)((const char*)(gbase) + (voff)[_i]), (PG8_LAS unsigned*)(lds + (bufoff) + ldsw + _i * 8192), 16, 0, 0); } while (0)
; #define PG8_LDA(dst, b, h) do { _Pragma("unroll") for (int m = 0; m < 4; ++m) _Pragma("unroll") for (int k = 0; k < 2; ++k) dst[m][k] = *(const PG8_LAS bf16x8*)(lds + PG8_SA(b, h) + aoff + m * 2048 + k * 1024); } while (0)
; #define PG8_LDB(dst, b, h) do { _Pragma("unroll") for (int n = 0; n < 2; ++n) _Pragma("unroll") for (int k = 0; k < 2; ++k) dst[n][k] = *(const PG8_LAS bf16x8*)(lds + PG8_SB(b, h) + boff + n * 2048 + k * 1024); } while (0)
; #define PG8_MMA(ai, bj, At, Bt) do { __builtin_amdgcn_s_setprio(1); _Pragma("unroll") for (int m = 0; m < 4; ++m) _Pragma("unroll") for (int n = 0; n < 2; ++n) _Pragma("unroll") for (int k = 0; k < 2; ++k) \
;         acc[ai][bj][m][n] = __builtin_amdgcn_mfma_f32_16x16x32_bf16(Bt[n][k], At[m][k], acc[ai][bj][m][n], 0, 0, 0); __builtin_amdgcn_s_setprio(0); } while (0)
; #define PG8_WAIT_V(n) asm volatile("s_waitcnt vmcnt(" #n ")" ::: "memory")
; #define PG8_WAIT_L(n) asm volatile("s_waitcnt lgkmcnt(" #n ")" ::: "memory")
; #define PG8_BAR __builtin_amdgcn_s_barrier()
; #define PG8_SCHED __builtin_amdgcn_sched_barrier(0)
; template <class Epi, class Sched, bool ALIGN_EPI = false, bool SP2 = false>
; __device__ __forceinline__ void gemm_phase(PG8_LAS unsigned char* lds, const Gemm g, const Sched& S, const Epi& E) {
;     ...
;             PG8_LDB(B0, 0, 0); PG8_LDB(B1, 0, 1); PG8_SCHED; PG8_LDA(At, 0, 0); PG8_STAGE(PG8_SA(1, 1), a1 + hstepA, voffA);
;             PG8_WAIT_V(8); PG8_WAIT_L(0); PG8_BAR; PG8_MMA(0, 0, At, B0); PG8_MMA(0, 1, At, B1); PG8_BAR; PG8_SCHED;
;             PG8_LDA(At, 0, 1); PG8_STAGE(PG8_SB(0, 0), b2, voffB); PG8_STAGE(PG8_SB(0, 1), b2 + hstepB, voffB); PG8_STAGE(PG8_SA(0, 0), a2, voffA);
;             PG8_WAIT_V(8); PG8_WAIT_L(0); PG8_BAR; PG8_MMA(1, 0, At, B0); PG8_MMA(1, 1, At, B1); PG8_BAR; PG8_SCHED;
.LBB0_425:
	s_add_i32 s51, s28, 2
	s_add_u32 s29, s26, 0xfffc0080
	s_addc_u32 s30, s27, -1
	s_add_i32 s52, 0, 0x10000
	s_cmp_eq_u32 s46, s28
	s_cselect_b32 s31, s2, s30
	s_cselect_b32 s30, s5, s29
	v_add_u32_e32 v64, s52, v168
	s_cselect_b32 s29, s17, s50
	s_cselect_b32 s28, s19, s25
	s_add_i32 s54, 0, 0x14000
	ds_read_b128 v[142:145], v64
	ds_read_b128 v[146:149], v64 offset:1024
	ds_read_b128 v[150:153], v64 offset:2048
	ds_read_b128 v[154:157], v64 offset:3072
	v_add_u32_e32 v64, s54, v168
	ds_read_b128 v[158:161], v64
	ds_read_b128 v[162:165], v64 offset:1024
	ds_read_b128 v[170:173], v64 offset:2048
	ds_read_b128 v[174:177], v64 offset:3072
	v_lshl_add_u64 v[222:223], s[26:27], 0, v[138:139]
	s_add_i32 m0, s37, 0xc000
	ds_read_b128 v[178:181], v169
	ds_read_b128 v[182:185], v169 offset:1024
	ds_read_b128 v[186:189], v169 offset:2048
	ds_read_b128 v[202:205], v169 offset:3072
	ds_read_b128 v[206:209], v169 offset:4096
	ds_read_b128 v[210:213], v169 offset:5120
	ds_read_b128 v[214:217], v169 offset:6144
	ds_read_b128 v[218:221], v169 offset:7168
	global_load_lds_dwordx4 v[222:223], off
	v_lshl_add_u64 v[222:223], s[26:27], 0, v[140:141]
	s_add_i32 m0, s37, 0xe000
	s_nop 0
	global_load_lds_dwordx4 v[222:223], off
	s_waitcnt vmcnt(8)
	s_waitcnt lgkmcnt(0)
	s_barrier
	s_setprio 1
	v_mfma_f32_16x16x32_bf16 v[126:129], v[142:145], v[178:181], v[126:129]
	v_mfma_f32_16x16x32_bf16 v[122:125], v[150:153], v[178:181], v[122:125]
	v_mfma_f32_16x16x32_bf16 v[118:121], v[142:145], v[186:189], v[118:121]
	v_mfma_f32_16x16x32_bf16 v[114:117], v[150:153], v[186:189], v[114:117]
	v_mfma_f32_16x16x32_bf16 v[110:113], v[142:145], v[206:209], v[110:113]
	v_mfma_f32_16x16x32_bf16 v[106:109], v[150:153], v[206:209], v[106:109]
	v_mfma_f32_16x16x32_bf16 v[102:105], v[142:145], v[214:217], v[102:105]
	v_mfma_f32_16x16x32_bf16 v[98:101], v[150:153], v[214:217], v[98:101]
	v_mfma_f32_16x16x32_bf16 v[126:129], v[146:149], v[182:185], v[126:129]
	v_mfma_f32_16x16x32_bf16 v[122:125], v[154:157], v[182:185], v[122:125]
	v_mfma_f32_16x16x32_bf16 v[118:121], v[146:149], v[202:205], v[118:121]
	v_mfma_f32_16x16x32_bf16 v[114:117], v[154:157], v[202:205], v[114:117]
	v_mfma_f32_16x16x32_bf16 v[110:113], v[146:149], v[210:213], v[110:113]
	v_mfma_f32_16x16x32_bf16 v[106:109], v[154:157], v[210:213], v[106:109]
	v_mfma_f32_16x16x32_bf16 v[102:105], v[146:149], v[218:221], v[102:105]
	v_mfma_f32_16x16x32_bf16 v[98:101], v[154:157], v[218:221], v[98:101]
	v_mfma_f32_16x16x32_bf16 v[60:63], v[158:161], v[178:181], v[60:63]
	v_mfma_f32_16x16x32_bf16 v[56:59], v[170:173], v[178:181], v[56:59]
	v_mfma_f32_16x16x32_bf16 v[52:55], v[158:161], v[186:189], v[52:55]
	v_mfma_f32_16x16x32_bf16 v[48:51], v[170:173], v[186:189], v[48:51]
	v_mfma_f32_16x16x32_bf16 v[44:47], v[158:161], v[206:209], v[44:47]
	v_mfma_f32_16x16x32_bf16 v[40:43], v[170:173], v[206:209], v[40:43]
	v_mfma_f32_16x16x32_bf16 v[36:39], v[158:161], v[214:217], v[36:39]
	v_mfma_f32_16x16x32_bf16 v[32:35], v[170:173], v[214:217], v[32:35]
	v_mfma_f32_16x16x32_bf16 v[60:63], v[162:165], v[182:185], v[60:63]
	v_mfma_f32_16x16x32_bf16 v[56:59], v[174:177], v[182:185], v[56:59]
	v_mfma_f32_16x16x32_bf16 v[52:55], v[162:165], v[202:205], v[52:55]
	v_mfma_f32_16x16x32_bf16 v[48:51], v[174:177], v[202:205], v[48:51]
	v_mfma_f32_16x16x32_bf16 v[44:47], v[162:165], v[210:213], v[44:47]
	v_mfma_f32_16x16x32_bf16 v[40:43], v[174:177], v[210:213], v[40:43]
	v_mfma_f32_16x16x32_bf16 v[36:39], v[162:165], v[218:221], v[36:39]
	v_mfma_f32_16x16x32_bf16 v[32:35], v[174:177], v[218:221], v[32:35]
	s_setprio 0
	s_barrier
	s_add_i32 s52, s52, s34
	v_lshl_add_u64 v[222:223], s[28:29], 0, v[134:135]
	s_mov_b32 m0, s52
	ds_read_b128 v[178:181], v169 offset:16384
	ds_read_b128 v[182:185], v169 offset:17408
	ds_read_b128 v[186:189], v169 offset:18432
	ds_read_b128 v[202:205], v169 offset:19456
	ds_read_b128 v[206:209], v169 offset:20480
	ds_read_b128 v[210:213], v169 offset:21504
	ds_read_b128 v[214:217], v169 offset:22528
	ds_read_b128 v[218:221], v169 offset:23552
	global_load_lds_dwordx4 v[222:223], off
	s_add_i32 m0, s52, 0x2000
	s_add_u32 s52, s28, 0x40000
	v_lshl_add_u64 v[224:225], s[28:29], 0, v[130:131]
	s_addc_u32 s53, s29, 0
	s_add_i32 s54, s54, s34
	global_load_lds_dwordx4 v[224:225], off
	v_lshl_add_u64 v[226:227], s[52:53], 0, v[134:135]
	s_mov_b32 m0, s54
	v_lshl_add_u64 v[234:235], s[30:31], 0, v[132:133]
	global_load_lds_dwordx4 v[226:227], off
	v_lshl_add_u64 v[226:227], s[52:53], 0, v[130:131]
	s_add_i32 m0, s54, 0x2000
	s_nop 0
	global_load_lds_dwordx4 v[226:227], off
	v_lshl_add_u64 v[226:227], s[30:31], 0, v[136:137]
	s_mov_b32 m0, s37
	s_nop 0
	global_load_lds_dwordx4 v[226:227], off
	s_mov_b32 m0, s38
	s_nop 0
	global_load_lds_dwordx4 v[234:235], off
	s_waitcnt vmcnt(8)
	s_waitcnt lgkmcnt(0)
	s_barrier
; #define PG8_STAGE(bufoff, gbase, voff) do { _Pragma("unroll") for (int _i = 0; _i < 2; ++_i) \
;         __builtin_amdgcn_global_load_lds((const unsigned*)((const char*)(gbase) + (voff)[_i]), (PG8_LAS unsigned*)(lds + (bufoff) + ldsw + _i * 8192), 16, 0, 0); } while (0)
; #define PG8_LDA(dst, b, h) do { _Pragma("unroll") for (int m = 0; m < 4; ++m) _Pragma("unroll") for (int k = 0; k < 2; ++k) dst[m][k] = *(const PG8_LAS bf16x8*)(lds + PG8_SA(b, h) + aoff + m * 2048 + k * 1024); } while (0)
; #define PG8_LDB(dst, b, h) do { _Pragma("unroll") for (int n = 0; n < 2; ++n) _Pragma("unroll") for (int k = 0; k < 2; ++k) dst[n][k] = *(const PG8_LAS bf16x8*)(lds + PG8_SB(b, h) + boff + n * 2048 + k * 1024); } while (0)
; #define PG8_MMA(ai, bj, At, Bt) do { __builtin_amdgcn_s_setprio(1); _Pragma("unroll") for (int m = 0; m < 4; ++m) _Pragma("unroll") for (int n = 0; n < 2; ++n) _Pragma("unroll") for (int k = 0; k < 2; ++k) \
;         acc[ai][bj][m][n] = __builtin_amdgcn_mfma_f32_16x16x32_bf16(Bt[n][k], At[m][k], acc[ai][bj][m][n], 0, 0, 0); __builtin_amdgcn_s_setprio(0); } while (0)
; #define PG8_WAIT_V(n) asm volatile("s_waitcnt vmcnt(" #n ")" ::: "memory")
; #define PG8_WAIT_L(n) asm volatile("s_waitcnt lgkmcnt(" #n ")" ::: "memory")
; #define PG8_BAR __builtin_amdgcn_s_barrier()
; #define PG8_SCHED __builtin_amdgcn_sched_barrier(0)
; template <class Epi, class Sched, bool ALIGN_EPI = false, bool SP2 = false>
; __device__ __forceinline__ void gemm_phase(PG8_LAS unsigned char* lds, const Gemm g, const Sched& S, const Epi& E) {
;     ...
;             PG8_WAIT_V(8); PG8_WAIT_L(0); PG8_BAR; PG8_MMA(1, 0, At, B0); PG8_MMA(1, 1, At, B1); PG8_BAR; PG8_SCHED;
;             PG8_LDB(B0, 1, 0); PG8_LDB(B1, 1, 1); PG8_SCHED; PG8_LDA(At, 1, 0); PG8_STAGE(PG8_SA(0, 1), a2 + hstepA, voffA);
;             PG8_WAIT_V(8); PG8_WAIT_L(0); PG8_BAR; PG8_MMA(0, 0, At, B0); PG8_MMA(0, 1, At, B1); PG8_BAR; PG8_SCHED;
	s_setprio 1
	v_mfma_f32_16x16x32_bf16 v[94:97], v[142:145], v[178:181], v[94:97]
	v_mfma_f32_16x16x32_bf16 v[90:93], v[150:153], v[178:181], v[90:93]
	v_mfma_f32_16x16x32_bf16 v[86:89], v[142:145], v[186:189], v[86:89]
	v_mfma_f32_16x16x32_bf16 v[82:85], v[150:153], v[186:189], v[82:85]
	v_mfma_f32_16x16x32_bf16 v[78:81], v[142:145], v[206:209], v[78:81]
	v_mfma_f32_16x16x32_bf16 v[74:77], v[150:153], v[206:209], v[74:77]
	v_mfma_f32_16x16x32_bf16 v[70:73], v[142:145], v[214:217], v[70:73]
	v_mfma_f32_16x16x32_bf16 v[66:69], v[150:153], v[214:217], v[66:69]
	v_mfma_f32_16x16x32_bf16 v[94:97], v[146:149], v[182:185], v[94:97]
	v_mfma_f32_16x16x32_bf16 v[90:93], v[154:157], v[182:185], v[90:93]
	v_mfma_f32_16x16x32_bf16 v[86:89], v[146:149], v[202:205], v[86:89]
	v_mfma_f32_16x16x32_bf16 v[82:85], v[154:157], v[202:205], v[82:85]
	v_mfma_f32_16x16x32_bf16 v[78:81], v[146:149], v[210:213], v[78:81]
	v_mfma_f32_16x16x32_bf16 v[74:77], v[154:157], v[210:213], v[74:77]
	v_mfma_f32_16x16x32_bf16 v[70:73], v[146:149], v[218:221], v[70:73]
	v_mfma_f32_16x16x32_bf16 v[66:69], v[154:157], v[218:221], v[66:69]
	v_mfma_f32_16x16x32_bf16 v[28:31], v[158:161], v[178:181], v[28:31]
	v_mfma_f32_16x16x32_bf16 v[24:27], v[170:173], v[178:181], v[24:27]
	v_mfma_f32_16x16x32_bf16 v[20:23], v[158:161], v[186:189], v[20:23]
	v_mfma_f32_16x16x32_bf16 v[16:19], v[170:173], v[186:189], v[16:19]
	v_mfma_f32_16x16x32_bf16 v[12:15], v[158:161], v[206:209], v[12:15]
	v_mfma_f32_16x16x32_bf16 v[8:11], v[170:173], v[206:209], v[8:11]
	v_mfma_f32_16x16x32_bf16 v[4:7], v[158:161], v[214:217], v[4:7]
	v_mfma_f32_16x16x32_bf16 v[0:3], v[170:173], v[214:217], v[0:3]
	v_mfma_f32_16x16x32_bf16 v[28:31], v[162:165], v[182:185], v[28:31]
	v_mfma_f32_16x16x32_bf16 v[24:27], v[174:177], v[182:185], v[24:27]
	v_mfma_f32_16x16x32_bf16 v[20:23], v[162:165], v[202:205], v[20:23]
	v_mfma_f32_16x16x32_bf16 v[16:19], v[174:177], v[202:205], v[16:19]
	v_mfma_f32_16x16x32_bf16 v[12:15], v[162:165], v[210:213], v[12:15]
	v_mfma_f32_16x16x32_bf16 v[8:11], v[174:177], v[210:213], v[8:11]
	v_mfma_f32_16x16x32_bf16 v[4:7], v[162:165], v[218:221], v[4:7]
	v_mfma_f32_16x16x32_bf16 v[0:3], v[174:177], v[218:221], v[0:3]
	s_setprio 0
	s_barrier
	s_add_i32 s52, 0, 0x18000
	v_add_u32_e32 v64, s52, v168
	s_add_i32 s53, 0, 0x1c000
	ds_read_b128 v[142:145], v64
	ds_read_b128 v[146:149], v64 offset:1024
	ds_read_b128 v[150:153], v64 offset:2048
	ds_read_b128 v[154:157], v64 offset:3072
	v_add_u32_e32 v64, s53, v168
	ds_read_b128 v[158:161], v64
	ds_read_b128 v[162:165], v64 offset:1024
	ds_read_b128 v[170:173], v64 offset:2048
	ds_read_b128 v[174:177], v64 offset:3072
	s_add_u32 s30, s30, 0x40000
	s_addc_u32 s31, s31, 0
	s_mov_b32 m0, s39
	v_lshl_add_u64 v[240:241], s[30:31], 0, v[136:137]
	ds_read_b128 v[178:181], v169 offset:32768
	ds_read_b128 v[182:185], v169 offset:33792
	ds_read_b128 v[186:189], v169 offset:34816
	ds_read_b128 v[202:205], v169 offset:35840
	ds_read_b128 v[206:209], v169 offset:36864
	ds_read_b128 v[210:213], v169 offset:37888
	ds_read_b128 v[214:217], v169 offset:38912
	ds_read_b128 v[218:221], v169 offset:39936
	global_load_lds_dwordx4 v[240:241], off
	v_lshl_add_u64 v[240:241], s[30:31], 0, v[132:133]
	s_mov_b32 m0, s40
	s_nop 0
	global_load_lds_dwordx4 v[240:241], off
	s_waitcnt vmcnt(8)
	s_waitcnt lgkmcnt(0)
	s_barrier
	s_setprio 1
	v_mfma_f32_16x16x32_bf16 v[126:129], v[142:145], v[178:181], v[126:129]
	v_mfma_f32_16x16x32_bf16 v[122:125], v[150:153], v[178:181], v[122:125]
	v_mfma_f32_16x16x32_bf16 v[118:121], v[142:145], v[186:189], v[118:121]
	v_mfma_f32_16x16x32_bf16 v[114:117], v[150:153], v[186:189], v[114:117]
	v_mfma_f32_16x16x32_bf16 v[110:113], v[142:145], v[206:209], v[110:113]
	v_mfma_f32_16x16x32_bf16 v[106:109], v[150:153], v[206:209], v[106:109]
	v_mfma_f32_16x16x32_bf16 v[102:105], v[142:145], v[214:217], v[102:105]
	v_mfma_f32_16x16x32_bf16 v[98:101], v[150:153], v[214:217], v[98:101]
	v_mfma_f32_16x16x32_bf16 v[126:129], v[146:149], v[182:185], v[126:129]
	v_mfma_f32_16x16x32_bf16 v[122:125], v[154:157], v[182:185], v[122:125]
	v_mfma_f32_16x16x32_bf16 v[118:121], v[146:149], v[202:205], v[118:121]
	v_mfma_f32_16x16x32_bf16 v[114:117], v[154:157], v[202:205], v[114:117]
	v_mfma_f32_16x16x32_bf16 v[110:113], v[146:149], v[210:213], v[110:113]
	v_mfma_f32_16x16x32_bf16 v[106:109], v[154:157], v[210:213], v[106:109]
	v_mfma_f32_16x16x32_bf16 v[102:105], v[146:149], v[218:221], v[102:105]
	v_mfma_f32_16x16x32_bf16 v[98:101], v[154:157], v[218:221], v[98:101]
	v_mfma_f32_16x16x32_bf16 v[60:63], v[158:161], v[178:181], v[60:63]
	v_mfma_f32_16x16x32_bf16 v[56:59], v[170:173], v[178:181], v[56:59]
	v_mfma_f32_16x16x32_bf16 v[52:55], v[158:161], v[186:189], v[52:55]
	v_mfma_f32_16x16x32_bf16 v[48:51], v[170:173], v[186:189], v[48:51]
	v_mfma_f32_16x16x32_bf16 v[44:47], v[158:161], v[206:209], v[44:47]
	v_mfma_f32_16x16x32_bf16 v[40:43], v[170:173], v[206:209], v[40:43]
	v_mfma_f32_16x16x32_bf16 v[36:39], v[158:161], v[214:217], v[36:39]
	v_mfma_f32_16x16x32_bf16 v[32:35], v[170:173], v[214:217], v[32:35]
	v_mfma_f32_16x16x32_bf16 v[60:63], v[162:165], v[182:185], v[60:63]
	v_mfma_f32_16x16x32_bf16 v[56:59], v[174:177], v[182:185], v[56:59]
	v_mfma_f32_16x16x32_bf16 v[52:55], v[162:165], v[202:205], v[52:55]
	v_mfma_f32_16x16x32_bf16 v[48:51], v[174:177], v[202:205], v[48:51]
	v_mfma_f32_16x16x32_bf16 v[44:47], v[162:165], v[210:213], v[44:47]
	v_mfma_f32_16x16x32_bf16 v[40:43], v[174:177], v[210:213], v[40:43]
	v_mfma_f32_16x16x32_bf16 v[36:39], v[162:165], v[218:221], v[36:39]
	v_mfma_f32_16x16x32_bf16 v[32:35], v[174:177], v[218:221], v[32:35]
	s_setprio 0
	s_barrier
; #define PG8_STAGE(bufoff, gbase, voff) do { _Pragma("unroll") for (int _i = 0; _i < 2; ++_i) \
;         __builtin_amdgcn_global_load_lds((const unsigned*)((const char*)(gbase) + (voff)[_i]), (PG8_LAS unsigned*)(lds + (bufoff) + ldsw + _i * 8192), 16, 0, 0); } while (0)
; #define PG8_LDA(dst, b, h) do { _Pragma("unroll") for (int m = 0; m < 4; ++m) _Pragma("unroll") for (int k = 0; k < 2; ++k) dst[m][k] = *(const PG8_LAS bf16x8*)(lds + PG8_SA(b, h) + aoff + m * 2048 + k * 1024); } while (0)
; #define PG8_MMA(ai, bj, At, Bt) do { __builtin_amdgcn_s_setprio(1); _Pragma("unroll") for (int m = 0; m < 4; ++m) _Pragma("unroll") for (int n = 0; n < 2; ++n) _Pragma("unroll") for (int k = 0; k < 2; ++k) \
;         acc[ai][bj][m][n] = __builtin_amdgcn_mfma_f32_16x16x32_bf16(Bt[n][k], At[m][k], acc[ai][bj][m][n], 0, 0, 0); __builtin_amdgcn_s_setprio(0); } while (0)
; #define PG8_WAIT_V(n) asm volatile("s_waitcnt vmcnt(" #n ")" ::: "memory")
; #define PG8_WAIT_L(n) asm volatile("s_waitcnt lgkmcnt(" #n ")" ::: "memory")
; #define PG8_BAR __builtin_amdgcn_s_barrier()
; #define PG8_SCHED __builtin_amdgcn_sched_barrier(0)
; template <class Epi, class Sched, bool ALIGN_EPI = false, bool SP2 = false>
; __device__ __forceinline__ void gemm_phase(PG8_LAS unsigned char* lds, const Gemm g, const Sched& S, const Epi& E) {
;     ...
;             PG8_LDA(At, 1, 1); PG8_STAGE(PG8_SB(1, 0), b3, voffB); PG8_STAGE(PG8_SB(1, 1), b3 + hstepB, voffB); PG8_STAGE(PG8_SA(1, 0), a3, voffA);
;             PG8_WAIT_V(8); PG8_WAIT_L(0); PG8_BAR; PG8_MMA(1, 0, At, B0); PG8_MMA(1, 1, At, B1); PG8_BAR; PG8_SCHED;
	s_add_i32 s30, s52, s34
	v_lshl_add_u64 v[222:223], v[222:223], 0, s[88:89]
	s_mov_b32 m0, s30
	ds_read_b128 v[178:181], v169 offset:49152
	ds_read_b128 v[182:185], v169 offset:50176
	ds_read_b128 v[186:189], v169 offset:51200
	ds_read_b128 v[202:205], v169 offset:52224
	ds_read_b128 v[206:209], v169 offset:53248
	ds_read_b128 v[210:213], v169 offset:54272
	ds_read_b128 v[214:217], v169 offset:55296
	ds_read_b128 v[218:221], v169 offset:56320
	global_load_lds_dwordx4 v[222:223], off
	s_add_i32 m0, s30, 0x2000
	s_add_u32 s28, s28, 0x40080
	v_lshl_add_u64 v[222:223], v[224:225], 0, s[88:89]
	s_addc_u32 s29, s29, 0
	s_add_i32 s30, s53, s34
	global_load_lds_dwordx4 v[222:223], off
	v_lshl_add_u64 v[222:223], s[28:29], 0, v[134:135]
	s_mov_b32 m0, s30
	s_nop 0
	global_load_lds_dwordx4 v[222:223], off
	v_lshl_add_u64 v[222:223], s[28:29], 0, v[130:131]
	s_add_i32 m0, s30, 0x2000
	s_nop 0
	global_load_lds_dwordx4 v[222:223], off
	v_lshl_add_u64 v[222:223], v[226:227], 0, s[88:89]
	s_mov_b32 m0, s44
	s_nop 0
	global_load_lds_dwordx4 v[222:223], off
	v_lshl_add_u64 v[222:223], v[234:235], 0, s[88:89]
	s_mov_b32 m0, s45
	s_nop 0
	global_load_lds_dwordx4 v[222:223], off
	s_waitcnt vmcnt(8)
	s_waitcnt lgkmcnt(0)
	s_barrier
	s_setprio 1
	v_mfma_f32_16x16x32_bf16 v[94:97], v[142:145], v[178:181], v[94:97]
	v_mfma_f32_16x16x32_bf16 v[90:93], v[150:153], v[178:181], v[90:93]
	v_mfma_f32_16x16x32_bf16 v[86:89], v[142:145], v[186:189], v[86:89]
	v_mfma_f32_16x16x32_bf16 v[82:85], v[150:153], v[186:189], v[82:85]
	v_mfma_f32_16x16x32_bf16 v[78:81], v[142:145], v[206:209], v[78:81]
	v_mfma_f32_16x16x32_bf16 v[74:77], v[150:153], v[206:209], v[74:77]
	v_mfma_f32_16x16x32_bf16 v[70:73], v[142:145], v[214:217], v[70:73]
	v_mfma_f32_16x16x32_bf16 v[66:69], v[150:153], v[214:217], v[66:69]
	v_mfma_f32_16x16x32_bf16 v[94:97], v[146:149], v[182:185], v[94:97]
	v_mfma_f32_16x16x32_bf16 v[90:93], v[154:157], v[182:185], v[90:93]
	v_mfma_f32_16x16x32_bf16 v[86:89], v[146:149], v[202:205], v[86:89]
	v_mfma_f32_16x16x32_bf16 v[82:85], v[154:157], v[202:205], v[82:85]
	v_mfma_f32_16x16x32_bf16 v[78:81], v[146:149], v[210:213], v[78:81]
	v_mfma_f32_16x16x32_bf16 v[74:77], v[154:157], v[210:213], v[74:77]
	v_mfma_f32_16x16x32_bf16 v[70:73], v[146:149], v[218:221], v[70:73]
	v_mfma_f32_16x16x32_bf16 v[66:69], v[154:157], v[218:221], v[66:69]
	v_mfma_f32_16x16x32_bf16 v[28:31], v[158:161], v[178:181], v[28:31]
	v_mfma_f32_16x16x32_bf16 v[24:27], v[170:173], v[178:181], v[24:27]
	v_mfma_f32_16x16x32_bf16 v[20:23], v[158:161], v[186:189], v[20:23]
	v_mfma_f32_16x16x32_bf16 v[16:19], v[170:173], v[186:189], v[16:19]
	v_mfma_f32_16x16x32_bf16 v[12:15], v[158:161], v[206:209], v[12:15]
	v_mfma_f32_16x16x32_bf16 v[8:11], v[170:173], v[206:209], v[8:11]
	v_mfma_f32_16x16x32_bf16 v[4:7], v[158:161], v[214:217], v[4:7]
	v_mfma_f32_16x16x32_bf16 v[0:3], v[170:173], v[214:217], v[0:3]
	v_mfma_f32_16x16x32_bf16 v[28:31], v[162:165], v[182:185], v[28:31]
	v_mfma_f32_16x16x32_bf16 v[24:27], v[174:177], v[182:185], v[24:27]
	v_mfma_f32_16x16x32_bf16 v[20:23], v[162:165], v[202:205], v[20:23]
	v_mfma_f32_16x16x32_bf16 v[16:19], v[174:177], v[202:205], v[16:19]
	v_mfma_f32_16x16x32_bf16 v[12:15], v[162:165], v[210:213], v[12:15]
	v_mfma_f32_16x16x32_bf16 v[8:11], v[174:177], v[210:213], v[8:11]
	v_mfma_f32_16x16x32_bf16 v[4:7], v[162:165], v[218:221], v[4:7]
	v_mfma_f32_16x16x32_bf16 v[0:3], v[174:177], v[218:221], v[0:3]
	s_setprio 0
	s_barrier
	s_add_u32 s26, s26, 0x100
	s_addc_u32 s27, s27, 0
	s_add_u32 s25, s25, 0x100
	s_addc_u32 s50, s50, 0
	s_cmp_ge_i32 s51, s41
	s_mov_b32 s28, s51
	s_cbranch_scc0 .LBB0_425

; #define PG8_STAGE(bufoff, gbase, voff) do { _Pragma("unroll") for (int _i = 0; _i < 2; ++_i) \
;         __builtin_amdgcn_global_load_lds((const unsigned*)((const char*)(gbase) + (voff)[_i]), (PG8_LAS unsigned*)(lds + (bufoff) + ldsw + _i * 8192), 16, 0, 0); } while (0)
; #define PG8_LDA(dst, b, h) do { _Pragma("unroll") for (int m = 0; m < 4; ++m) _Pragma("unroll") for (int k = 0; k < 2; ++k) dst[m][k] = *(const PG8_LAS bf16x8*)(lds + PG8_SA(b, h) + aoff + m * 2048 + k * 1024); } while (0)
; #define PG8_LDB(dst, b, h) do { _Pragma("unroll") for (int n = 0; n < 2; ++n) _Pragma("unroll") for (int k = 0; k < 2; ++k) dst[n][k] = *(const PG8_LAS bf16x8*)(lds + PG8_SB(b, h) + boff + n * 2048 + k * 1024); } while (0)
; #define PG8_MMA(ai, bj, At, Bt) do { __builtin_amdgcn_s_setprio(1); _Pragma("unroll") for (int m = 0; m < 4; ++m) _Pragma("unroll") for (int n = 0; n < 2; ++n) _Pragma("unroll") for (int k = 0; k < 2; ++k) \
;         acc[ai][bj][m][n] = __builtin_amdgcn_mfma_f32_16x16x32_bf16(Bt[n][k], At[m][k], acc[ai][bj][m][n], 0, 0, 0); __builtin_amdgcn_s_setprio(0); } while (0)
; #define PG8_WAIT_V(n) asm volatile("s_waitcnt vmcnt(" #n ")" ::: "memory")
; #define PG8_WAIT_L(n) asm volatile("s_waitcnt lgkmcnt(" #n ")" ::: "memory")
; #define PG8_BAR __builtin_amdgcn_s_barrier()
; #define PG8_SCHED __builtin_amdgcn_sched_barrier(0)
; template <class Epi, class Sched, bool ALIGN_EPI = false, bool SP2 = false>
; __device__ __forceinline__ void gemm_phase(PG8_LAS unsigned char* lds, const Gemm g, const Sched& S, const Epi& E) {
;     ...
;             PG8_LDB(B0, 0, 0); PG8_LDB(B1, 0, 1); PG8_SCHED; PG8_LDA(At, 0, 0); PG8_STAGE(PG8_SA(1, 1), a1 + hstepA, voffA);
;             PG8_WAIT_V(8); PG8_WAIT_L(0); PG8_BAR; PG8_MMA(0, 0, At, B0); PG8_MMA(0, 1, At, B1); PG8_BAR; PG8_SCHED;
;             PG8_LDA(At, 0, 1); PG8_STAGE(PG8_SB(0, 0), b2, voffB); PG8_STAGE(PG8_SB(0, 1), b2 + hstepB, voffB); PG8_STAGE(PG8_SA(0, 0), a2, voffA);
;             PG8_WAIT_V(8); PG8_WAIT_L(0); PG8_BAR; PG8_MMA(1, 0, At, B0); PG8_MMA(1, 1, At, B1); PG8_BAR; PG8_SCHED;
.LBB0_654:
	s_add_i32 s49, s22, 2
	s_add_u32 s23, s4, 0xfffc0080
	s_addc_u32 s24, s5, -1
	s_add_i32 s50, 0, 0x10000
	s_cmp_eq_u32 s40, s22
	s_cselect_b32 s25, s15, s24
	s_cselect_b32 s24, s17, s23
	s_cselect_b32 s23, s45, s48
	s_cselect_b32 s22, s46, s47
	s_add_i32 s52, 0, 0x14000
	v_add_u32_e32 v142, s50, v218
	v_add_u32_e32 v158, s52, v218
	ds_read_b128 v[130:133], v142
	ds_read_b128 v[134:137], v142 offset:1024
	ds_read_b128 v[138:141], v142 offset:2048
	ds_read_b128 v[142:145], v142 offset:3072
	ds_read_b128 v[146:149], v158
	ds_read_b128 v[150:153], v158 offset:1024
	ds_read_b128 v[154:157], v158 offset:2048
	ds_read_b128 v[158:161], v158 offset:3072
	v_lshl_add_u64 v[220:221], s[4:5], 0, v[208:209]
	s_add_i32 m0, s29, 0xc000
	ds_read_b128 v[162:165], v219
	ds_read_b128 v[166:169], v219 offset:1024
	ds_read_b128 v[170:173], v219 offset:2048
	ds_read_b128 v[174:177], v219 offset:3072
	ds_read_b128 v[178:181], v219 offset:4096
	ds_read_b128 v[182:185], v219 offset:5120
	ds_read_b128 v[186:189], v219 offset:6144
	ds_read_b128 v[212:215], v219 offset:7168
	global_load_lds_dwordx4 v[220:221], off
	v_lshl_add_u64 v[220:221], s[4:5], 0, v[210:211]
	s_add_i32 m0, s29, 0xe000
	s_nop 0
	global_load_lds_dwordx4 v[220:221], off
	s_waitcnt vmcnt(8)
	s_waitcnt lgkmcnt(0)
	s_barrier
	s_setprio 1
	v_mfma_f32_16x16x32_bf16 v[122:125], v[130:133], v[162:165], v[122:125]
	v_mfma_f32_16x16x32_bf16 v[126:129], v[138:141], v[162:165], v[126:129]
	v_mfma_f32_16x16x32_bf16 v[110:113], v[130:133], v[170:173], v[110:113]
	v_mfma_f32_16x16x32_bf16 v[106:109], v[138:141], v[170:173], v[106:109]
	v_mfma_f32_16x16x32_bf16 v[94:97], v[130:133], v[178:181], v[94:97]
	v_mfma_f32_16x16x32_bf16 v[90:93], v[138:141], v[178:181], v[90:93]
	v_mfma_f32_16x16x32_bf16 v[78:81], v[130:133], v[186:189], v[78:81]
	v_mfma_f32_16x16x32_bf16 v[74:77], v[138:141], v[186:189], v[74:77]
	v_mfma_f32_16x16x32_bf16 v[122:125], v[134:137], v[166:169], v[122:125]
	v_mfma_f32_16x16x32_bf16 v[126:129], v[142:145], v[166:169], v[126:129]
	v_mfma_f32_16x16x32_bf16 v[110:113], v[134:137], v[174:177], v[110:113]
	v_mfma_f32_16x16x32_bf16 v[106:109], v[142:145], v[174:177], v[106:109]
	v_mfma_f32_16x16x32_bf16 v[94:97], v[134:137], v[182:185], v[94:97]
	v_mfma_f32_16x16x32_bf16 v[90:93], v[142:145], v[182:185], v[90:93]
	v_mfma_f32_16x16x32_bf16 v[78:81], v[134:137], v[212:215], v[78:81]
	v_mfma_f32_16x16x32_bf16 v[74:77], v[142:145], v[212:215], v[74:77]
	v_mfma_f32_16x16x32_bf16 v[118:121], v[146:149], v[162:165], v[118:121]
	v_mfma_f32_16x16x32_bf16 v[114:117], v[154:157], v[162:165], v[114:117]
	v_mfma_f32_16x16x32_bf16 v[102:105], v[146:149], v[170:173], v[102:105]
	v_mfma_f32_16x16x32_bf16 v[98:101], v[154:157], v[170:173], v[98:101]
	v_mfma_f32_16x16x32_bf16 v[86:89], v[146:149], v[178:181], v[86:89]
	v_mfma_f32_16x16x32_bf16 v[82:85], v[154:157], v[178:181], v[82:85]
	v_mfma_f32_16x16x32_bf16 v[70:73], v[146:149], v[186:189], v[70:73]
	v_mfma_f32_16x16x32_bf16 v[66:69], v[154:157], v[186:189], v[66:69]
	v_mfma_f32_16x16x32_bf16 v[118:121], v[150:153], v[166:169], v[118:121]
	v_mfma_f32_16x16x32_bf16 v[114:117], v[158:161], v[166:169], v[114:117]
	v_mfma_f32_16x16x32_bf16 v[102:105], v[150:153], v[174:177], v[102:105]
	v_mfma_f32_16x16x32_bf16 v[98:101], v[158:161], v[174:177], v[98:101]
	v_mfma_f32_16x16x32_bf16 v[86:89], v[150:153], v[182:185], v[86:89]
	v_mfma_f32_16x16x32_bf16 v[82:85], v[158:161], v[182:185], v[82:85]
	v_mfma_f32_16x16x32_bf16 v[70:73], v[150:153], v[212:215], v[70:73]
	v_mfma_f32_16x16x32_bf16 v[66:69], v[158:161], v[212:215], v[66:69]
	s_setprio 0
	s_barrier
	s_add_i32 s50, s50, s26
	v_lshl_add_u64 v[220:221], s[22:23], 0, v[64:65]
	s_mov_b32 m0, s50
	ds_read_b128 v[162:165], v219 offset:16384
	ds_read_b128 v[166:169], v219 offset:17408
	ds_read_b128 v[170:173], v219 offset:18432
	ds_read_b128 v[174:177], v219 offset:19456
	ds_read_b128 v[178:181], v219 offset:20480
	ds_read_b128 v[182:185], v219 offset:21504
	ds_read_b128 v[186:189], v219 offset:22528
	ds_read_b128 v[212:215], v219 offset:23552
	global_load_lds_dwordx4 v[220:221], off
	s_add_i32 m0, s50, 0x2000
	s_add_u32 s50, s22, 0x40000
	v_lshl_add_u64 v[222:223], s[22:23], 0, v[202:203]
	s_addc_u32 s51, s23, 0
	s_add_i32 s52, s52, s26
	global_load_lds_dwordx4 v[222:223], off
	v_lshl_add_u64 v[224:225], s[50:51], 0, v[64:65]
	s_mov_b32 m0, s52
	v_lshl_add_u64 v[226:227], s[24:25], 0, v[204:205]
	global_load_lds_dwordx4 v[224:225], off
	v_lshl_add_u64 v[224:225], s[50:51], 0, v[202:203]
	s_add_i32 m0, s52, 0x2000
	s_nop 0
	global_load_lds_dwordx4 v[224:225], off
	v_lshl_add_u64 v[224:225], s[24:25], 0, v[206:207]
	s_mov_b32 m0, s29
	s_nop 0
	global_load_lds_dwordx4 v[224:225], off
	s_mov_b32 m0, s30
	s_nop 0
	global_load_lds_dwordx4 v[226:227], off
	s_waitcnt vmcnt(8)
	s_waitcnt lgkmcnt(0)
	s_barrier
; #define PG8_STAGE(bufoff, gbase, voff) do { _Pragma("unroll") for (int _i = 0; _i < 2; ++_i) \
;         __builtin_amdgcn_global_load_lds((const unsigned*)((const char*)(gbase) + (voff)[_i]), (PG8_LAS unsigned*)(lds + (bufoff) + ldsw + _i * 8192), 16, 0, 0); } while (0)
; #define PG8_LDA(dst, b, h) do { _Pragma("unroll") for (int m = 0; m < 4; ++m) _Pragma("unroll") for (int k = 0; k < 2; ++k) dst[m][k] = *(const PG8_LAS bf16x8*)(lds + PG8_SA(b, h) + aoff + m * 2048 + k * 1024); } while (0)
; #define PG8_LDB(dst, b, h) do { _Pragma("unroll") for (int n = 0; n < 2; ++n) _Pragma("unroll") for (int k = 0; k < 2; ++k) dst[n][k] = *(const PG8_LAS bf16x8*)(lds + PG8_SB(b, h) + boff + n * 2048 + k * 1024); } while (0)
; #define PG8_MMA(ai, bj, At, Bt) do { __builtin_amdgcn_s_setprio(1); _Pragma("unroll") for (int m = 0; m < 4; ++m) _Pragma("unroll") for (int n = 0; n < 2; ++n) _Pragma("unroll") for (int k = 0; k < 2; ++k) \
;         acc[ai][bj][m][n] = __builtin_amdgcn_mfma_f32_16x16x32_bf16(Bt[n][k], At[m][k], acc[ai][bj][m][n], 0, 0, 0); __builtin_amdgcn_s_setprio(0); } while (0)
; #define PG8_WAIT_V(n) asm volatile("s_waitcnt vmcnt(" #n ")" ::: "memory")
; #define PG8_WAIT_L(n) asm volatile("s_waitcnt lgkmcnt(" #n ")" ::: "memory")
; #define PG8_BAR __builtin_amdgcn_s_barrier()
; #define PG8_SCHED __builtin_amdgcn_sched_barrier(0)
; template <class Epi, class Sched, bool ALIGN_EPI = false, bool SP2 = false>
; __device__ __forceinline__ void gemm_phase(PG8_LAS unsigned char* lds, const Gemm g, const Sched& S, const Epi& E) {
;     ...
;             PG8_WAIT_V(8); PG8_WAIT_L(0); PG8_BAR; PG8_MMA(1, 0, At, B0); PG8_MMA(1, 1, At, B1); PG8_BAR; PG8_SCHED;
;             PG8_LDB(B0, 1, 0); PG8_LDB(B1, 1, 1); PG8_SCHED; PG8_LDA(At, 1, 0); PG8_STAGE(PG8_SA(0, 1), a2 + hstepA, voffA);
;             PG8_WAIT_V(8); PG8_WAIT_L(0); PG8_BAR; PG8_MMA(0, 0, At, B0); PG8_MMA(0, 1, At, B1); PG8_BAR; PG8_SCHED;
	s_setprio 1
	v_mfma_f32_16x16x32_bf16 v[60:63], v[130:133], v[162:165], v[60:63]
	v_mfma_f32_16x16x32_bf16 v[56:59], v[138:141], v[162:165], v[56:59]
	v_mfma_f32_16x16x32_bf16 v[44:47], v[130:133], v[170:173], v[44:47]
	v_mfma_f32_16x16x32_bf16 v[40:43], v[138:141], v[170:173], v[40:43]
	v_mfma_f32_16x16x32_bf16 v[28:31], v[130:133], v[178:181], v[28:31]
	v_mfma_f32_16x16x32_bf16 v[24:27], v[138:141], v[178:181], v[24:27]
	v_mfma_f32_16x16x32_bf16 v[12:15], v[130:133], v[186:189], v[12:15]
	v_mfma_f32_16x16x32_bf16 v[8:11], v[138:141], v[186:189], v[8:11]
	v_mfma_f32_16x16x32_bf16 v[60:63], v[134:137], v[166:169], v[60:63]
	v_mfma_f32_16x16x32_bf16 v[56:59], v[142:145], v[166:169], v[56:59]
	v_mfma_f32_16x16x32_bf16 v[44:47], v[134:137], v[174:177], v[44:47]
	v_mfma_f32_16x16x32_bf16 v[40:43], v[142:145], v[174:177], v[40:43]
	v_mfma_f32_16x16x32_bf16 v[28:31], v[134:137], v[182:185], v[28:31]
	v_mfma_f32_16x16x32_bf16 v[24:27], v[142:145], v[182:185], v[24:27]
	v_mfma_f32_16x16x32_bf16 v[12:15], v[134:137], v[212:215], v[12:15]
	v_mfma_f32_16x16x32_bf16 v[8:11], v[142:145], v[212:215], v[8:11]
	v_mfma_f32_16x16x32_bf16 v[52:55], v[146:149], v[162:165], v[52:55]
	v_mfma_f32_16x16x32_bf16 v[48:51], v[154:157], v[162:165], v[48:51]
	v_mfma_f32_16x16x32_bf16 v[36:39], v[146:149], v[170:173], v[36:39]
	v_mfma_f32_16x16x32_bf16 v[32:35], v[154:157], v[170:173], v[32:35]
	v_mfma_f32_16x16x32_bf16 v[20:23], v[146:149], v[178:181], v[20:23]
	v_mfma_f32_16x16x32_bf16 v[16:19], v[154:157], v[178:181], v[16:19]
	v_mfma_f32_16x16x32_bf16 v[4:7], v[146:149], v[186:189], v[4:7]
	v_mfma_f32_16x16x32_bf16 v[0:3], v[154:157], v[186:189], v[0:3]
	v_mfma_f32_16x16x32_bf16 v[52:55], v[150:153], v[166:169], v[52:55]
	v_mfma_f32_16x16x32_bf16 v[48:51], v[158:161], v[166:169], v[48:51]
	v_mfma_f32_16x16x32_bf16 v[36:39], v[150:153], v[174:177], v[36:39]
	v_mfma_f32_16x16x32_bf16 v[32:35], v[158:161], v[174:177], v[32:35]
	v_mfma_f32_16x16x32_bf16 v[20:23], v[150:153], v[182:185], v[20:23]
	v_mfma_f32_16x16x32_bf16 v[16:19], v[158:161], v[182:185], v[16:19]
	v_mfma_f32_16x16x32_bf16 v[4:7], v[150:153], v[212:215], v[4:7]
	v_mfma_f32_16x16x32_bf16 v[0:3], v[158:161], v[212:215], v[0:3]
	s_setprio 0
	s_barrier
	s_add_i32 s50, 0, 0x18000
	s_add_i32 s51, 0, 0x1c000
	v_add_u32_e32 v142, s50, v218
	v_add_u32_e32 v158, s51, v218
	ds_read_b128 v[130:133], v142
	ds_read_b128 v[134:137], v142 offset:1024
	ds_read_b128 v[138:141], v142 offset:2048
	ds_read_b128 v[142:145], v142 offset:3072
	ds_read_b128 v[146:149], v158
	ds_read_b128 v[150:153], v158 offset:1024
	ds_read_b128 v[154:157], v158 offset:2048
	ds_read_b128 v[158:161], v158 offset:3072
	s_add_u32 s24, s24, 0x40000
	s_addc_u32 s25, s25, 0
	s_mov_b32 m0, s31
	v_lshl_add_u64 v[234:235], s[24:25], 0, v[206:207]
	ds_read_b128 v[162:165], v219 offset:32768
	ds_read_b128 v[166:169], v219 offset:33792
	ds_read_b128 v[170:173], v219 offset:34816
	ds_read_b128 v[174:177], v219 offset:35840
	ds_read_b128 v[178:181], v219 offset:36864
	ds_read_b128 v[182:185], v219 offset:37888
	ds_read_b128 v[186:189], v219 offset:38912
	ds_read_b128 v[212:215], v219 offset:39936
	global_load_lds_dwordx4 v[234:235], off
	v_lshl_add_u64 v[234:235], s[24:25], 0, v[204:205]
	s_mov_b32 m0, s34
	s_nop 0
	global_load_lds_dwordx4 v[234:235], off
	s_waitcnt vmcnt(8)
	s_waitcnt lgkmcnt(0)
	s_barrier
	s_setprio 1
	v_mfma_f32_16x16x32_bf16 v[122:125], v[130:133], v[162:165], v[122:125]
	v_mfma_f32_16x16x32_bf16 v[126:129], v[138:141], v[162:165], v[126:129]
	v_mfma_f32_16x16x32_bf16 v[110:113], v[130:133], v[170:173], v[110:113]
	v_mfma_f32_16x16x32_bf16 v[106:109], v[138:141], v[170:173], v[106:109]
	v_mfma_f32_16x16x32_bf16 v[94:97], v[130:133], v[178:181], v[94:97]
	v_mfma_f32_16x16x32_bf16 v[90:93], v[138:141], v[178:181], v[90:93]
	v_mfma_f32_16x16x32_bf16 v[78:81], v[130:133], v[186:189], v[78:81]
	v_mfma_f32_16x16x32_bf16 v[74:77], v[138:141], v[186:189], v[74:77]
	v_mfma_f32_16x16x32_bf16 v[122:125], v[134:137], v[166:169], v[122:125]
	v_mfma_f32_16x16x32_bf16 v[126:129], v[142:145], v[166:169], v[126:129]
	v_mfma_f32_16x16x32_bf16 v[110:113], v[134:137], v[174:177], v[110:113]
	v_mfma_f32_16x16x32_bf16 v[106:109], v[142:145], v[174:177], v[106:109]
	v_mfma_f32_16x16x32_bf16 v[94:97], v[134:137], v[182:185], v[94:97]
	v_mfma_f32_16x16x32_bf16 v[90:93], v[142:145], v[182:185], v[90:93]
	v_mfma_f32_16x16x32_bf16 v[78:81], v[134:137], v[212:215], v[78:81]
	v_mfma_f32_16x16x32_bf16 v[74:77], v[142:145], v[212:215], v[74:77]
	v_mfma_f32_16x16x32_bf16 v[118:121], v[146:149], v[162:165], v[118:121]
	v_mfma_f32_16x16x32_bf16 v[114:117], v[154:157], v[162:165], v[114:117]
	v_mfma_f32_16x16x32_bf16 v[102:105], v[146:149], v[170:173], v[102:105]
	v_mfma_f32_16x16x32_bf16 v[98:101], v[154:157], v[170:173], v[98:101]
	v_mfma_f32_16x16x32_bf16 v[86:89], v[146:149], v[178:181], v[86:89]
	v_mfma_f32_16x16x32_bf16 v[82:85], v[154:157], v[178:181], v[82:85]
	v_mfma_f32_16x16x32_bf16 v[70:73], v[146:149], v[186:189], v[70:73]
	v_mfma_f32_16x16x32_bf16 v[66:69], v[154:157], v[186:189], v[66:69]
	v_mfma_f32_16x16x32_bf16 v[118:121], v[150:153], v[166:169], v[118:121]
	v_mfma_f32_16x16x32_bf16 v[114:117], v[158:161], v[166:169], v[114:117]
	v_mfma_f32_16x16x32_bf16 v[102:105], v[150:153], v[174:177], v[102:105]
	v_mfma_f32_16x16x32_bf16 v[98:101], v[158:161], v[174:177], v[98:101]
	v_mfma_f32_16x16x32_bf16 v[86:89], v[150:153], v[182:185], v[86:89]
	v_mfma_f32_16x16x32_bf16 v[82:85], v[158:161], v[182:185], v[82:85]
	v_mfma_f32_16x16x32_bf16 v[70:73], v[150:153], v[212:215], v[70:73]
	v_mfma_f32_16x16x32_bf16 v[66:69], v[158:161], v[212:215], v[66:69]
	s_setprio 0
	s_barrier
; #define PG8_STAGE(bufoff, gbase, voff) do { _Pragma("unroll") for (int _i = 0; _i < 2; ++_i) \
;         __builtin_amdgcn_global_load_lds((const unsigned*)((const char*)(gbase) + (voff)[_i]), (PG8_LAS unsigned*)(lds + (bufoff) + ldsw + _i * 8192), 16, 0, 0); } while (0)
; #define PG8_LDA(dst, b, h) do { _Pragma("unroll") for (int m = 0; m < 4; ++m) _Pragma("unroll") for (int k = 0; k < 2; ++k) dst[m][k] = *(const PG8_LAS bf16x8*)(lds + PG8_SA(b, h) + aoff + m * 2048 + k * 1024); } while (0)
; #define PG8_MMA(ai, bj, At, Bt) do { __builtin_amdgcn_s_setprio(1); _Pragma("unroll") for (int m = 0; m < 4; ++m) _Pragma("unroll") for (int n = 0; n < 2; ++n) _Pragma("unroll") for (int k = 0; k < 2; ++k) \
;         acc[ai][bj][m][n] = __builtin_amdgcn_mfma_f32_16x16x32_bf16(Bt[n][k], At[m][k], acc[ai][bj][m][n], 0, 0, 0); __builtin_amdgcn_s_setprio(0); } while (0)
; #define PG8_WAIT_V(n) asm volatile("s_waitcnt vmcnt(" #n ")" ::: "memory")
; #define PG8_WAIT_L(n) asm volatile("s_waitcnt lgkmcnt(" #n ")" ::: "memory")
; #define PG8_BAR __builtin_amdgcn_s_barrier()
; #define PG8_SCHED __builtin_amdgcn_sched_barrier(0)
; template <class Epi, class Sched, bool ALIGN_EPI = false, bool SP2 = false>
; __device__ __forceinline__ void gemm_phase(PG8_LAS unsigned char* lds, const Gemm g, const Sched& S, const Epi& E) {
;     ...
;             PG8_LDA(At, 1, 1); PG8_STAGE(PG8_SB(1, 0), b3, voffB); PG8_STAGE(PG8_SB(1, 1), b3 + hstepB, voffB); PG8_STAGE(PG8_SA(1, 0), a3, voffA);
;             PG8_WAIT_V(8); PG8_WAIT_L(0); PG8_BAR; PG8_MMA(1, 0, At, B0); PG8_MMA(1, 1, At, B1); PG8_BAR; PG8_SCHED;
	s_add_i32 s24, s50, s26
	v_lshl_add_u64 v[220:221], v[220:221], 0, s[88:89]
	s_mov_b32 m0, s24
	ds_read_b128 v[162:165], v219 offset:49152
	ds_read_b128 v[166:169], v219 offset:50176
	ds_read_b128 v[170:173], v219 offset:51200
	ds_read_b128 v[174:177], v219 offset:52224
	ds_read_b128 v[178:181], v219 offset:53248
	ds_read_b128 v[182:185], v219 offset:54272
	ds_read_b128 v[186:189], v219 offset:55296
	ds_read_b128 v[212:215], v219 offset:56320
	global_load_lds_dwordx4 v[220:221], off
	s_add_i32 m0, s24, 0x2000
	s_add_u32 s22, s22, 0x40080
	v_lshl_add_u64 v[220:221], v[222:223], 0, s[88:89]
	s_addc_u32 s23, s23, 0
	s_add_i32 s24, s51, s26
	global_load_lds_dwordx4 v[220:221], off
	v_lshl_add_u64 v[220:221], s[22:23], 0, v[64:65]
	s_mov_b32 m0, s24
	s_nop 0
	global_load_lds_dwordx4 v[220:221], off
	v_lshl_add_u64 v[220:221], s[22:23], 0, v[202:203]
	s_add_i32 m0, s24, 0x2000
	s_nop 0
	global_load_lds_dwordx4 v[220:221], off
	v_lshl_add_u64 v[220:221], v[224:225], 0, s[88:89]
	s_mov_b32 m0, s38
	s_nop 0
	global_load_lds_dwordx4 v[220:221], off
	v_lshl_add_u64 v[220:221], v[226:227], 0, s[88:89]
	s_mov_b32 m0, s39
	s_nop 0
	global_load_lds_dwordx4 v[220:221], off
	s_waitcnt vmcnt(8)
	s_waitcnt lgkmcnt(0)
	s_barrier
	s_setprio 1
	v_mfma_f32_16x16x32_bf16 v[60:63], v[130:133], v[162:165], v[60:63]
	v_mfma_f32_16x16x32_bf16 v[56:59], v[138:141], v[162:165], v[56:59]
	v_mfma_f32_16x16x32_bf16 v[44:47], v[130:133], v[170:173], v[44:47]
	v_mfma_f32_16x16x32_bf16 v[40:43], v[138:141], v[170:173], v[40:43]
	v_mfma_f32_16x16x32_bf16 v[28:31], v[130:133], v[178:181], v[28:31]
	v_mfma_f32_16x16x32_bf16 v[24:27], v[138:141], v[178:181], v[24:27]
	v_mfma_f32_16x16x32_bf16 v[12:15], v[130:133], v[186:189], v[12:15]
	v_mfma_f32_16x16x32_bf16 v[8:11], v[138:141], v[186:189], v[8:11]
	v_mfma_f32_16x16x32_bf16 v[60:63], v[134:137], v[166:169], v[60:63]
	v_mfma_f32_16x16x32_bf16 v[56:59], v[142:145], v[166:169], v[56:59]
	v_mfma_f32_16x16x32_bf16 v[44:47], v[134:137], v[174:177], v[44:47]
	v_mfma_f32_16x16x32_bf16 v[40:43], v[142:145], v[174:177], v[40:43]
	v_mfma_f32_16x16x32_bf16 v[28:31], v[134:137], v[182:185], v[28:31]
	v_mfma_f32_16x16x32_bf16 v[24:27], v[142:145], v[182:185], v[24:27]
	v_mfma_f32_16x16x32_bf16 v[12:15], v[134:137], v[212:215], v[12:15]
	v_mfma_f32_16x16x32_bf16 v[8:11], v[142:145], v[212:215], v[8:11]
	v_mfma_f32_16x16x32_bf16 v[52:55], v[146:149], v[162:165], v[52:55]
	v_mfma_f32_16x16x32_bf16 v[48:51], v[154:157], v[162:165], v[48:51]
	v_mfma_f32_16x16x32_bf16 v[36:39], v[146:149], v[170:173], v[36:39]
	v_mfma_f32_16x16x32_bf16 v[32:35], v[154:157], v[170:173], v[32:35]
	v_mfma_f32_16x16x32_bf16 v[20:23], v[146:149], v[178:181], v[20:23]
	v_mfma_f32_16x16x32_bf16 v[16:19], v[154:157], v[178:181], v[16:19]
	v_mfma_f32_16x16x32_bf16 v[4:7], v[146:149], v[186:189], v[4:7]
	v_mfma_f32_16x16x32_bf16 v[0:3], v[154:157], v[186:189], v[0:3]
	v_mfma_f32_16x16x32_bf16 v[52:55], v[150:153], v[166:169], v[52:55]
	v_mfma_f32_16x16x32_bf16 v[48:51], v[158:161], v[166:169], v[48:51]
	v_mfma_f32_16x16x32_bf16 v[36:39], v[150:153], v[174:177], v[36:39]
	v_mfma_f32_16x16x32_bf16 v[32:35], v[158:161], v[174:177], v[32:35]
	v_mfma_f32_16x16x32_bf16 v[20:23], v[150:153], v[182:185], v[20:23]
	v_mfma_f32_16x16x32_bf16 v[16:19], v[158:161], v[182:185], v[16:19]
	v_mfma_f32_16x16x32_bf16 v[4:7], v[150:153], v[212:215], v[4:7]
	v_mfma_f32_16x16x32_bf16 v[0:3], v[158:161], v[212:215], v[0:3]
	s_setprio 0
	s_barrier
	s_add_u32 s4, s4, 0x100
	s_addc_u32 s5, s5, 0
	s_add_u32 s47, s47, 0x100
	s_addc_u32 s48, s48, 0
	s_cmp_ge_i32 s49, s36
	s_mov_b32 s22, s49
	s_cbranch_scc0 .LBB0_654

; #define PG8_STAGE(bufoff, gbase, voff) do { _Pragma("unroll") for (int _i = 0; _i < 2; ++_i) \
;         __builtin_amdgcn_global_load_lds((const unsigned*)((const char*)(gbase) + (voff)[_i]), (PG8_LAS unsigned*)(lds + (bufoff) + ldsw + _i * 8192), 16, 0, 0); } while (0)
; #define PG8_LDA(dst, b, h) do { _Pragma("unroll") for (int m = 0; m < 4; ++m) _Pragma("unroll") for (int k = 0; k < 2; ++k) dst[m][k] = *(const PG8_LAS bf16x8*)(lds + PG8_SA(b, h) + aoff + m * 2048 + k * 1024); } while (0)
; #define PG8_LDB(dst, b, h) do { _Pragma("unroll") for (int n = 0; n < 2; ++n) _Pragma("unroll") for (int k = 0; k < 2; ++k) dst[n][k] = *(const PG8_LAS bf16x8*)(lds + PG8_SB(b, h) + boff + n * 2048 + k * 1024); } while (0)
; #define PG8_MMA(ai, bj, At, Bt) do { __builtin_amdgcn_s_setprio(1); _Pragma("unroll") for (int m = 0; m < 4; ++m) _Pragma("unroll") for (int n = 0; n < 2; ++n) _Pragma("unroll") for (int k = 0; k < 2; ++k) \
;         acc[ai][bj][m][n] = __builtin_amdgcn_mfma_f32_16x16x32_bf16(Bt[n][k], At[m][k], acc[ai][bj][m][n], 0, 0, 0); __builtin_amdgcn_s_setprio(0); } while (0)
; #define PG8_WAIT_V(n) asm volatile("s_waitcnt vmcnt(" #n ")" ::: "memory")
; #define PG8_WAIT_L(n) asm volatile("s_waitcnt lgkmcnt(" #n ")" ::: "memory")
; #define PG8_BAR __builtin_amdgcn_s_barrier()
; #define PG8_SCHED __builtin_amdgcn_sched_barrier(0)
; template <class Epi, class Sched, bool ALIGN_EPI = false, bool SP2 = false>
; __device__ __forceinline__ void gemm_phase(PG8_LAS unsigned char* lds, const Gemm g, const Sched& S, const Epi& E) {
;     ...
;             PG8_LDB(B0, 0, 0); PG8_LDB(B1, 0, 1); PG8_SCHED; PG8_LDA(At, 0, 0); PG8_STAGE(PG8_SA(1, 1), a1 + hstepA, voffA);
;             PG8_WAIT_V(8); PG8_WAIT_L(0); PG8_BAR; PG8_MMA(0, 0, At, B0); PG8_MMA(0, 1, At, B1); PG8_BAR; PG8_SCHED;
;             PG8_LDA(At, 0, 1); PG8_STAGE(PG8_SB(0, 0), b2, voffB); PG8_STAGE(PG8_SB(0, 1), b2 + hstepB, voffB); PG8_STAGE(PG8_SA(0, 0), a2, voffA);
;             PG8_WAIT_V(8); PG8_WAIT_L(0); PG8_BAR; PG8_MMA(1, 0, At, B0); PG8_MMA(1, 1, At, B1); PG8_BAR; PG8_SCHED;
.LBB0_746:
	s_add_i32 s31, s8, 2
	s_add_u32 s9, s4, 0xfffc0080
	s_addc_u32 s10, s5, -1
	s_add_i32 s34, 0, 0x10000
	s_cmp_eq_u32 s47, s8
	s_cselect_b32 s11, s19, s10
	s_cselect_b32 s10, s21, s9
	s_cselect_b32 s9, s27, s30
	s_cselect_b32 s8, s28, s29
	s_add_i32 s50, 0, 0x14000
	v_add_u32_e32 v102, s34, v177
	v_add_u32_e32 v126, s50, v177
	ds_read_b128 v[90:93], v102
	ds_read_b128 v[94:97], v102 offset:1024
	ds_read_b128 v[98:101], v102 offset:2048
	ds_read_b128 v[102:105], v102 offset:3072
	ds_read_b128 v[106:109], v126
	ds_read_b128 v[114:117], v126 offset:1024
	ds_read_b128 v[118:121], v126 offset:2048
	ds_read_b128 v[126:129], v126 offset:3072
	v_lshl_add_u64 v[226:227], s[4:5], 0, v[168:169]
	s_add_i32 m0, s38, 0xc000
	ds_read_b128 v[186:189], v179
	ds_read_b128 v[202:205], v179 offset:1024
	ds_read_b128 v[206:209], v179 offset:2048
	ds_read_b128 v[210:213], v179 offset:3072
	ds_read_b128 v[214:217], v179 offset:4096
	ds_read_b128 v[218:221], v179 offset:5120
	ds_read_b128 v[222:225], v179 offset:6144
	ds_read_b128 v[240:243], v179 offset:7168
	global_load_lds_dwordx4 v[226:227], off
	v_lshl_add_u64 v[226:227], s[4:5], 0, v[170:171]
	s_add_i32 m0, s38, 0xe000
	s_nop 0
	global_load_lds_dwordx4 v[226:227], off
	s_waitcnt vmcnt(8)
	s_waitcnt lgkmcnt(0)
	s_barrier
	s_setprio 1
	v_mfma_f32_16x16x32_bf16 v[158:161], v[90:93], v[186:189], v[158:161]
	v_mfma_f32_16x16x32_bf16 v[154:157], v[98:101], v[186:189], v[154:157]
	v_mfma_f32_16x16x32_bf16 v[142:145], v[90:93], v[206:209], v[142:145]
	v_mfma_f32_16x16x32_bf16 v[138:141], v[98:101], v[206:209], v[138:141]
	v_mfma_f32_16x16x32_bf16 v[122:125], v[90:93], v[214:217], v[122:125]
	v_mfma_f32_16x16x32_bf16 v[110:113], v[98:101], v[214:217], v[110:113]
	v_mfma_f32_16x16x32_bf16 v[78:81], v[90:93], v[222:225], v[78:81]
	v_mfma_f32_16x16x32_bf16 v[74:77], v[98:101], v[222:225], v[74:77]
	v_mfma_f32_16x16x32_bf16 v[158:161], v[94:97], v[202:205], v[158:161]
	v_mfma_f32_16x16x32_bf16 v[154:157], v[102:105], v[202:205], v[154:157]
	v_mfma_f32_16x16x32_bf16 v[142:145], v[94:97], v[210:213], v[142:145]
	v_mfma_f32_16x16x32_bf16 v[138:141], v[102:105], v[210:213], v[138:141]
	v_mfma_f32_16x16x32_bf16 v[122:125], v[94:97], v[218:221], v[122:125]
	v_mfma_f32_16x16x32_bf16 v[110:113], v[102:105], v[218:221], v[110:113]
	v_mfma_f32_16x16x32_bf16 v[78:81], v[94:97], v[240:243], v[78:81]
	v_mfma_f32_16x16x32_bf16 v[74:77], v[102:105], v[240:243], v[74:77]
	v_mfma_f32_16x16x32_bf16 v[150:153], v[106:109], v[186:189], v[150:153]
	v_mfma_f32_16x16x32_bf16 v[146:149], v[118:121], v[186:189], v[146:149]
	v_mfma_f32_16x16x32_bf16 v[134:137], v[106:109], v[206:209], v[134:137]
	v_mfma_f32_16x16x32_bf16 v[130:133], v[118:121], v[206:209], v[130:133]
	v_mfma_f32_16x16x32_bf16 v[86:89], v[106:109], v[214:217], v[86:89]
	v_mfma_f32_16x16x32_bf16 v[82:85], v[118:121], v[214:217], v[82:85]
	v_mfma_f32_16x16x32_bf16 v[70:73], v[106:109], v[222:225], v[70:73]
	v_mfma_f32_16x16x32_bf16 v[66:69], v[118:121], v[222:225], v[66:69]
	v_mfma_f32_16x16x32_bf16 v[150:153], v[114:117], v[202:205], v[150:153]
	v_mfma_f32_16x16x32_bf16 v[146:149], v[126:129], v[202:205], v[146:149]
	v_mfma_f32_16x16x32_bf16 v[134:137], v[114:117], v[210:213], v[134:137]
	v_mfma_f32_16x16x32_bf16 v[130:133], v[126:129], v[210:213], v[130:133]
	v_mfma_f32_16x16x32_bf16 v[86:89], v[114:117], v[218:221], v[86:89]
	v_mfma_f32_16x16x32_bf16 v[82:85], v[126:129], v[218:221], v[82:85]
	v_mfma_f32_16x16x32_bf16 v[70:73], v[114:117], v[240:243], v[70:73]
	v_mfma_f32_16x16x32_bf16 v[66:69], v[126:129], v[240:243], v[66:69]
	s_setprio 0
	s_barrier
	s_add_i32 s34, s34, s36
	v_lshl_add_u64 v[226:227], s[8:9], 0, v[64:65]
	s_mov_b32 m0, s34
	ds_read_b128 v[186:189], v179 offset:16384
	ds_read_b128 v[202:205], v179 offset:17408
	ds_read_b128 v[206:209], v179 offset:18432
	ds_read_b128 v[210:213], v179 offset:19456
	ds_read_b128 v[214:217], v179 offset:20480
	ds_read_b128 v[218:221], v179 offset:21504
	ds_read_b128 v[222:225], v179 offset:22528
	ds_read_b128 v[240:243], v179 offset:23552
	global_load_lds_dwordx4 v[226:227], off
	s_add_i32 m0, s34, 0x2000
	s_add_u32 s34, s8, 0x40000
	v_lshl_add_u64 v[244:245], s[8:9], 0, v[162:163]
	s_addc_u32 s35, s9, 0
	s_add_i32 s50, s50, s36
	global_load_lds_dwordx4 v[244:245], off
	v_lshl_add_u64 v[246:247], s[34:35], 0, v[64:65]
	s_mov_b32 m0, s50
	v_lshl_add_u64 v[248:249], s[10:11], 0, v[164:165]
	global_load_lds_dwordx4 v[246:247], off
	v_lshl_add_u64 v[246:247], s[34:35], 0, v[162:163]
	s_add_i32 m0, s50, 0x2000
	s_nop 0
	global_load_lds_dwordx4 v[246:247], off
	v_lshl_add_u64 v[246:247], s[10:11], 0, v[166:167]
	s_mov_b32 m0, s38
	s_nop 0
	global_load_lds_dwordx4 v[246:247], off
	s_mov_b32 m0, s39
	s_nop 0
	global_load_lds_dwordx4 v[248:249], off
	s_waitcnt vmcnt(8)
	s_waitcnt lgkmcnt(0)
	s_barrier
; #define PG8_STAGE(bufoff, gbase, voff) do { _Pragma("unroll") for (int _i = 0; _i < 2; ++_i) \
;         __builtin_amdgcn_global_load_lds((const unsigned*)((const char*)(gbase) + (voff)[_i]), (PG8_LAS unsigned*)(lds + (bufoff) + ldsw + _i * 8192), 16, 0, 0); } while (0)
; #define PG8_LDA(dst, b, h) do { _Pragma("unroll") for (int m = 0; m < 4; ++m) _Pragma("unroll") for (int k = 0; k < 2; ++k) dst[m][k] = *(const PG8_LAS bf16x8*)(lds + PG8_SA(b, h) + aoff + m * 2048 + k * 1024); } while (0)
; #define PG8_LDB(dst, b, h) do { _Pragma("unroll") for (int n = 0; n < 2; ++n) _Pragma("unroll") for (int k = 0; k < 2; ++k) dst[n][k] = *(const PG8_LAS bf16x8*)(lds + PG8_SB(b, h) + boff + n * 2048 + k * 1024); } while (0)
; #define PG8_MMA(ai, bj, At, Bt) do { __builtin_amdgcn_s_setprio(1); _Pragma("unroll") for (int m = 0; m < 4; ++m) _Pragma("unroll") for (int n = 0; n < 2; ++n) _Pragma("unroll") for (int k = 0; k < 2; ++k) \
;         acc[ai][bj][m][n] = __builtin_amdgcn_mfma_f32_16x16x32_bf16(Bt[n][k], At[m][k], acc[ai][bj][m][n], 0, 0, 0); __builtin_amdgcn_s_setprio(0); } while (0)
; #define PG8_WAIT_V(n) asm volatile("s_waitcnt vmcnt(" #n ")" ::: "memory")
; #define PG8_WAIT_L(n) asm volatile("s_waitcnt lgkmcnt(" #n ")" ::: "memory")
; #define PG8_BAR __builtin_amdgcn_s_barrier()
; #define PG8_SCHED __builtin_amdgcn_sched_barrier(0)
; template <class Epi, class Sched, bool ALIGN_EPI = false, bool SP2 = false>
; __device__ __forceinline__ void gemm_phase(PG8_LAS unsigned char* lds, const Gemm g, const Sched& S, const Epi& E) {
;     ...
;             PG8_WAIT_V(8); PG8_WAIT_L(0); PG8_BAR; PG8_MMA(1, 0, At, B0); PG8_MMA(1, 1, At, B1); PG8_BAR; PG8_SCHED;
;             PG8_LDB(B0, 1, 0); PG8_LDB(B1, 1, 1); PG8_SCHED; PG8_LDA(At, 1, 0); PG8_STAGE(PG8_SA(0, 1), a2 + hstepA, voffA);
;             PG8_WAIT_V(8); PG8_WAIT_L(0); PG8_BAR; PG8_MMA(0, 0, At, B0); PG8_MMA(0, 1, At, B1); PG8_BAR; PG8_SCHED;
	s_setprio 1
	v_mfma_f32_16x16x32_bf16 v[60:63], v[90:93], v[186:189], v[60:63]
	v_mfma_f32_16x16x32_bf16 v[56:59], v[98:101], v[186:189], v[56:59]
	v_mfma_f32_16x16x32_bf16 v[44:47], v[90:93], v[206:209], v[44:47]
	v_mfma_f32_16x16x32_bf16 v[40:43], v[98:101], v[206:209], v[40:43]
	v_mfma_f32_16x16x32_bf16 v[28:31], v[90:93], v[214:217], v[28:31]
	v_mfma_f32_16x16x32_bf16 v[24:27], v[98:101], v[214:217], v[24:27]
	v_mfma_f32_16x16x32_bf16 v[12:15], v[90:93], v[222:225], v[12:15]
	v_mfma_f32_16x16x32_bf16 v[8:11], v[98:101], v[222:225], v[8:11]
	v_mfma_f32_16x16x32_bf16 v[60:63], v[94:97], v[202:205], v[60:63]
	v_mfma_f32_16x16x32_bf16 v[56:59], v[102:105], v[202:205], v[56:59]
	v_mfma_f32_16x16x32_bf16 v[44:47], v[94:97], v[210:213], v[44:47]
	v_mfma_f32_16x16x32_bf16 v[40:43], v[102:105], v[210:213], v[40:43]
	v_mfma_f32_16x16x32_bf16 v[28:31], v[94:97], v[218:221], v[28:31]
	v_mfma_f32_16x16x32_bf16 v[24:27], v[102:105], v[218:221], v[24:27]
	v_mfma_f32_16x16x32_bf16 v[12:15], v[94:97], v[240:243], v[12:15]
	v_mfma_f32_16x16x32_bf16 v[8:11], v[102:105], v[240:243], v[8:11]
	v_mfma_f32_16x16x32_bf16 v[52:55], v[106:109], v[186:189], v[52:55]
	v_mfma_f32_16x16x32_bf16 v[48:51], v[118:121], v[186:189], v[48:51]
	v_mfma_f32_16x16x32_bf16 v[36:39], v[106:109], v[206:209], v[36:39]
	v_mfma_f32_16x16x32_bf16 v[32:35], v[118:121], v[206:209], v[32:35]
	v_mfma_f32_16x16x32_bf16 v[20:23], v[106:109], v[214:217], v[20:23]
	v_mfma_f32_16x16x32_bf16 v[16:19], v[118:121], v[214:217], v[16:19]
	v_mfma_f32_16x16x32_bf16 v[4:7], v[106:109], v[222:225], v[4:7]
	v_mfma_f32_16x16x32_bf16 v[0:3], v[118:121], v[222:225], v[0:3]
	v_mfma_f32_16x16x32_bf16 v[52:55], v[114:117], v[202:205], v[52:55]
	v_mfma_f32_16x16x32_bf16 v[48:51], v[126:129], v[202:205], v[48:51]
	v_mfma_f32_16x16x32_bf16 v[36:39], v[114:117], v[210:213], v[36:39]
	v_mfma_f32_16x16x32_bf16 v[32:35], v[126:129], v[210:213], v[32:35]
	v_mfma_f32_16x16x32_bf16 v[20:23], v[114:117], v[218:221], v[20:23]
	v_mfma_f32_16x16x32_bf16 v[16:19], v[126:129], v[218:221], v[16:19]
	v_mfma_f32_16x16x32_bf16 v[4:7], v[114:117], v[240:243], v[4:7]
	v_mfma_f32_16x16x32_bf16 v[0:3], v[126:129], v[240:243], v[0:3]
	s_setprio 0
	s_barrier
	s_add_i32 s34, 0, 0x18000
	s_add_i32 s35, 0, 0x1c000
	v_add_u32_e32 v102, s34, v177
	v_add_u32_e32 v126, s35, v177
	ds_read_b128 v[90:93], v102
	ds_read_b128 v[94:97], v102 offset:1024
	ds_read_b128 v[98:101], v102 offset:2048
	ds_read_b128 v[102:105], v102 offset:3072
	ds_read_b128 v[106:109], v126
	ds_read_b128 v[114:117], v126 offset:1024
	ds_read_b128 v[118:121], v126 offset:2048
	ds_read_b128 v[126:129], v126 offset:3072
	s_add_u32 s10, s10, 0x40000
	s_addc_u32 s11, s11, 0
	s_mov_b32 m0, s40
	v_lshl_add_u64 v[250:251], s[10:11], 0, v[166:167]
	ds_read_b128 v[186:189], v179 offset:32768
	ds_read_b128 v[202:205], v179 offset:33792
	ds_read_b128 v[206:209], v179 offset:34816
	ds_read_b128 v[210:213], v179 offset:35840
	ds_read_b128 v[214:217], v179 offset:36864
	ds_read_b128 v[218:221], v179 offset:37888
	ds_read_b128 v[222:225], v179 offset:38912
	ds_read_b128 v[240:243], v179 offset:39936
	global_load_lds_dwordx4 v[250:251], off
	v_lshl_add_u64 v[250:251], s[10:11], 0, v[164:165]
	s_mov_b32 m0, s41
	s_nop 0
	global_load_lds_dwordx4 v[250:251], off
	s_waitcnt vmcnt(8)
	s_waitcnt lgkmcnt(0)
	s_barrier
	s_setprio 1
	v_mfma_f32_16x16x32_bf16 v[158:161], v[90:93], v[186:189], v[158:161]
	v_mfma_f32_16x16x32_bf16 v[154:157], v[98:101], v[186:189], v[154:157]
	v_mfma_f32_16x16x32_bf16 v[142:145], v[90:93], v[206:209], v[142:145]
	v_mfma_f32_16x16x32_bf16 v[138:141], v[98:101], v[206:209], v[138:141]
	v_mfma_f32_16x16x32_bf16 v[122:125], v[90:93], v[214:217], v[122:125]
	v_mfma_f32_16x16x32_bf16 v[110:113], v[98:101], v[214:217], v[110:113]
	v_mfma_f32_16x16x32_bf16 v[78:81], v[90:93], v[222:225], v[78:81]
	v_mfma_f32_16x16x32_bf16 v[74:77], v[98:101], v[222:225], v[74:77]
	v_mfma_f32_16x16x32_bf16 v[158:161], v[94:97], v[202:205], v[158:161]
	v_mfma_f32_16x16x32_bf16 v[154:157], v[102:105], v[202:205], v[154:157]
	v_mfma_f32_16x16x32_bf16 v[142:145], v[94:97], v[210:213], v[142:145]
	v_mfma_f32_16x16x32_bf16 v[138:141], v[102:105], v[210:213], v[138:141]
	v_mfma_f32_16x16x32_bf16 v[122:125], v[94:97], v[218:221], v[122:125]
	v_mfma_f32_16x16x32_bf16 v[110:113], v[102:105], v[218:221], v[110:113]
	v_mfma_f32_16x16x32_bf16 v[78:81], v[94:97], v[240:243], v[78:81]
	v_mfma_f32_16x16x32_bf16 v[74:77], v[102:105], v[240:243], v[74:77]
	v_mfma_f32_16x16x32_bf16 v[150:153], v[106:109], v[186:189], v[150:153]
	v_mfma_f32_16x16x32_bf16 v[146:149], v[118:121], v[186:189], v[146:149]
	v_mfma_f32_16x16x32_bf16 v[134:137], v[106:109], v[206:209], v[134:137]
	v_mfma_f32_16x16x32_bf16 v[130:133], v[118:121], v[206:209], v[130:133]
	v_mfma_f32_16x16x32_bf16 v[86:89], v[106:109], v[214:217], v[86:89]
	v_mfma_f32_16x16x32_bf16 v[82:85], v[118:121], v[214:217], v[82:85]
	v_mfma_f32_16x16x32_bf16 v[70:73], v[106:109], v[222:225], v[70:73]
	v_mfma_f32_16x16x32_bf16 v[66:69], v[118:121], v[222:225], v[66:69]
	v_mfma_f32_16x16x32_bf16 v[150:153], v[114:117], v[202:205], v[150:153]
	v_mfma_f32_16x16x32_bf16 v[146:149], v[126:129], v[202:205], v[146:149]
	v_mfma_f32_16x16x32_bf16 v[134:137], v[114:117], v[210:213], v[134:137]
	v_mfma_f32_16x16x32_bf16 v[130:133], v[126:129], v[210:213], v[130:133]
	v_mfma_f32_16x16x32_bf16 v[86:89], v[114:117], v[218:221], v[86:89]
	v_mfma_f32_16x16x32_bf16 v[82:85], v[126:129], v[218:221], v[82:85]
	v_mfma_f32_16x16x32_bf16 v[70:73], v[114:117], v[240:243], v[70:73]
	v_mfma_f32_16x16x32_bf16 v[66:69], v[126:129], v[240:243], v[66:69]
	s_setprio 0
	s_barrier
; #define PG8_STAGE(bufoff, gbase, voff) do { _Pragma("unroll") for (int _i = 0; _i < 2; ++_i) \
;         __builtin_amdgcn_global_load_lds((const unsigned*)((const char*)(gbase) + (voff)[_i]), (PG8_LAS unsigned*)(lds + (bufoff) + ldsw + _i * 8192), 16, 0, 0); } while (0)
; #define PG8_LDA(dst, b, h) do { _Pragma("unroll") for (int m = 0; m < 4; ++m) _Pragma("unroll") for (int k = 0; k < 2; ++k) dst[m][k] = *(const PG8_LAS bf16x8*)(lds + PG8_SA(b, h) + aoff + m * 2048 + k * 1024); } while (0)
; #define PG8_MMA(ai, bj, At, Bt) do { __builtin_amdgcn_s_setprio(1); _Pragma("unroll") for (int m = 0; m < 4; ++m) _Pragma("unroll") for (int n = 0; n < 2; ++n) _Pragma("unroll") for (int k = 0; k < 2; ++k) \
;         acc[ai][bj][m][n] = __builtin_amdgcn_mfma_f32_16x16x32_bf16(Bt[n][k], At[m][k], acc[ai][bj][m][n], 0, 0, 0); __builtin_amdgcn_s_setprio(0); } while (0)
; #define PG8_WAIT_V(n) asm volatile("s_waitcnt vmcnt(" #n ")" ::: "memory")
; #define PG8_WAIT_L(n) asm volatile("s_waitcnt lgkmcnt(" #n ")" ::: "memory")
; #define PG8_BAR __builtin_amdgcn_s_barrier()
; #define PG8_SCHED __builtin_amdgcn_sched_barrier(0)
; template <class Epi, class Sched, bool ALIGN_EPI = false, bool SP2 = false>
; __device__ __forceinline__ void gemm_phase(PG8_LAS unsigned char* lds, const Gemm g, const Sched& S, const Epi& E) {
;     ...
;             PG8_LDA(At, 1, 1); PG8_STAGE(PG8_SB(1, 0), b3, voffB); PG8_STAGE(PG8_SB(1, 1), b3 + hstepB, voffB); PG8_STAGE(PG8_SA(1, 0), a3, voffA);
;             PG8_WAIT_V(8); PG8_WAIT_L(0); PG8_BAR; PG8_MMA(1, 0, At, B0); PG8_MMA(1, 1, At, B1); PG8_BAR; PG8_SCHED;
	s_add_i32 s10, s34, s36
	v_lshl_add_u64 v[226:227], v[226:227], 0, s[88:89]
	s_mov_b32 m0, s10
	ds_read_b128 v[186:189], v179 offset:49152
	ds_read_b128 v[202:205], v179 offset:50176
	ds_read_b128 v[206:209], v179 offset:51200
	ds_read_b128 v[210:213], v179 offset:52224
	ds_read_b128 v[214:217], v179 offset:53248
	ds_read_b128 v[218:221], v179 offset:54272
	ds_read_b128 v[222:225], v179 offset:55296
	ds_read_b128 v[240:243], v179 offset:56320
	global_load_lds_dwordx4 v[226:227], off
	s_add_i32 m0, s10, 0x2000
	s_add_u32 s8, s8, 0x40080
	v_lshl_add_u64 v[226:227], v[244:245], 0, s[88:89]
	s_addc_u32 s9, s9, 0
	s_add_i32 s10, s35, s36
	global_load_lds_dwordx4 v[226:227], off
	v_lshl_add_u64 v[226:227], s[8:9], 0, v[64:65]
	s_mov_b32 m0, s10
	s_nop 0
	global_load_lds_dwordx4 v[226:227], off
	v_lshl_add_u64 v[226:227], s[8:9], 0, v[162:163]
	s_add_i32 m0, s10, 0x2000
	s_nop 0
	global_load_lds_dwordx4 v[226:227], off
	v_lshl_add_u64 v[226:227], v[246:247], 0, s[88:89]
	s_mov_b32 m0, s45
	s_nop 0
	global_load_lds_dwordx4 v[226:227], off
	v_lshl_add_u64 v[226:227], v[248:249], 0, s[88:89]
	s_mov_b32 m0, s46
	s_nop 0
	global_load_lds_dwordx4 v[226:227], off
	s_waitcnt vmcnt(8)
	s_waitcnt lgkmcnt(0)
	s_barrier
	s_setprio 1
	v_mfma_f32_16x16x32_bf16 v[60:63], v[90:93], v[186:189], v[60:63]
	v_mfma_f32_16x16x32_bf16 v[56:59], v[98:101], v[186:189], v[56:59]
	v_mfma_f32_16x16x32_bf16 v[44:47], v[90:93], v[206:209], v[44:47]
	v_mfma_f32_16x16x32_bf16 v[40:43], v[98:101], v[206:209], v[40:43]
	v_mfma_f32_16x16x32_bf16 v[28:31], v[90:93], v[214:217], v[28:31]
	v_mfma_f32_16x16x32_bf16 v[24:27], v[98:101], v[214:217], v[24:27]
	v_mfma_f32_16x16x32_bf16 v[12:15], v[90:93], v[222:225], v[12:15]
	v_mfma_f32_16x16x32_bf16 v[8:11], v[98:101], v[222:225], v[8:11]
	v_mfma_f32_16x16x32_bf16 v[60:63], v[94:97], v[202:205], v[60:63]
	v_mfma_f32_16x16x32_bf16 v[56:59], v[102:105], v[202:205], v[56:59]
	v_mfma_f32_16x16x32_bf16 v[44:47], v[94:97], v[210:213], v[44:47]
	v_mfma_f32_16x16x32_bf16 v[40:43], v[102:105], v[210:213], v[40:43]
	v_mfma_f32_16x16x32_bf16 v[28:31], v[94:97], v[218:221], v[28:31]
	v_mfma_f32_16x16x32_bf16 v[24:27], v[102:105], v[218:221], v[24:27]
	v_mfma_f32_16x16x32_bf16 v[12:15], v[94:97], v[240:243], v[12:15]
	v_mfma_f32_16x16x32_bf16 v[8:11], v[102:105], v[240:243], v[8:11]
	v_mfma_f32_16x16x32_bf16 v[52:55], v[106:109], v[186:189], v[52:55]
	v_mfma_f32_16x16x32_bf16 v[48:51], v[118:121], v[186:189], v[48:51]
	v_mfma_f32_16x16x32_bf16 v[36:39], v[106:109], v[206:209], v[36:39]
	v_mfma_f32_16x16x32_bf16 v[32:35], v[118:121], v[206:209], v[32:35]
	v_mfma_f32_16x16x32_bf16 v[20:23], v[106:109], v[214:217], v[20:23]
	v_mfma_f32_16x16x32_bf16 v[16:19], v[118:121], v[214:217], v[16:19]
	v_mfma_f32_16x16x32_bf16 v[4:7], v[106:109], v[222:225], v[4:7]
	v_mfma_f32_16x16x32_bf16 v[0:3], v[118:121], v[222:225], v[0:3]
	v_mfma_f32_16x16x32_bf16 v[52:55], v[114:117], v[202:205], v[52:55]
	v_mfma_f32_16x16x32_bf16 v[48:51], v[126:129], v[202:205], v[48:51]
	v_mfma_f32_16x16x32_bf16 v[36:39], v[114:117], v[210:213], v[36:39]
	v_mfma_f32_16x16x32_bf16 v[32:35], v[126:129], v[210:213], v[32:35]
	v_mfma_f32_16x16x32_bf16 v[20:23], v[114:117], v[218:221], v[20:23]
	v_mfma_f32_16x16x32_bf16 v[16:19], v[126:129], v[218:221], v[16:19]
	v_mfma_f32_16x16x32_bf16 v[4:7], v[114:117], v[240:243], v[4:7]
	v_mfma_f32_16x16x32_bf16 v[0:3], v[126:129], v[240:243], v[0:3]
	s_setprio 0
	s_barrier
	s_add_u32 s4, s4, 0x100
	s_addc_u32 s5, s5, 0
	s_add_u32 s29, s29, 0x100
	s_addc_u32 s30, s30, 0
	s_cmp_ge_i32 s31, s43
	s_mov_b32 s8, s31
	s_cbranch_scc0 .LBB0_746

; #define PG8_STAGE(bufoff, gbase, voff) do { _Pragma("unroll") for (int _i = 0; _i < 2; ++_i) \
;         __builtin_amdgcn_global_load_lds((const unsigned*)((const char*)(gbase) + (voff)[_i]), (PG8_LAS unsigned*)(lds + (bufoff) + ldsw + _i * 8192), 16, 0, 0); } while (0)
; #define PG8_LDA(dst, b, h) do { _Pragma("unroll") for (int m = 0; m < 4; ++m) _Pragma("unroll") for (int k = 0; k < 2; ++k) dst[m][k] = *(const PG8_LAS bf16x8*)(lds + PG8_SA(b, h) + aoff + m * 2048 + k * 1024); } while (0)
; #define PG8_LDB(dst, b, h) do { _Pragma("unroll") for (int n = 0; n < 2; ++n) _Pragma("unroll") for (int k = 0; k < 2; ++k) dst[n][k] = *(const PG8_LAS bf16x8*)(lds + PG8_SB(b, h) + boff + n * 2048 + k * 1024); } while (0)
; #define PG8_MMA(ai, bj, At, Bt) do { __builtin_amdgcn_s_setprio(1); _Pragma("unroll") for (int m = 0; m < 4; ++m) _Pragma("unroll") for (int n = 0; n < 2; ++n) _Pragma("unroll") for (int k = 0; k < 2; ++k) \
;         acc[ai][bj][m][n] = __builtin_amdgcn_mfma_f32_16x16x32_bf16(Bt[n][k], At[m][k], acc[ai][bj][m][n], 0, 0, 0); __builtin_amdgcn_s_setprio(0); } while (0)
; #define PG8_WAIT_V(n) asm volatile("s_waitcnt vmcnt(" #n ")" ::: "memory")
; #define PG8_WAIT_L(n) asm volatile("s_waitcnt lgkmcnt(" #n ")" ::: "memory")
; #define PG8_BAR __builtin_amdgcn_s_barrier()
; #define PG8_SCHED __builtin_amdgcn_sched_barrier(0)
; template <class Epi, class Sched, bool ALIGN_EPI = false, bool SP2 = false>
; __device__ __forceinline__ void gemm_phase(PG8_LAS unsigned char* lds, const Gemm g, const Sched& S, const Epi& E) {
;     ...
;             PG8_LDB(B0, 0, 0); PG8_LDB(B1, 0, 1); PG8_SCHED; PG8_LDA(At, 0, 0); PG8_STAGE(PG8_SA(1, 1), a1 + hstepA, voffA);
;             PG8_WAIT_V(8); PG8_WAIT_L(0); PG8_BAR; PG8_MMA(0, 0, At, B0); PG8_MMA(0, 1, At, B1); PG8_BAR; PG8_SCHED;
;             PG8_LDA(At, 0, 1); PG8_STAGE(PG8_SB(0, 0), b2, voffB); PG8_STAGE(PG8_SB(0, 1), b2 + hstepB, voffB); PG8_STAGE(PG8_SA(0, 0), a2, voffA);
;             PG8_WAIT_V(8); PG8_WAIT_L(0); PG8_BAR; PG8_MMA(1, 0, At, B0); PG8_MMA(1, 1, At, B1); PG8_BAR; PG8_SCHED;
.LBB0_905:
	s_add_i32 s48, s20, 2
	s_add_u32 s21, s18, 0xfffc0080
	s_addc_u32 s22, s19, -1
	s_add_i32 s49, 0, 0x10000
	s_cmp_eq_u32 s45, s20
	s_cselect_b32 s23, s13, s22
	s_cselect_b32 s22, s44, s21
	v_add_u32_e32 v149, s49, v145
	s_cselect_b32 s21, s15, s47
	s_cselect_b32 s20, s14, s46
	s_add_i32 s52, 0, 0x14000
	ds_read_b128 v[156:159], v149
	ds_read_b128 v[160:163], v149 offset:1024
	ds_read_b128 v[164:167], v149 offset:2048
	ds_read_b128 v[168:171], v149 offset:3072
	v_add_u32_e32 v149, s52, v145
	ds_read_b128 v[172:175], v149
	ds_read_b128 v[176:179], v149 offset:1024
	ds_read_b128 v[180:183], v149 offset:2048
	ds_read_b128 v[184:187], v149 offset:3072
	v_lshl_add_u64 v[188:189], s[18:19], 0, v[136:137]
	s_add_i32 m0, s2, 0xc000
	ds_read_b128 v[202:205], v147
	ds_read_b128 v[206:209], v147 offset:1024
	ds_read_b128 v[210:213], v147 offset:2048
	ds_read_b128 v[214:217], v147 offset:3072
	ds_read_b128 v[218:221], v147 offset:4096
	ds_read_b128 v[222:225], v147 offset:5120
	ds_read_b128 v[240:243], v147 offset:6144
	ds_read_b128 v[244:247], v147 offset:7168
	global_load_lds_dwordx4 v[188:189], off
	v_lshl_add_u64 v[188:189], s[18:19], 0, v[138:139]
	s_add_i32 m0, s2, 0xe000
	s_nop 0
	global_load_lds_dwordx4 v[188:189], off
	s_waitcnt vmcnt(8)
	s_waitcnt lgkmcnt(0)
	s_barrier
	s_setprio 1
	v_mfma_f32_16x16x32_bf16 v[126:129], v[156:159], v[202:205], v[126:129]
	v_mfma_f32_16x16x32_bf16 v[122:125], v[164:167], v[202:205], v[122:125]
	v_mfma_f32_16x16x32_bf16 v[118:121], v[156:159], v[210:213], v[118:121]
	v_mfma_f32_16x16x32_bf16 v[110:113], v[164:167], v[210:213], v[110:113]
	v_mfma_f32_16x16x32_bf16 v[102:105], v[156:159], v[218:221], v[102:105]
	v_mfma_f32_16x16x32_bf16 v[94:97], v[164:167], v[218:221], v[94:97]
	v_mfma_f32_16x16x32_bf16 v[86:89], v[156:159], v[240:243], v[86:89]
	v_mfma_f32_16x16x32_bf16 v[78:81], v[164:167], v[240:243], v[78:81]
	v_mfma_f32_16x16x32_bf16 v[126:129], v[160:163], v[206:209], v[126:129]
	v_mfma_f32_16x16x32_bf16 v[122:125], v[168:171], v[206:209], v[122:125]
	v_mfma_f32_16x16x32_bf16 v[118:121], v[160:163], v[214:217], v[118:121]
	v_mfma_f32_16x16x32_bf16 v[110:113], v[168:171], v[214:217], v[110:113]
	v_mfma_f32_16x16x32_bf16 v[102:105], v[160:163], v[222:225], v[102:105]
	v_mfma_f32_16x16x32_bf16 v[94:97], v[168:171], v[222:225], v[94:97]
	v_mfma_f32_16x16x32_bf16 v[86:89], v[160:163], v[244:247], v[86:89]
	v_mfma_f32_16x16x32_bf16 v[78:81], v[168:171], v[244:247], v[78:81]
	v_mfma_f32_16x16x32_bf16 v[114:117], v[172:175], v[202:205], v[114:117]
	v_mfma_f32_16x16x32_bf16 v[106:109], v[180:183], v[202:205], v[106:109]
	v_mfma_f32_16x16x32_bf16 v[98:101], v[172:175], v[210:213], v[98:101]
	v_mfma_f32_16x16x32_bf16 v[90:93], v[180:183], v[210:213], v[90:93]
	v_mfma_f32_16x16x32_bf16 v[82:85], v[172:175], v[218:221], v[82:85]
	v_mfma_f32_16x16x32_bf16 v[74:77], v[180:183], v[218:221], v[74:77]
	v_mfma_f32_16x16x32_bf16 v[70:73], v[172:175], v[240:243], v[70:73]
	v_mfma_f32_16x16x32_bf16 v[66:69], v[180:183], v[240:243], v[66:69]
	v_mfma_f32_16x16x32_bf16 v[114:117], v[176:179], v[206:209], v[114:117]
	v_mfma_f32_16x16x32_bf16 v[106:109], v[184:187], v[206:209], v[106:109]
	v_mfma_f32_16x16x32_bf16 v[98:101], v[176:179], v[214:217], v[98:101]
	v_mfma_f32_16x16x32_bf16 v[90:93], v[184:187], v[214:217], v[90:93]
	v_mfma_f32_16x16x32_bf16 v[82:85], v[176:179], v[222:225], v[82:85]
	v_mfma_f32_16x16x32_bf16 v[74:77], v[184:187], v[222:225], v[74:77]
	v_mfma_f32_16x16x32_bf16 v[70:73], v[176:179], v[244:247], v[70:73]
	v_mfma_f32_16x16x32_bf16 v[66:69], v[184:187], v[244:247], v[66:69]
	s_setprio 0
	s_barrier
	s_add_i32 s49, s49, s24
	v_lshl_add_u64 v[188:189], s[20:21], 0, v[64:65]
	s_mov_b32 m0, s49
	ds_read_b128 v[202:205], v147 offset:16384
	ds_read_b128 v[206:209], v147 offset:17408
	ds_read_b128 v[210:213], v147 offset:18432
	ds_read_b128 v[214:217], v147 offset:19456
	ds_read_b128 v[218:221], v147 offset:20480
	ds_read_b128 v[222:225], v147 offset:21504
	ds_read_b128 v[240:243], v147 offset:22528
	ds_read_b128 v[244:247], v147 offset:23552
	global_load_lds_dwordx4 v[188:189], off
	s_add_i32 m0, s49, 0x2000
	s_add_u32 s50, s20, 0x18000
	v_lshl_add_u64 v[226:227], s[20:21], 0, v[130:131]
	s_addc_u32 s51, s21, 0
	s_add_i32 s49, s52, s24
	global_load_lds_dwordx4 v[226:227], off
	v_lshl_add_u64 v[248:249], s[50:51], 0, v[64:65]
	s_mov_b32 m0, s49
	v_lshl_add_u64 v[250:251], s[22:23], 0, v[132:133]
	global_load_lds_dwordx4 v[248:249], off
	v_lshl_add_u64 v[248:249], s[50:51], 0, v[130:131]
	s_add_i32 m0, s49, 0x2000
	s_nop 0
	global_load_lds_dwordx4 v[248:249], off
	v_lshl_add_u64 v[248:249], s[22:23], 0, v[134:135]
	s_mov_b32 m0, s2
	s_nop 0
	global_load_lds_dwordx4 v[248:249], off
	s_mov_b32 m0, s34
	s_nop 0
	global_load_lds_dwordx4 v[250:251], off
	s_waitcnt vmcnt(8)
	s_waitcnt lgkmcnt(0)
	s_barrier
; #define PG8_STAGE(bufoff, gbase, voff) do { _Pragma("unroll") for (int _i = 0; _i < 2; ++_i) \
;         __builtin_amdgcn_global_load_lds((const unsigned*)((const char*)(gbase) + (voff)[_i]), (PG8_LAS unsigned*)(lds + (bufoff) + ldsw + _i * 8192), 16, 0, 0); } while (0)
; #define PG8_LDA(dst, b, h) do { _Pragma("unroll") for (int m = 0; m < 4; ++m) _Pragma("unroll") for (int k = 0; k < 2; ++k) dst[m][k] = *(const PG8_LAS bf16x8*)(lds + PG8_SA(b, h) + aoff + m * 2048 + k * 1024); } while (0)
; #define PG8_LDB(dst, b, h) do { _Pragma("unroll") for (int n = 0; n < 2; ++n) _Pragma("unroll") for (int k = 0; k < 2; ++k) dst[n][k] = *(const PG8_LAS bf16x8*)(lds + PG8_SB(b, h) + boff + n * 2048 + k * 1024); } while (0)
; #define PG8_MMA(ai, bj, At, Bt) do { __builtin_amdgcn_s_setprio(1); _Pragma("unroll") for (int m = 0; m < 4; ++m) _Pragma("unroll") for (int n = 0; n < 2; ++n) _Pragma("unroll") for (int k = 0; k < 2; ++k) \
;         acc[ai][bj][m][n] = __builtin_amdgcn_mfma_f32_16x16x32_bf16(Bt[n][k], At[m][k], acc[ai][bj][m][n], 0, 0, 0); __builtin_amdgcn_s_setprio(0); } while (0)
; #define PG8_WAIT_V(n) asm volatile("s_waitcnt vmcnt(" #n ")" ::: "memory")
; #define PG8_WAIT_L(n) asm volatile("s_waitcnt lgkmcnt(" #n ")" ::: "memory")
; #define PG8_BAR __builtin_amdgcn_s_barrier()
; #define PG8_SCHED __builtin_amdgcn_sched_barrier(0)
; template <class Epi, class Sched, bool ALIGN_EPI = false, bool SP2 = false>
; __device__ __forceinline__ void gemm_phase(PG8_LAS unsigned char* lds, const Gemm g, const Sched& S, const Epi& E) {
;     ...
;             PG8_WAIT_V(8); PG8_WAIT_L(0); PG8_BAR; PG8_MMA(1, 0, At, B0); PG8_MMA(1, 1, At, B1); PG8_BAR; PG8_SCHED;
;             PG8_LDB(B0, 1, 0); PG8_LDB(B1, 1, 1); PG8_SCHED; PG8_LDA(At, 1, 0); PG8_STAGE(PG8_SA(0, 1), a2 + hstepA, voffA);
;             PG8_WAIT_V(8); PG8_WAIT_L(0); PG8_BAR; PG8_MMA(0, 0, At, B0); PG8_MMA(0, 1, At, B1); PG8_BAR; PG8_SCHED;
	s_setprio 1
	v_mfma_f32_16x16x32_bf16 v[60:63], v[156:159], v[202:205], v[60:63]
	v_mfma_f32_16x16x32_bf16 v[56:59], v[164:167], v[202:205], v[56:59]
	v_mfma_f32_16x16x32_bf16 v[52:55], v[156:159], v[210:213], v[52:55]
	v_mfma_f32_16x16x32_bf16 v[44:47], v[164:167], v[210:213], v[44:47]
	v_mfma_f32_16x16x32_bf16 v[36:39], v[156:159], v[218:221], v[36:39]
	v_mfma_f32_16x16x32_bf16 v[28:31], v[164:167], v[218:221], v[28:31]
	v_mfma_f32_16x16x32_bf16 v[20:23], v[156:159], v[240:243], v[20:23]
	v_mfma_f32_16x16x32_bf16 v[12:15], v[164:167], v[240:243], v[12:15]
	v_mfma_f32_16x16x32_bf16 v[60:63], v[160:163], v[206:209], v[60:63]
	v_mfma_f32_16x16x32_bf16 v[56:59], v[168:171], v[206:209], v[56:59]
	v_mfma_f32_16x16x32_bf16 v[52:55], v[160:163], v[214:217], v[52:55]
	v_mfma_f32_16x16x32_bf16 v[44:47], v[168:171], v[214:217], v[44:47]
	v_mfma_f32_16x16x32_bf16 v[36:39], v[160:163], v[222:225], v[36:39]
	v_mfma_f32_16x16x32_bf16 v[28:31], v[168:171], v[222:225], v[28:31]
	v_mfma_f32_16x16x32_bf16 v[20:23], v[160:163], v[244:247], v[20:23]
	v_mfma_f32_16x16x32_bf16 v[12:15], v[168:171], v[244:247], v[12:15]
	v_mfma_f32_16x16x32_bf16 v[48:51], v[172:175], v[202:205], v[48:51]
	v_mfma_f32_16x16x32_bf16 v[40:43], v[180:183], v[202:205], v[40:43]
	v_mfma_f32_16x16x32_bf16 v[32:35], v[172:175], v[210:213], v[32:35]
	v_mfma_f32_16x16x32_bf16 v[24:27], v[180:183], v[210:213], v[24:27]
	v_mfma_f32_16x16x32_bf16 v[16:19], v[172:175], v[218:221], v[16:19]
	v_mfma_f32_16x16x32_bf16 v[8:11], v[180:183], v[218:221], v[8:11]
	v_mfma_f32_16x16x32_bf16 v[4:7], v[172:175], v[240:243], v[4:7]
	v_mfma_f32_16x16x32_bf16 v[0:3], v[180:183], v[240:243], v[0:3]
	v_mfma_f32_16x16x32_bf16 v[48:51], v[176:179], v[206:209], v[48:51]
	v_mfma_f32_16x16x32_bf16 v[40:43], v[184:187], v[206:209], v[40:43]
	v_mfma_f32_16x16x32_bf16 v[32:35], v[176:179], v[214:217], v[32:35]
	v_mfma_f32_16x16x32_bf16 v[24:27], v[184:187], v[214:217], v[24:27]
	v_mfma_f32_16x16x32_bf16 v[16:19], v[176:179], v[222:225], v[16:19]
	v_mfma_f32_16x16x32_bf16 v[8:11], v[184:187], v[222:225], v[8:11]
	v_mfma_f32_16x16x32_bf16 v[4:7], v[176:179], v[244:247], v[4:7]
	v_mfma_f32_16x16x32_bf16 v[0:3], v[184:187], v[244:247], v[0:3]
	s_setprio 0
	s_barrier
	s_add_i32 s49, 0, 0x18000
	v_add_u32_e32 v149, s49, v145
	s_add_i32 s50, 0, 0x1c000
	ds_read_b128 v[156:159], v149
	ds_read_b128 v[160:163], v149 offset:1024
	ds_read_b128 v[164:167], v149 offset:2048
	ds_read_b128 v[168:171], v149 offset:3072
	v_add_u32_e32 v149, s50, v145
	ds_read_b128 v[172:175], v149
	ds_read_b128 v[176:179], v149 offset:1024
	ds_read_b128 v[180:183], v149 offset:2048
	ds_read_b128 v[184:187], v149 offset:3072
	s_add_u32 s22, s22, 0x40000
	s_addc_u32 s23, s23, 0
	s_mov_b32 m0, s35
	v_lshl_add_u64 v[252:253], s[22:23], 0, v[134:135]
	ds_read_b128 v[202:205], v147 offset:32768
	ds_read_b128 v[206:209], v147 offset:33792
	ds_read_b128 v[210:213], v147 offset:34816
	ds_read_b128 v[214:217], v147 offset:35840
	ds_read_b128 v[218:221], v147 offset:36864
	ds_read_b128 v[222:225], v147 offset:37888
	ds_read_b128 v[240:243], v147 offset:38912
	ds_read_b128 v[244:247], v147 offset:39936
	global_load_lds_dwordx4 v[252:253], off
	v_lshl_add_u64 v[252:253], s[22:23], 0, v[132:133]
	s_mov_b32 m0, s36
	s_nop 0
	global_load_lds_dwordx4 v[252:253], off
	s_waitcnt vmcnt(8)
	s_waitcnt lgkmcnt(0)
	s_barrier
	s_setprio 1
	v_mfma_f32_16x16x32_bf16 v[126:129], v[156:159], v[202:205], v[126:129]
	v_mfma_f32_16x16x32_bf16 v[122:125], v[164:167], v[202:205], v[122:125]
	v_mfma_f32_16x16x32_bf16 v[118:121], v[156:159], v[210:213], v[118:121]
	v_mfma_f32_16x16x32_bf16 v[110:113], v[164:167], v[210:213], v[110:113]
	v_mfma_f32_16x16x32_bf16 v[102:105], v[156:159], v[218:221], v[102:105]
	v_mfma_f32_16x16x32_bf16 v[94:97], v[164:167], v[218:221], v[94:97]
	v_mfma_f32_16x16x32_bf16 v[86:89], v[156:159], v[240:243], v[86:89]
	v_mfma_f32_16x16x32_bf16 v[78:81], v[164:167], v[240:243], v[78:81]
	v_mfma_f32_16x16x32_bf16 v[126:129], v[160:163], v[206:209], v[126:129]
	v_mfma_f32_16x16x32_bf16 v[122:125], v[168:171], v[206:209], v[122:125]
	v_mfma_f32_16x16x32_bf16 v[118:121], v[160:163], v[214:217], v[118:121]
	v_mfma_f32_16x16x32_bf16 v[110:113], v[168:171], v[214:217], v[110:113]
	v_mfma_f32_16x16x32_bf16 v[102:105], v[160:163], v[222:225], v[102:105]
	v_mfma_f32_16x16x32_bf16 v[94:97], v[168:171], v[222:225], v[94:97]
	v_mfma_f32_16x16x32_bf16 v[86:89], v[160:163], v[244:247], v[86:89]
	v_mfma_f32_16x16x32_bf16 v[78:81], v[168:171], v[244:247], v[78:81]
	v_mfma_f32_16x16x32_bf16 v[114:117], v[172:175], v[202:205], v[114:117]
	v_mfma_f32_16x16x32_bf16 v[106:109], v[180:183], v[202:205], v[106:109]
	v_mfma_f32_16x16x32_bf16 v[98:101], v[172:175], v[210:213], v[98:101]
	v_mfma_f32_16x16x32_bf16 v[90:93], v[180:183], v[210:213], v[90:93]
	v_mfma_f32_16x16x32_bf16 v[82:85], v[172:175], v[218:221], v[82:85]
	v_mfma_f32_16x16x32_bf16 v[74:77], v[180:183], v[218:221], v[74:77]
	v_mfma_f32_16x16x32_bf16 v[70:73], v[172:175], v[240:243], v[70:73]
	v_mfma_f32_16x16x32_bf16 v[66:69], v[180:183], v[240:243], v[66:69]
	v_mfma_f32_16x16x32_bf16 v[114:117], v[176:179], v[206:209], v[114:117]
	v_mfma_f32_16x16x32_bf16 v[106:109], v[184:187], v[206:209], v[106:109]
	v_mfma_f32_16x16x32_bf16 v[98:101], v[176:179], v[214:217], v[98:101]
	v_mfma_f32_16x16x32_bf16 v[90:93], v[184:187], v[214:217], v[90:93]
	v_mfma_f32_16x16x32_bf16 v[82:85], v[176:179], v[222:225], v[82:85]
	v_mfma_f32_16x16x32_bf16 v[74:77], v[184:187], v[222:225], v[74:77]
	v_mfma_f32_16x16x32_bf16 v[70:73], v[176:179], v[244:247], v[70:73]
	v_mfma_f32_16x16x32_bf16 v[66:69], v[184:187], v[244:247], v[66:69]
	s_setprio 0
	s_barrier
; #define PG8_STAGE(bufoff, gbase, voff) do { _Pragma("unroll") for (int _i = 0; _i < 2; ++_i) \
;         __builtin_amdgcn_global_load_lds((const unsigned*)((const char*)(gbase) + (voff)[_i]), (PG8_LAS unsigned*)(lds + (bufoff) + ldsw + _i * 8192), 16, 0, 0); } while (0)
; #define PG8_LDA(dst, b, h) do { _Pragma("unroll") for (int m = 0; m < 4; ++m) _Pragma("unroll") for (int k = 0; k < 2; ++k) dst[m][k] = *(const PG8_LAS bf16x8*)(lds + PG8_SA(b, h) + aoff + m * 2048 + k * 1024); } while (0)
; #define PG8_MMA(ai, bj, At, Bt) do { __builtin_amdgcn_s_setprio(1); _Pragma("unroll") for (int m = 0; m < 4; ++m) _Pragma("unroll") for (int n = 0; n < 2; ++n) _Pragma("unroll") for (int k = 0; k < 2; ++k) \
;         acc[ai][bj][m][n] = __builtin_amdgcn_mfma_f32_16x16x32_bf16(Bt[n][k], At[m][k], acc[ai][bj][m][n], 0, 0, 0); __builtin_amdgcn_s_setprio(0); } while (0)
; #define PG8_WAIT_V(n) asm volatile("s_waitcnt vmcnt(" #n ")" ::: "memory")
; #define PG8_WAIT_L(n) asm volatile("s_waitcnt lgkmcnt(" #n ")" ::: "memory")
; #define PG8_BAR __builtin_amdgcn_s_barrier()
; #define PG8_SCHED __builtin_amdgcn_sched_barrier(0)
; template <class Epi, class Sched, bool ALIGN_EPI = false, bool SP2 = false>
; __device__ __forceinline__ void gemm_phase(PG8_LAS unsigned char* lds, const Gemm g, const Sched& S, const Epi& E) {
;     ...
;             PG8_LDA(At, 1, 1); PG8_STAGE(PG8_SB(1, 0), b3, voffB); PG8_STAGE(PG8_SB(1, 1), b3 + hstepB, voffB); PG8_STAGE(PG8_SA(1, 0), a3, voffA);
;             PG8_WAIT_V(8); PG8_WAIT_L(0); PG8_BAR; PG8_MMA(1, 0, At, B0); PG8_MMA(1, 1, At, B1); PG8_BAR; PG8_SCHED;
;     ...
;         if constexpr (ALIGN_EPI) { if (wr == 0) PG8_BAR; }
	s_add_i32 s22, s49, s24
	v_lshl_add_u64 v[188:189], v[188:189], 0, s[88:89]
	s_mov_b32 m0, s22
	ds_read_b128 v[202:205], v147 offset:49152
	ds_read_b128 v[206:209], v147 offset:50176
	ds_read_b128 v[210:213], v147 offset:51200
	ds_read_b128 v[214:217], v147 offset:52224
	ds_read_b128 v[218:221], v147 offset:53248
	ds_read_b128 v[222:225], v147 offset:54272
	ds_read_b128 v[240:243], v147 offset:55296
	ds_read_b128 v[244:247], v147 offset:56320
	global_load_lds_dwordx4 v[188:189], off
	s_add_i32 m0, s22, 0x2000
	s_add_u32 s20, s20, 0x18080
	v_lshl_add_u64 v[188:189], v[226:227], 0, s[88:89]
	s_addc_u32 s21, s21, 0
	s_add_i32 s22, s50, s24
	global_load_lds_dwordx4 v[188:189], off
	v_lshl_add_u64 v[188:189], s[20:21], 0, v[64:65]
	s_mov_b32 m0, s22
	s_nop 0
	global_load_lds_dwordx4 v[188:189], off
	v_lshl_add_u64 v[188:189], s[20:21], 0, v[130:131]
	s_add_i32 m0, s22, 0x2000
	s_nop 0
	global_load_lds_dwordx4 v[188:189], off
	v_lshl_add_u64 v[188:189], v[248:249], 0, s[88:89]
	s_mov_b32 m0, s37
	s_nop 0
	global_load_lds_dwordx4 v[188:189], off
	v_lshl_add_u64 v[188:189], v[250:251], 0, s[88:89]
	s_mov_b32 m0, s38
	s_nop 0
	global_load_lds_dwordx4 v[188:189], off
	s_waitcnt vmcnt(8)
	s_waitcnt lgkmcnt(0)
	s_barrier
	s_setprio 1
	v_mfma_f32_16x16x32_bf16 v[60:63], v[156:159], v[202:205], v[60:63]
	v_mfma_f32_16x16x32_bf16 v[56:59], v[164:167], v[202:205], v[56:59]
	v_mfma_f32_16x16x32_bf16 v[52:55], v[156:159], v[210:213], v[52:55]
	v_mfma_f32_16x16x32_bf16 v[44:47], v[164:167], v[210:213], v[44:47]
	v_mfma_f32_16x16x32_bf16 v[36:39], v[156:159], v[218:221], v[36:39]
	v_mfma_f32_16x16x32_bf16 v[28:31], v[164:167], v[218:221], v[28:31]
	v_mfma_f32_16x16x32_bf16 v[20:23], v[156:159], v[240:243], v[20:23]
	v_mfma_f32_16x16x32_bf16 v[12:15], v[164:167], v[240:243], v[12:15]
	v_mfma_f32_16x16x32_bf16 v[60:63], v[160:163], v[206:209], v[60:63]
	v_mfma_f32_16x16x32_bf16 v[56:59], v[168:171], v[206:209], v[56:59]
	v_mfma_f32_16x16x32_bf16 v[52:55], v[160:163], v[214:217], v[52:55]
	v_mfma_f32_16x16x32_bf16 v[44:47], v[168:171], v[214:217], v[44:47]
	v_mfma_f32_16x16x32_bf16 v[36:39], v[160:163], v[222:225], v[36:39]
	v_mfma_f32_16x16x32_bf16 v[28:31], v[168:171], v[222:225], v[28:31]
	v_mfma_f32_16x16x32_bf16 v[20:23], v[160:163], v[244:247], v[20:23]
	v_mfma_f32_16x16x32_bf16 v[12:15], v[168:171], v[244:247], v[12:15]
	v_mfma_f32_16x16x32_bf16 v[48:51], v[172:175], v[202:205], v[48:51]
	v_mfma_f32_16x16x32_bf16 v[40:43], v[180:183], v[202:205], v[40:43]
	v_mfma_f32_16x16x32_bf16 v[32:35], v[172:175], v[210:213], v[32:35]
	v_mfma_f32_16x16x32_bf16 v[24:27], v[180:183], v[210:213], v[24:27]
	v_mfma_f32_16x16x32_bf16 v[16:19], v[172:175], v[218:221], v[16:19]
	v_mfma_f32_16x16x32_bf16 v[8:11], v[180:183], v[218:221], v[8:11]
	v_mfma_f32_16x16x32_bf16 v[4:7], v[172:175], v[240:243], v[4:7]
	v_mfma_f32_16x16x32_bf16 v[0:3], v[180:183], v[240:243], v[0:3]
	v_mfma_f32_16x16x32_bf16 v[48:51], v[176:179], v[206:209], v[48:51]
	v_mfma_f32_16x16x32_bf16 v[40:43], v[184:187], v[206:209], v[40:43]
	v_mfma_f32_16x16x32_bf16 v[32:35], v[176:179], v[214:217], v[32:35]
	v_mfma_f32_16x16x32_bf16 v[24:27], v[184:187], v[214:217], v[24:27]
	v_mfma_f32_16x16x32_bf16 v[16:19], v[176:179], v[222:225], v[16:19]
	v_mfma_f32_16x16x32_bf16 v[8:11], v[184:187], v[222:225], v[8:11]
	v_mfma_f32_16x16x32_bf16 v[4:7], v[176:179], v[244:247], v[4:7]
	v_mfma_f32_16x16x32_bf16 v[0:3], v[184:187], v[244:247], v[0:3]
	s_setprio 0
	s_barrier
	s_add_u32 s18, s18, 0x100
	s_addc_u32 s19, s19, 0
	s_add_u32 s46, s46, 0x100
	s_addc_u32 s47, s47, 0
	s_cmp_ge_u32 s48, s43
	s_mov_b32 s20, s48
	s_cbranch_scc0 .LBB0_905
	s_and_b64 vcc, exec, s[10:11]
	s_cbranch_vccz .LBB0_908
	s_barrier

; #define PG8_STAGE(bufoff, gbase, voff) do { _Pragma("unroll") for (int _i = 0; _i < 2; ++_i) \
;         __builtin_amdgcn_global_load_lds((const unsigned*)((const char*)(gbase) + (voff)[_i]), (PG8_LAS unsigned*)(lds + (bufoff) + ldsw + _i * 8192), 16, 0, 0); } while (0)
; #define PG8_LDA(dst, b, h) do { _Pragma("unroll") for (int m = 0; m < 4; ++m) _Pragma("unroll") for (int k = 0; k < 2; ++k) dst[m][k] = *(const PG8_LAS bf16x8*)(lds + PG8_SA(b, h) + aoff + m * 2048 + k * 1024); } while (0)
; #define PG8_LDB(dst, b, h) do { _Pragma("unroll") for (int n = 0; n < 2; ++n) _Pragma("unroll") for (int k = 0; k < 2; ++k) dst[n][k] = *(const PG8_LAS bf16x8*)(lds + PG8_SB(b, h) + boff + n * 2048 + k * 1024); } while (0)
; #define PG8_MMA(ai, bj, At, Bt) do { __builtin_amdgcn_s_setprio(1); _Pragma("unroll") for (int m = 0; m < 4; ++m) _Pragma("unroll") for (int n = 0; n < 2; ++n) _Pragma("unroll") for (int k = 0; k < 2; ++k) \
;         acc[ai][bj][m][n] = __builtin_amdgcn_mfma_f32_16x16x32_bf16(Bt[n][k], At[m][k], acc[ai][bj][m][n], 0, 0, 0); __builtin_amdgcn_s_setprio(0); } while (0)
; #define PG8_WAIT_V(n) asm volatile("s_waitcnt vmcnt(" #n ")" ::: "memory")
; #define PG8_WAIT_L(n) asm volatile("s_waitcnt lgkmcnt(" #n ")" ::: "memory")
; #define PG8_BAR __builtin_amdgcn_s_barrier()
; #define PG8_SCHED __builtin_amdgcn_sched_barrier(0)
; template <class Epi, class Sched, bool ALIGN_EPI = false, bool SP2 = false>
; __device__ __forceinline__ void gemm_phase(PG8_LAS unsigned char* lds, const Gemm g, const Sched& S, const Epi& E) {
;     ...
;             PG8_LDB(B0, 0, 0); PG8_LDB(B1, 0, 1); PG8_SCHED; PG8_LDA(At, 0, 0); PG8_STAGE(PG8_SA(1, 1), a1 + hstepA, voffA);
;             PG8_WAIT_V(8); PG8_WAIT_L(0); PG8_BAR; PG8_MMA(0, 0, At, B0); PG8_MMA(0, 1, At, B1); PG8_BAR; PG8_SCHED;
;             PG8_LDA(At, 0, 1); PG8_STAGE(PG8_SB(0, 0), b2, voffB); PG8_STAGE(PG8_SB(0, 1), b2 + hstepB, voffB); PG8_STAGE(PG8_SA(0, 0), a2, voffA);
;             PG8_WAIT_V(8); PG8_WAIT_L(0); PG8_BAR; PG8_MMA(1, 0, At, B0); PG8_MMA(1, 1, At, B1); PG8_BAR; PG8_SCHED;
.LBB0_1187:
	s_add_i32 s49, s22, 2
	s_add_u32 s23, s4, 0xfffc0080
	s_addc_u32 s24, s5, -1
	s_add_i32 s50, 0, 0x10000
	s_cmp_eq_u32 s40, s22
	s_cselect_b32 s25, s13, s24
	s_cselect_b32 s24, s15, s23
	s_cselect_b32 s23, s45, s48
	s_cselect_b32 s22, s46, s47
	s_add_i32 s52, 0, 0x14000
	v_add_u32_e32 v142, s50, v218
	v_add_u32_e32 v158, s52, v218
	ds_read_b128 v[130:133], v142
	ds_read_b128 v[134:137], v142 offset:1024
	ds_read_b128 v[138:141], v142 offset:2048
	ds_read_b128 v[142:145], v142 offset:3072
	ds_read_b128 v[146:149], v158
	ds_read_b128 v[150:153], v158 offset:1024
	ds_read_b128 v[154:157], v158 offset:2048
	ds_read_b128 v[158:161], v158 offset:3072
	v_lshl_add_u64 v[220:221], s[4:5], 0, v[208:209]
	s_add_i32 m0, s29, 0xc000
	ds_read_b128 v[162:165], v219
	ds_read_b128 v[166:169], v219 offset:1024
	ds_read_b128 v[170:173], v219 offset:2048
	ds_read_b128 v[174:177], v219 offset:3072
	ds_read_b128 v[178:181], v219 offset:4096
	ds_read_b128 v[182:185], v219 offset:5120
	ds_read_b128 v[186:189], v219 offset:6144
	ds_read_b128 v[212:215], v219 offset:7168
	global_load_lds_dwordx4 v[220:221], off
	v_lshl_add_u64 v[220:221], s[4:5], 0, v[210:211]
	s_add_i32 m0, s29, 0xe000
	s_nop 0
	global_load_lds_dwordx4 v[220:221], off
	s_waitcnt vmcnt(8)
	s_waitcnt lgkmcnt(0)
	s_barrier
	s_setprio 1
	v_mfma_f32_16x16x32_bf16 v[122:125], v[130:133], v[162:165], v[122:125]
	v_mfma_f32_16x16x32_bf16 v[126:129], v[138:141], v[162:165], v[126:129]
	v_mfma_f32_16x16x32_bf16 v[110:113], v[130:133], v[170:173], v[110:113]
	v_mfma_f32_16x16x32_bf16 v[106:109], v[138:141], v[170:173], v[106:109]
	v_mfma_f32_16x16x32_bf16 v[94:97], v[130:133], v[178:181], v[94:97]
	v_mfma_f32_16x16x32_bf16 v[90:93], v[138:141], v[178:181], v[90:93]
	v_mfma_f32_16x16x32_bf16 v[78:81], v[130:133], v[186:189], v[78:81]
	v_mfma_f32_16x16x32_bf16 v[74:77], v[138:141], v[186:189], v[74:77]
	v_mfma_f32_16x16x32_bf16 v[122:125], v[134:137], v[166:169], v[122:125]
	v_mfma_f32_16x16x32_bf16 v[126:129], v[142:145], v[166:169], v[126:129]
	v_mfma_f32_16x16x32_bf16 v[110:113], v[134:137], v[174:177], v[110:113]
	v_mfma_f32_16x16x32_bf16 v[106:109], v[142:145], v[174:177], v[106:109]
	v_mfma_f32_16x16x32_bf16 v[94:97], v[134:137], v[182:185], v[94:97]
	v_mfma_f32_16x16x32_bf16 v[90:93], v[142:145], v[182:185], v[90:93]
	v_mfma_f32_16x16x32_bf16 v[78:81], v[134:137], v[212:215], v[78:81]
	v_mfma_f32_16x16x32_bf16 v[74:77], v[142:145], v[212:215], v[74:77]
	v_mfma_f32_16x16x32_bf16 v[118:121], v[146:149], v[162:165], v[118:121]
	v_mfma_f32_16x16x32_bf16 v[114:117], v[154:157], v[162:165], v[114:117]
	v_mfma_f32_16x16x32_bf16 v[102:105], v[146:149], v[170:173], v[102:105]
	v_mfma_f32_16x16x32_bf16 v[98:101], v[154:157], v[170:173], v[98:101]
	v_mfma_f32_16x16x32_bf16 v[86:89], v[146:149], v[178:181], v[86:89]
	v_mfma_f32_16x16x32_bf16 v[82:85], v[154:157], v[178:181], v[82:85]
	v_mfma_f32_16x16x32_bf16 v[70:73], v[146:149], v[186:189], v[70:73]
	v_mfma_f32_16x16x32_bf16 v[66:69], v[154:157], v[186:189], v[66:69]
	v_mfma_f32_16x16x32_bf16 v[118:121], v[150:153], v[166:169], v[118:121]
	v_mfma_f32_16x16x32_bf16 v[114:117], v[158:161], v[166:169], v[114:117]
	v_mfma_f32_16x16x32_bf16 v[102:105], v[150:153], v[174:177], v[102:105]
	v_mfma_f32_16x16x32_bf16 v[98:101], v[158:161], v[174:177], v[98:101]
	v_mfma_f32_16x16x32_bf16 v[86:89], v[150:153], v[182:185], v[86:89]
	v_mfma_f32_16x16x32_bf16 v[82:85], v[158:161], v[182:185], v[82:85]
	v_mfma_f32_16x16x32_bf16 v[70:73], v[150:153], v[212:215], v[70:73]
	v_mfma_f32_16x16x32_bf16 v[66:69], v[158:161], v[212:215], v[66:69]
	s_setprio 0
	s_barrier
	s_add_i32 s50, s50, s26
	v_lshl_add_u64 v[220:221], s[22:23], 0, v[64:65]
	s_mov_b32 m0, s50
	ds_read_b128 v[162:165], v219 offset:16384
	ds_read_b128 v[166:169], v219 offset:17408
	ds_read_b128 v[170:173], v219 offset:18432
	ds_read_b128 v[174:177], v219 offset:19456
	ds_read_b128 v[178:181], v219 offset:20480
	ds_read_b128 v[182:185], v219 offset:21504
	ds_read_b128 v[186:189], v219 offset:22528
	ds_read_b128 v[212:215], v219 offset:23552
	global_load_lds_dwordx4 v[220:221], off
	s_add_i32 m0, s50, 0x2000
	s_add_u32 s50, s22, 0x40000
	v_lshl_add_u64 v[222:223], s[22:23], 0, v[202:203]
	s_addc_u32 s51, s23, 0
	s_add_i32 s52, s52, s26
	global_load_lds_dwordx4 v[222:223], off
	v_lshl_add_u64 v[224:225], s[50:51], 0, v[64:65]
	s_mov_b32 m0, s52
	v_lshl_add_u64 v[226:227], s[24:25], 0, v[204:205]
	global_load_lds_dwordx4 v[224:225], off
	v_lshl_add_u64 v[224:225], s[50:51], 0, v[202:203]
	s_add_i32 m0, s52, 0x2000
	s_nop 0
	global_load_lds_dwordx4 v[224:225], off
	v_lshl_add_u64 v[224:225], s[24:25], 0, v[206:207]
	s_mov_b32 m0, s29
	s_nop 0
	global_load_lds_dwordx4 v[224:225], off
	s_mov_b32 m0, s30
	s_nop 0
	global_load_lds_dwordx4 v[226:227], off
	s_waitcnt vmcnt(8)
	s_waitcnt lgkmcnt(0)
	s_barrier
; #define PG8_STAGE(bufoff, gbase, voff) do { _Pragma("unroll") for (int _i = 0; _i < 2; ++_i) \
;         __builtin_amdgcn_global_load_lds((const unsigned*)((const char*)(gbase) + (voff)[_i]), (PG8_LAS unsigned*)(lds + (bufoff) + ldsw + _i * 8192), 16, 0, 0); } while (0)
; #define PG8_LDA(dst, b, h) do { _Pragma("unroll") for (int m = 0; m < 4; ++m) _Pragma("unroll") for (int k = 0; k < 2; ++k) dst[m][k] = *(const PG8_LAS bf16x8*)(lds + PG8_SA(b, h) + aoff + m * 2048 + k * 1024); } while (0)
; #define PG8_LDB(dst, b, h) do { _Pragma("unroll") for (int n = 0; n < 2; ++n) _Pragma("unroll") for (int k = 0; k < 2; ++k) dst[n][k] = *(const PG8_LAS bf16x8*)(lds + PG8_SB(b, h) + boff + n * 2048 + k * 1024); } while (0)
; #define PG8_MMA(ai, bj, At, Bt) do { __builtin_amdgcn_s_setprio(1); _Pragma("unroll") for (int m = 0; m < 4; ++m) _Pragma("unroll") for (int n = 0; n < 2; ++n) _Pragma("unroll") for (int k = 0; k < 2; ++k) \
;         acc[ai][bj][m][n] = __builtin_amdgcn_mfma_f32_16x16x32_bf16(Bt[n][k], At[m][k], acc[ai][bj][m][n], 0, 0, 0); __builtin_amdgcn_s_setprio(0); } while (0)
; #define PG8_WAIT_V(n) asm volatile("s_waitcnt vmcnt(" #n ")" ::: "memory")
; #define PG8_WAIT_L(n) asm volatile("s_waitcnt lgkmcnt(" #n ")" ::: "memory")
; #define PG8_BAR __builtin_amdgcn_s_barrier()
; #define PG8_SCHED __builtin_amdgcn_sched_barrier(0)
; template <class Epi, class Sched, bool ALIGN_EPI = false, bool SP2 = false>
; __device__ __forceinline__ void gemm_phase(PG8_LAS unsigned char* lds, const Gemm g, const Sched& S, const Epi& E) {
;     ...
;             PG8_WAIT_V(8); PG8_WAIT_L(0); PG8_BAR; PG8_MMA(1, 0, At, B0); PG8_MMA(1, 1, At, B1); PG8_BAR; PG8_SCHED;
;             PG8_LDB(B0, 1, 0); PG8_LDB(B1, 1, 1); PG8_SCHED; PG8_LDA(At, 1, 0); PG8_STAGE(PG8_SA(0, 1), a2 + hstepA, voffA);
;             PG8_WAIT_V(8); PG8_WAIT_L(0); PG8_BAR; PG8_MMA(0, 0, At, B0); PG8_MMA(0, 1, At, B1); PG8_BAR; PG8_SCHED;
	s_setprio 1
	v_mfma_f32_16x16x32_bf16 v[60:63], v[130:133], v[162:165], v[60:63]
	v_mfma_f32_16x16x32_bf16 v[56:59], v[138:141], v[162:165], v[56:59]
	v_mfma_f32_16x16x32_bf16 v[44:47], v[130:133], v[170:173], v[44:47]
	v_mfma_f32_16x16x32_bf16 v[40:43], v[138:141], v[170:173], v[40:43]
	v_mfma_f32_16x16x32_bf16 v[28:31], v[130:133], v[178:181], v[28:31]
	v_mfma_f32_16x16x32_bf16 v[24:27], v[138:141], v[178:181], v[24:27]
	v_mfma_f32_16x16x32_bf16 v[12:15], v[130:133], v[186:189], v[12:15]
	v_mfma_f32_16x16x32_bf16 v[8:11], v[138:141], v[186:189], v[8:11]
	v_mfma_f32_16x16x32_bf16 v[60:63], v[134:137], v[166:169], v[60:63]
	v_mfma_f32_16x16x32_bf16 v[56:59], v[142:145], v[166:169], v[56:59]
	v_mfma_f32_16x16x32_bf16 v[44:47], v[134:137], v[174:177], v[44:47]
	v_mfma_f32_16x16x32_bf16 v[40:43], v[142:145], v[174:177], v[40:43]
	v_mfma_f32_16x16x32_bf16 v[28:31], v[134:137], v[182:185], v[28:31]
	v_mfma_f32_16x16x32_bf16 v[24:27], v[142:145], v[182:185], v[24:27]
	v_mfma_f32_16x16x32_bf16 v[12:15], v[134:137], v[212:215], v[12:15]
	v_mfma_f32_16x16x32_bf16 v[8:11], v[142:145], v[212:215], v[8:11]
	v_mfma_f32_16x16x32_bf16 v[52:55], v[146:149], v[162:165], v[52:55]
	v_mfma_f32_16x16x32_bf16 v[48:51], v[154:157], v[162:165], v[48:51]
	v_mfma_f32_16x16x32_bf16 v[36:39], v[146:149], v[170:173], v[36:39]
	v_mfma_f32_16x16x32_bf16 v[32:35], v[154:157], v[170:173], v[32:35]
	v_mfma_f32_16x16x32_bf16 v[20:23], v[146:149], v[178:181], v[20:23]
	v_mfma_f32_16x16x32_bf16 v[16:19], v[154:157], v[178:181], v[16:19]
	v_mfma_f32_16x16x32_bf16 v[4:7], v[146:149], v[186:189], v[4:7]
	v_mfma_f32_16x16x32_bf16 v[0:3], v[154:157], v[186:189], v[0:3]
	v_mfma_f32_16x16x32_bf16 v[52:55], v[150:153], v[166:169], v[52:55]
	v_mfma_f32_16x16x32_bf16 v[48:51], v[158:161], v[166:169], v[48:51]
	v_mfma_f32_16x16x32_bf16 v[36:39], v[150:153], v[174:177], v[36:39]
	v_mfma_f32_16x16x32_bf16 v[32:35], v[158:161], v[174:177], v[32:35]
	v_mfma_f32_16x16x32_bf16 v[20:23], v[150:153], v[182:185], v[20:23]
	v_mfma_f32_16x16x32_bf16 v[16:19], v[158:161], v[182:185], v[16:19]
	v_mfma_f32_16x16x32_bf16 v[4:7], v[150:153], v[212:215], v[4:7]
	v_mfma_f32_16x16x32_bf16 v[0:3], v[158:161], v[212:215], v[0:3]
	s_setprio 0
	s_barrier
	s_add_i32 s50, 0, 0x18000
	s_add_i32 s51, 0, 0x1c000
	v_add_u32_e32 v142, s50, v218
	v_add_u32_e32 v158, s51, v218
	ds_read_b128 v[130:133], v142
	ds_read_b128 v[134:137], v142 offset:1024
	ds_read_b128 v[138:141], v142 offset:2048
	ds_read_b128 v[142:145], v142 offset:3072
	ds_read_b128 v[146:149], v158
	ds_read_b128 v[150:153], v158 offset:1024
	ds_read_b128 v[154:157], v158 offset:2048
	ds_read_b128 v[158:161], v158 offset:3072
	s_add_u32 s24, s24, 0x40000
	s_addc_u32 s25, s25, 0
	s_mov_b32 m0, s31
	v_lshl_add_u64 v[240:241], s[24:25], 0, v[206:207]
	ds_read_b128 v[162:165], v219 offset:32768
	ds_read_b128 v[166:169], v219 offset:33792
	ds_read_b128 v[170:173], v219 offset:34816
	ds_read_b128 v[174:177], v219 offset:35840
	ds_read_b128 v[178:181], v219 offset:36864
	ds_read_b128 v[182:185], v219 offset:37888
	ds_read_b128 v[186:189], v219 offset:38912
	ds_read_b128 v[212:215], v219 offset:39936
	global_load_lds_dwordx4 v[240:241], off
	v_lshl_add_u64 v[240:241], s[24:25], 0, v[204:205]
	s_mov_b32 m0, s34
	s_nop 0
	global_load_lds_dwordx4 v[240:241], off
	s_waitcnt vmcnt(8)
	s_waitcnt lgkmcnt(0)
	s_barrier
	s_setprio 1
	v_mfma_f32_16x16x32_bf16 v[122:125], v[130:133], v[162:165], v[122:125]
	v_mfma_f32_16x16x32_bf16 v[126:129], v[138:141], v[162:165], v[126:129]
	v_mfma_f32_16x16x32_bf16 v[110:113], v[130:133], v[170:173], v[110:113]
	v_mfma_f32_16x16x32_bf16 v[106:109], v[138:141], v[170:173], v[106:109]
	v_mfma_f32_16x16x32_bf16 v[94:97], v[130:133], v[178:181], v[94:97]
	v_mfma_f32_16x16x32_bf16 v[90:93], v[138:141], v[178:181], v[90:93]
	v_mfma_f32_16x16x32_bf16 v[78:81], v[130:133], v[186:189], v[78:81]
	v_mfma_f32_16x16x32_bf16 v[74:77], v[138:141], v[186:189], v[74:77]
	v_mfma_f32_16x16x32_bf16 v[122:125], v[134:137], v[166:169], v[122:125]
	v_mfma_f32_16x16x32_bf16 v[126:129], v[142:145], v[166:169], v[126:129]
	v_mfma_f32_16x16x32_bf16 v[110:113], v[134:137], v[174:177], v[110:113]
	v_mfma_f32_16x16x32_bf16 v[106:109], v[142:145], v[174:177], v[106:109]
	v_mfma_f32_16x16x32_bf16 v[94:97], v[134:137], v[182:185], v[94:97]
	v_mfma_f32_16x16x32_bf16 v[90:93], v[142:145], v[182:185], v[90:93]
	v_mfma_f32_16x16x32_bf16 v[78:81], v[134:137], v[212:215], v[78:81]
	v_mfma_f32_16x16x32_bf16 v[74:77], v[142:145], v[212:215], v[74:77]
	v_mfma_f32_16x16x32_bf16 v[118:121], v[146:149], v[162:165], v[118:121]
	v_mfma_f32_16x16x32_bf16 v[114:117], v[154:157], v[162:165], v[114:117]
	v_mfma_f32_16x16x32_bf16 v[102:105], v[146:149], v[170:173], v[102:105]
	v_mfma_f32_16x16x32_bf16 v[98:101], v[154:157], v[170:173], v[98:101]
	v_mfma_f32_16x16x32_bf16 v[86:89], v[146:149], v[178:181], v[86:89]
	v_mfma_f32_16x16x32_bf16 v[82:85], v[154:157], v[178:181], v[82:85]
	v_mfma_f32_16x16x32_bf16 v[70:73], v[146:149], v[186:189], v[70:73]
	v_mfma_f32_16x16x32_bf16 v[66:69], v[154:157], v[186:189], v[66:69]
	v_mfma_f32_16x16x32_bf16 v[118:121], v[150:153], v[166:169], v[118:121]
	v_mfma_f32_16x16x32_bf16 v[114:117], v[158:161], v[166:169], v[114:117]
	v_mfma_f32_16x16x32_bf16 v[102:105], v[150:153], v[174:177], v[102:105]
	v_mfma_f32_16x16x32_bf16 v[98:101], v[158:161], v[174:177], v[98:101]
	v_mfma_f32_16x16x32_bf16 v[86:89], v[150:153], v[182:185], v[86:89]
	v_mfma_f32_16x16x32_bf16 v[82:85], v[158:161], v[182:185], v[82:85]
	v_mfma_f32_16x16x32_bf16 v[70:73], v[150:153], v[212:215], v[70:73]
	v_mfma_f32_16x16x32_bf16 v[66:69], v[158:161], v[212:215], v[66:69]
	s_setprio 0
	s_barrier
; #define PG8_STAGE(bufoff, gbase, voff) do { _Pragma("unroll") for (int _i = 0; _i < 2; ++_i) \
;         __builtin_amdgcn_global_load_lds((const unsigned*)((const char*)(gbase) + (voff)[_i]), (PG8_LAS unsigned*)(lds + (bufoff) + ldsw + _i * 8192), 16, 0, 0); } while (0)
; #define PG8_LDA(dst, b, h) do { _Pragma("unroll") for (int m = 0; m < 4; ++m) _Pragma("unroll") for (int k = 0; k < 2; ++k) dst[m][k] = *(const PG8_LAS bf16x8*)(lds + PG8_SA(b, h) + aoff + m * 2048 + k * 1024); } while (0)
; #define PG8_MMA(ai, bj, At, Bt) do { __builtin_amdgcn_s_setprio(1); _Pragma("unroll") for (int m = 0; m < 4; ++m) _Pragma("unroll") for (int n = 0; n < 2; ++n) _Pragma("unroll") for (int k = 0; k < 2; ++k) \
;         acc[ai][bj][m][n] = __builtin_amdgcn_mfma_f32_16x16x32_bf16(Bt[n][k], At[m][k], acc[ai][bj][m][n], 0, 0, 0); __builtin_amdgcn_s_setprio(0); } while (0)
; #define PG8_WAIT_V(n) asm volatile("s_waitcnt vmcnt(" #n ")" ::: "memory")
; #define PG8_WAIT_L(n) asm volatile("s_waitcnt lgkmcnt(" #n ")" ::: "memory")
; #define PG8_BAR __builtin_amdgcn_s_barrier()
; #define PG8_SCHED __builtin_amdgcn_sched_barrier(0)
; template <class Epi, class Sched, bool ALIGN_EPI = false, bool SP2 = false>
; __device__ __forceinline__ void gemm_phase(PG8_LAS unsigned char* lds, const Gemm g, const Sched& S, const Epi& E) {
;     ...
;             PG8_LDA(At, 1, 1); PG8_STAGE(PG8_SB(1, 0), b3, voffB); PG8_STAGE(PG8_SB(1, 1), b3 + hstepB, voffB); PG8_STAGE(PG8_SA(1, 0), a3, voffA);
;             PG8_WAIT_V(8); PG8_WAIT_L(0); PG8_BAR; PG8_MMA(1, 0, At, B0); PG8_MMA(1, 1, At, B1); PG8_BAR; PG8_SCHED;
	s_add_i32 s24, s50, s26
	v_lshl_add_u64 v[220:221], v[220:221], 0, s[88:89]
	s_mov_b32 m0, s24
	ds_read_b128 v[162:165], v219 offset:49152
	ds_read_b128 v[166:169], v219 offset:50176
	ds_read_b128 v[170:173], v219 offset:51200
	ds_read_b128 v[174:177], v219 offset:52224
	ds_read_b128 v[178:181], v219 offset:53248
	ds_read_b128 v[182:185], v219 offset:54272
	ds_read_b128 v[186:189], v219 offset:55296
	ds_read_b128 v[212:215], v219 offset:56320
	global_load_lds_dwordx4 v[220:221], off
	s_add_i32 m0, s24, 0x2000
	s_add_u32 s22, s22, 0x40080
	v_lshl_add_u64 v[220:221], v[222:223], 0, s[88:89]
	s_addc_u32 s23, s23, 0
	s_add_i32 s24, s51, s26
	global_load_lds_dwordx4 v[220:221], off
	v_lshl_add_u64 v[220:221], s[22:23], 0, v[64:65]
	s_mov_b32 m0, s24
	s_nop 0
	global_load_lds_dwordx4 v[220:221], off
	v_lshl_add_u64 v[220:221], s[22:23], 0, v[202:203]
	s_add_i32 m0, s24, 0x2000
	s_nop 0
	global_load_lds_dwordx4 v[220:221], off
	v_lshl_add_u64 v[220:221], v[224:225], 0, s[88:89]
	s_mov_b32 m0, s38
	s_nop 0
	global_load_lds_dwordx4 v[220:221], off
	v_lshl_add_u64 v[220:221], v[226:227], 0, s[88:89]
	s_mov_b32 m0, s39
	s_nop 0
	global_load_lds_dwordx4 v[220:221], off
	s_waitcnt vmcnt(8)
	s_waitcnt lgkmcnt(0)
	s_barrier
	s_setprio 1
	v_mfma_f32_16x16x32_bf16 v[60:63], v[130:133], v[162:165], v[60:63]
	v_mfma_f32_16x16x32_bf16 v[56:59], v[138:141], v[162:165], v[56:59]
	v_mfma_f32_16x16x32_bf16 v[44:47], v[130:133], v[170:173], v[44:47]
	v_mfma_f32_16x16x32_bf16 v[40:43], v[138:141], v[170:173], v[40:43]
	v_mfma_f32_16x16x32_bf16 v[28:31], v[130:133], v[178:181], v[28:31]
	v_mfma_f32_16x16x32_bf16 v[24:27], v[138:141], v[178:181], v[24:27]
	v_mfma_f32_16x16x32_bf16 v[12:15], v[130:133], v[186:189], v[12:15]
	v_mfma_f32_16x16x32_bf16 v[8:11], v[138:141], v[186:189], v[8:11]
	v_mfma_f32_16x16x32_bf16 v[60:63], v[134:137], v[166:169], v[60:63]
	v_mfma_f32_16x16x32_bf16 v[56:59], v[142:145], v[166:169], v[56:59]
	v_mfma_f32_16x16x32_bf16 v[44:47], v[134:137], v[174:177], v[44:47]
	v_mfma_f32_16x16x32_bf16 v[40:43], v[142:145], v[174:177], v[40:43]
	v_mfma_f32_16x16x32_bf16 v[28:31], v[134:137], v[182:185], v[28:31]
	v_mfma_f32_16x16x32_bf16 v[24:27], v[142:145], v[182:185], v[24:27]
	v_mfma_f32_16x16x32_bf16 v[12:15], v[134:137], v[212:215], v[12:15]
	v_mfma_f32_16x16x32_bf16 v[8:11], v[142:145], v[212:215], v[8:11]
	v_mfma_f32_16x16x32_bf16 v[52:55], v[146:149], v[162:165], v[52:55]
	v_mfma_f32_16x16x32_bf16 v[48:51], v[154:157], v[162:165], v[48:51]
	v_mfma_f32_16x16x32_bf16 v[36:39], v[146:149], v[170:173], v[36:39]
	v_mfma_f32_16x16x32_bf16 v[32:35], v[154:157], v[170:173], v[32:35]
	v_mfma_f32_16x16x32_bf16 v[20:23], v[146:149], v[178:181], v[20:23]
	v_mfma_f32_16x16x32_bf16 v[16:19], v[154:157], v[178:181], v[16:19]
	v_mfma_f32_16x16x32_bf16 v[4:7], v[146:149], v[186:189], v[4:7]
	v_mfma_f32_16x16x32_bf16 v[0:3], v[154:157], v[186:189], v[0:3]
	v_mfma_f32_16x16x32_bf16 v[52:55], v[150:153], v[166:169], v[52:55]
	v_mfma_f32_16x16x32_bf16 v[48:51], v[158:161], v[166:169], v[48:51]
	v_mfma_f32_16x16x32_bf16 v[36:39], v[150:153], v[174:177], v[36:39]
	v_mfma_f32_16x16x32_bf16 v[32:35], v[158:161], v[174:177], v[32:35]
	v_mfma_f32_16x16x32_bf16 v[20:23], v[150:153], v[182:185], v[20:23]
	v_mfma_f32_16x16x32_bf16 v[16:19], v[158:161], v[182:185], v[16:19]
	v_mfma_f32_16x16x32_bf16 v[4:7], v[150:153], v[212:215], v[4:7]
	v_mfma_f32_16x16x32_bf16 v[0:3], v[158:161], v[212:215], v[0:3]
	s_setprio 0
	s_barrier
	s_add_u32 s4, s4, 0x100
	s_addc_u32 s5, s5, 0
	s_add_u32 s47, s47, 0x100
	s_addc_u32 s48, s48, 0
	s_cmp_ge_i32 s49, s36
	s_mov_b32 s22, s49
	s_cbranch_scc0 .LBB0_1187
